# v1 + P8/P11/P13 residual epilogues: all 16 base loads hoisted to epilogue top, counted vmcnt(14+j) per row group
# baseline (speedup 1.0000x reference)
; #define PG8_STAGE(bufoff, gbase, voff) do { _Pragma("unroll") for (int _i = 0; _i < 2; ++_i) \
;         __builtin_amdgcn_global_load_lds((const unsigned*)((const char*)(gbase) + (voff)[_i]), (PG8_LAS unsigned*)(lds + (bufoff) + ldsw + _i * 8192), 16, 0, PG8_LOAD_AUX); } while (0)
; #define PG8_LDA(dst, b, h) do { _Pragma("unroll") for (int m = 0; m < 4; ++m) _Pragma("unroll") for (int k = 0; k < 2; ++k) dst[m][k] = *(const PG8_LAS bf16x8*)(lds + PG8_SA(b, h) + aoff + m * 2048 + k * 1024); } while (0)
; #define PG8_LDB(dst, b, h) do { _Pragma("unroll") for (int n = 0; n < 2; ++n) _Pragma("unroll") for (int k = 0; k < 2; ++k) dst[n][k] = *(const PG8_LAS bf16x8*)(lds + PG8_SB(b, h) + boff + n * 2048 + k * 1024); } while (0)
; #define PG8_MMA(ai, bj, At, Bt) do { __builtin_amdgcn_s_setprio(1); _Pragma("unroll") for (int m = 0; m < 4; ++m) _Pragma("unroll") for (int n = 0; n < 2; ++n) _Pragma("unroll") for (int k = 0; k < 2; ++k) \
;         acc[ai][bj][m][n] = __builtin_amdgcn_mfma_f32_16x16x32_bf16(Bt[n][k], At[m][k], acc[ai][bj][m][n], 0, 0, 0); __builtin_amdgcn_s_setprio(0); } while (0)
; #define PG8_WAIT_V(n) asm volatile("s_waitcnt vmcnt(" #n ")" ::: "memory")
; #define PG8_BAR __builtin_amdgcn_s_barrier()
; template <class Epi, class Sched, bool ALIGN_EPI = false, bool SP2 = false>
; __device__ __forceinline__ void gemm_phase(PG8_LAS unsigned char* lds, const Gemm g, const Sched& S, const Epi& E) {
;     ...
;         for (int t = 0; t < nt; t += 2) {
;             const bool last = (t == nt - 2);
;             const char* a1 = cA + (size_t)(t + 1) * kstep;
;             const char* a2 = last ? nA : cA + (size_t)(t + 2) * kstep; const char* b2 = last ? nB : cB + (size_t)(t + 2) * kstep;
;             const char* a3 = a2 + kstep; const char* b3 = b2 + kstep;
;             if (last && has_next) S.a_ready(nxt);
;             if constexpr (SP2) {
;             PG8_LDB(B0, 0, 0); PG8_LDB(B1, 0, 1); PG8_SCHED; PG8_LDA(At, 0, 0); PG8_STAGE(PG8_SA(1, 1), a1 + hstepA, voffA);
;             PG8_WAIT_V(8); PG8_WAIT_L(0); PG8_BAR; PG8_MMA(0, 0, At, B0); PG8_MMA(0, 1, At, B1); PG8_BAR; PG8_SCHED;
;             PG8_LDA(At, 0, 1); PG8_STAGE(PG8_SB(0, 0), b2, voffB); PG8_STAGE(PG8_SB(0, 1), b2 + hstepB, voffB); PG8_STAGE(PG8_SA(0, 0), a2, voffA);
;             PG8_WAIT_V(8); PG8_WAIT_L(0); PG8_BAR; PG8_MMA(1, 0, At, B0); PG8_MMA(1, 1, At, B1); PG8_BAR; PG8_SCHED;
.LBB0_757:
	ds_read_b128 v[146:149], v157
	ds_read_b128 v[162:165], v157 offset:1024
	ds_read_b128 v[166:169], v157 offset:2048
	ds_read_b128 v[170:173], v157 offset:3072
	ds_read_b128 v[174:177], v158
	ds_read_b128 v[178:181], v158 offset:1024
	ds_read_b128 v[182:185], v158 offset:2048
	ds_read_b128 v[186:189], v158 offset:3072
	s_add_u32 s20, s0, 0xfff50080
	s_addc_u32 s21, s1, -1
	s_cmp_eq_u32 s27, 40
	s_cselect_b32 s23, s9, s21
	s_cselect_b32 s22, s8, s20
	s_cselect_b32 s21, s41, s26
	s_cselect_b32 s20, s40, s25
	v_lshl_add_u64 v[222:223], s[0:1], 0, v[138:139]
	s_add_i32 m0, s35, 0xc000
	ds_read_b128 v[190:193], v159
	ds_read_b128 v[194:197], v159 offset:1024
	ds_read_b128 v[198:201], v159 offset:2048
	ds_read_b128 v[202:205], v159 offset:3072
	ds_read_b128 v[206:209], v159 offset:4096
	ds_read_b128 v[210:213], v159 offset:5120
	ds_read_b128 v[214:217], v159 offset:6144
	ds_read_b128 v[218:221], v159 offset:7168
	global_load_lds_dwordx4 v[222:223], off
	v_lshl_add_u64 v[222:223], s[0:1], 0, v[140:141]
	s_add_i32 m0, s35, 0xe000
	s_nop 0
	global_load_lds_dwordx4 v[222:223], off
	s_waitcnt vmcnt(8)
	s_waitcnt lgkmcnt(0)
	s_barrier
	s_setprio 1
	s_waitcnt lgkmcnt(0)
	v_mfma_f32_16x16x32_bf16 v[124:127], v[146:149], v[190:193], v[124:127]
	v_mfma_f32_16x16x32_bf16 v[120:123], v[166:169], v[190:193], v[120:123]
	v_mfma_f32_16x16x32_bf16 v[108:111], v[146:149], v[198:201], v[108:111]
	v_mfma_f32_16x16x32_bf16 v[104:107], v[166:169], v[198:201], v[104:107]
	v_mfma_f32_16x16x32_bf16 v[92:95], v[146:149], v[206:209], v[92:95]
	v_mfma_f32_16x16x32_bf16 v[88:91], v[166:169], v[206:209], v[88:91]
	v_mfma_f32_16x16x32_bf16 v[76:79], v[146:149], v[214:217], v[76:79]
	v_mfma_f32_16x16x32_bf16 v[72:75], v[166:169], v[214:217], v[72:75]
	v_mfma_f32_16x16x32_bf16 v[124:127], v[162:165], v[194:197], v[124:127]
	v_mfma_f32_16x16x32_bf16 v[120:123], v[170:173], v[194:197], v[120:123]
	v_mfma_f32_16x16x32_bf16 v[108:111], v[162:165], v[202:205], v[108:111]
	v_mfma_f32_16x16x32_bf16 v[104:107], v[170:173], v[202:205], v[104:107]
	v_mfma_f32_16x16x32_bf16 v[92:95], v[162:165], v[210:213], v[92:95]
	v_mfma_f32_16x16x32_bf16 v[88:91], v[170:173], v[210:213], v[88:91]
	v_mfma_f32_16x16x32_bf16 v[76:79], v[162:165], v[218:221], v[76:79]
	v_mfma_f32_16x16x32_bf16 v[72:75], v[170:173], v[218:221], v[72:75]
	s_setprio 0
	s_setprio 1
	v_mfma_f32_16x16x32_bf16 v[116:119], v[174:177], v[190:193], v[116:119]
	v_mfma_f32_16x16x32_bf16 v[112:115], v[182:185], v[190:193], v[112:115]
	v_mfma_f32_16x16x32_bf16 v[100:103], v[174:177], v[198:201], v[100:103]
	v_mfma_f32_16x16x32_bf16 v[96:99], v[182:185], v[198:201], v[96:99]
	v_mfma_f32_16x16x32_bf16 v[84:87], v[174:177], v[206:209], v[84:87]
	v_mfma_f32_16x16x32_bf16 v[80:83], v[182:185], v[206:209], v[80:83]
	v_mfma_f32_16x16x32_bf16 v[68:71], v[174:177], v[214:217], v[68:71]
	v_mfma_f32_16x16x32_bf16 v[64:67], v[182:185], v[214:217], v[64:67]
	v_mfma_f32_16x16x32_bf16 v[116:119], v[178:181], v[194:197], v[116:119]
	v_mfma_f32_16x16x32_bf16 v[112:115], v[186:189], v[194:197], v[112:115]
	v_mfma_f32_16x16x32_bf16 v[100:103], v[178:181], v[202:205], v[100:103]
	v_mfma_f32_16x16x32_bf16 v[96:99], v[186:189], v[202:205], v[96:99]
	v_mfma_f32_16x16x32_bf16 v[84:87], v[178:181], v[210:213], v[84:87]
	v_mfma_f32_16x16x32_bf16 v[80:83], v[186:189], v[210:213], v[80:83]
	v_mfma_f32_16x16x32_bf16 v[68:71], v[178:181], v[218:221], v[68:71]
	v_mfma_f32_16x16x32_bf16 v[64:67], v[186:189], v[218:221], v[64:67]
	s_setprio 0
	s_barrier
	s_add_i32 s28, s55, s34
	v_lshl_add_u64 v[222:223], s[20:21], 0, v[130:131]
	s_mov_b32 m0, s28
	ds_read_b128 v[190:193], v159 offset:16384
	ds_read_b128 v[194:197], v159 offset:17408
	ds_read_b128 v[198:201], v159 offset:18432
	ds_read_b128 v[202:205], v159 offset:19456
	ds_read_b128 v[206:209], v159 offset:20480
	ds_read_b128 v[210:213], v159 offset:21504
	ds_read_b128 v[214:217], v159 offset:22528
	ds_read_b128 v[218:221], v159 offset:23552
	global_load_lds_dwordx4 v[222:223], off
	s_add_i32 m0, s28, 0x2000
	s_add_u32 s28, s20, 0x2c000
	v_lshl_add_u64 v[224:225], s[20:21], 0, v[134:135]
	s_addc_u32 s29, s21, 0
	s_add_i32 s30, s56, s34
	global_load_lds_dwordx4 v[224:225], off
	v_lshl_add_u64 v[226:227], s[28:29], 0, v[130:131]
	s_mov_b32 m0, s30
	v_lshl_add_u64 v[228:229], s[22:23], 0, v[132:133]
	global_load_lds_dwordx4 v[226:227], off
	v_lshl_add_u64 v[226:227], s[28:29], 0, v[134:135]
	s_add_i32 m0, s30, 0x2000
	s_nop 0
	global_load_lds_dwordx4 v[226:227], off
	v_lshl_add_u64 v[226:227], s[22:23], 0, v[128:129]
	s_mov_b32 m0, s35
	s_nop 0
	global_load_lds_dwordx4 v[226:227], off
	s_mov_b32 m0, s42
	s_nop 0
	global_load_lds_dwordx4 v[228:229], off
	s_waitcnt vmcnt(8)
	s_waitcnt lgkmcnt(0)
	s_barrier
; #define PG8_STAGE(bufoff, gbase, voff) do { _Pragma("unroll") for (int _i = 0; _i < 2; ++_i) \
;         __builtin_amdgcn_global_load_lds((const unsigned*)((const char*)(gbase) + (voff)[_i]), (PG8_LAS unsigned*)(lds + (bufoff) + ldsw + _i * 8192), 16, 0, PG8_LOAD_AUX); } while (0)
; #define PG8_LDA(dst, b, h) do { _Pragma("unroll") for (int m = 0; m < 4; ++m) _Pragma("unroll") for (int k = 0; k < 2; ++k) dst[m][k] = *(const PG8_LAS bf16x8*)(lds + PG8_SA(b, h) + aoff + m * 2048 + k * 1024); } while (0)
; #define PG8_LDB(dst, b, h) do { _Pragma("unroll") for (int n = 0; n < 2; ++n) _Pragma("unroll") for (int k = 0; k < 2; ++k) dst[n][k] = *(const PG8_LAS bf16x8*)(lds + PG8_SB(b, h) + boff + n * 2048 + k * 1024); } while (0)
; #define PG8_MMA(ai, bj, At, Bt) do { __builtin_amdgcn_s_setprio(1); _Pragma("unroll") for (int m = 0; m < 4; ++m) _Pragma("unroll") for (int n = 0; n < 2; ++n) _Pragma("unroll") for (int k = 0; k < 2; ++k) \
;         acc[ai][bj][m][n] = __builtin_amdgcn_mfma_f32_16x16x32_bf16(Bt[n][k], At[m][k], acc[ai][bj][m][n], 0, 0, 0); __builtin_amdgcn_s_setprio(0); } while (0)
; #define PG8_WAIT_V(n) asm volatile("s_waitcnt vmcnt(" #n ")" ::: "memory")
; #define PG8_WAIT_L(n) asm volatile("s_waitcnt lgkmcnt(" #n ")" ::: "memory")
; #define PG8_BAR __builtin_amdgcn_s_barrier()
; #define PG8_SCHED __builtin_amdgcn_sched_barrier(0)
; template <class Epi, class Sched, bool ALIGN_EPI = false, bool SP2 = false>
; __device__ __forceinline__ void gemm_phase(PG8_LAS unsigned char* lds, const Gemm g, const Sched& S, const Epi& E) {
;     ...
;             PG8_WAIT_V(8); PG8_WAIT_L(0); PG8_BAR; PG8_MMA(1, 0, At, B0); PG8_MMA(1, 1, At, B1); PG8_BAR; PG8_SCHED;
;             PG8_LDB(B0, 1, 0); PG8_LDB(B1, 1, 1); PG8_SCHED; PG8_LDA(At, 1, 0); PG8_STAGE(PG8_SA(0, 1), a2 + hstepA, voffA);
;             PG8_WAIT_V(8); PG8_WAIT_L(0); PG8_BAR; PG8_MMA(0, 0, At, B0); PG8_MMA(0, 1, At, B1); PG8_BAR; PG8_SCHED;
;             PG8_LDA(At, 1, 1); PG8_STAGE(PG8_SB(1, 0), b3, voffB); PG8_STAGE(PG8_SB(1, 1), b3 + hstepB, voffB); PG8_STAGE(PG8_SA(1, 0), a3, voffA);
;             PG8_WAIT_V(8); PG8_WAIT_L(0); PG8_BAR; PG8_MMA(1, 0, At, B0); PG8_MMA(1, 1, At, B1); PG8_BAR; PG8_SCHED;
	s_setprio 1
	s_waitcnt lgkmcnt(0)
	v_mfma_f32_16x16x32_bf16 v[60:63], v[146:149], v[190:193], v[60:63]
	v_mfma_f32_16x16x32_bf16 v[56:59], v[166:169], v[190:193], v[56:59]
	v_mfma_f32_16x16x32_bf16 v[44:47], v[146:149], v[198:201], v[44:47]
	v_mfma_f32_16x16x32_bf16 v[40:43], v[166:169], v[198:201], v[40:43]
	v_mfma_f32_16x16x32_bf16 v[28:31], v[146:149], v[206:209], v[28:31]
	v_mfma_f32_16x16x32_bf16 v[24:27], v[166:169], v[206:209], v[24:27]
	v_mfma_f32_16x16x32_bf16 v[12:15], v[146:149], v[214:217], v[12:15]
	v_mfma_f32_16x16x32_bf16 v[8:11], v[166:169], v[214:217], v[8:11]
	v_mfma_f32_16x16x32_bf16 v[60:63], v[162:165], v[194:197], v[60:63]
	v_mfma_f32_16x16x32_bf16 v[56:59], v[170:173], v[194:197], v[56:59]
	v_mfma_f32_16x16x32_bf16 v[44:47], v[162:165], v[202:205], v[44:47]
	v_mfma_f32_16x16x32_bf16 v[40:43], v[170:173], v[202:205], v[40:43]
	v_mfma_f32_16x16x32_bf16 v[28:31], v[162:165], v[210:213], v[28:31]
	v_mfma_f32_16x16x32_bf16 v[24:27], v[170:173], v[210:213], v[24:27]
	v_mfma_f32_16x16x32_bf16 v[12:15], v[162:165], v[218:221], v[12:15]
	v_mfma_f32_16x16x32_bf16 v[8:11], v[170:173], v[218:221], v[8:11]
	s_setprio 0
	s_setprio 1
	v_mfma_f32_16x16x32_bf16 v[52:55], v[174:177], v[190:193], v[52:55]
	v_mfma_f32_16x16x32_bf16 v[48:51], v[182:185], v[190:193], v[48:51]
	v_mfma_f32_16x16x32_bf16 v[36:39], v[174:177], v[198:201], v[36:39]
	v_mfma_f32_16x16x32_bf16 v[32:35], v[182:185], v[198:201], v[32:35]
	v_mfma_f32_16x16x32_bf16 v[20:23], v[174:177], v[206:209], v[20:23]
	v_mfma_f32_16x16x32_bf16 v[16:19], v[182:185], v[206:209], v[16:19]
	v_mfma_f32_16x16x32_bf16 v[4:7], v[174:177], v[214:217], v[4:7]
	v_mfma_f32_16x16x32_bf16 v[0:3], v[182:185], v[214:217], v[0:3]
	v_mfma_f32_16x16x32_bf16 v[52:55], v[178:181], v[194:197], v[52:55]
	v_mfma_f32_16x16x32_bf16 v[48:51], v[186:189], v[194:197], v[48:51]
	v_mfma_f32_16x16x32_bf16 v[36:39], v[178:181], v[202:205], v[36:39]
	v_mfma_f32_16x16x32_bf16 v[32:35], v[186:189], v[202:205], v[32:35]
	v_mfma_f32_16x16x32_bf16 v[20:23], v[178:181], v[210:213], v[20:23]
	v_mfma_f32_16x16x32_bf16 v[16:19], v[186:189], v[210:213], v[16:19]
	v_mfma_f32_16x16x32_bf16 v[4:7], v[178:181], v[218:221], v[4:7]
	v_mfma_f32_16x16x32_bf16 v[0:3], v[186:189], v[218:221], v[0:3]
	s_setprio 0
	s_barrier
	s_add_i32 s28, 0, 0x18000
	v_add_u32_e32 v161, s28, v151
	s_add_i32 s29, 0, 0x1c000
	ds_read_b128 v[146:149], v161
	ds_read_b128 v[162:165], v161 offset:1024
	ds_read_b128 v[166:169], v161 offset:2048
	ds_read_b128 v[170:173], v161 offset:3072
	v_add_u32_e32 v161, s29, v151
	ds_read_b128 v[174:177], v161
	ds_read_b128 v[178:181], v161 offset:1024
	ds_read_b128 v[182:185], v161 offset:2048
	ds_read_b128 v[186:189], v161 offset:3072
	s_add_u32 s22, s22, 0xb0000
	s_addc_u32 s23, s23, 0
	s_mov_b32 m0, s43
	v_lshl_add_u64 v[230:231], s[22:23], 0, v[128:129]
	ds_read_b128 v[190:193], v159 offset:32768
	ds_read_b128 v[194:197], v159 offset:33792
	ds_read_b128 v[198:201], v159 offset:34816
	ds_read_b128 v[202:205], v159 offset:35840
	ds_read_b128 v[206:209], v159 offset:36864
	ds_read_b128 v[210:213], v159 offset:37888
	ds_read_b128 v[214:217], v159 offset:38912
	ds_read_b128 v[218:221], v159 offset:39936
	global_load_lds_dwordx4 v[230:231], off
	v_lshl_add_u64 v[230:231], s[22:23], 0, v[132:133]
	s_mov_b32 m0, s46
	s_nop 0
	global_load_lds_dwordx4 v[230:231], off
	s_waitcnt vmcnt(8)
	s_waitcnt lgkmcnt(0)
	s_barrier
	s_setprio 1
	s_waitcnt lgkmcnt(0)
	v_mfma_f32_16x16x32_bf16 v[124:127], v[146:149], v[190:193], v[124:127]
	v_mfma_f32_16x16x32_bf16 v[120:123], v[166:169], v[190:193], v[120:123]
	v_mfma_f32_16x16x32_bf16 v[108:111], v[146:149], v[198:201], v[108:111]
	v_mfma_f32_16x16x32_bf16 v[104:107], v[166:169], v[198:201], v[104:107]
	v_mfma_f32_16x16x32_bf16 v[92:95], v[146:149], v[206:209], v[92:95]
	v_mfma_f32_16x16x32_bf16 v[88:91], v[166:169], v[206:209], v[88:91]
	v_mfma_f32_16x16x32_bf16 v[76:79], v[146:149], v[214:217], v[76:79]
	v_mfma_f32_16x16x32_bf16 v[72:75], v[166:169], v[214:217], v[72:75]
	v_mfma_f32_16x16x32_bf16 v[124:127], v[162:165], v[194:197], v[124:127]
	v_mfma_f32_16x16x32_bf16 v[120:123], v[170:173], v[194:197], v[120:123]
	v_mfma_f32_16x16x32_bf16 v[108:111], v[162:165], v[202:205], v[108:111]
	v_mfma_f32_16x16x32_bf16 v[104:107], v[170:173], v[202:205], v[104:107]
	v_mfma_f32_16x16x32_bf16 v[92:95], v[162:165], v[210:213], v[92:95]
	v_mfma_f32_16x16x32_bf16 v[88:91], v[170:173], v[210:213], v[88:91]
	v_mfma_f32_16x16x32_bf16 v[76:79], v[162:165], v[218:221], v[76:79]
	v_mfma_f32_16x16x32_bf16 v[72:75], v[170:173], v[218:221], v[72:75]
	s_setprio 0
	s_setprio 1
	v_mfma_f32_16x16x32_bf16 v[116:119], v[174:177], v[190:193], v[116:119]
	v_mfma_f32_16x16x32_bf16 v[112:115], v[182:185], v[190:193], v[112:115]
	v_mfma_f32_16x16x32_bf16 v[100:103], v[174:177], v[198:201], v[100:103]
	v_mfma_f32_16x16x32_bf16 v[96:99], v[182:185], v[198:201], v[96:99]
	v_mfma_f32_16x16x32_bf16 v[84:87], v[174:177], v[206:209], v[84:87]
	v_mfma_f32_16x16x32_bf16 v[80:83], v[182:185], v[206:209], v[80:83]
	v_mfma_f32_16x16x32_bf16 v[68:71], v[174:177], v[214:217], v[68:71]
	v_mfma_f32_16x16x32_bf16 v[64:67], v[182:185], v[214:217], v[64:67]
	v_mfma_f32_16x16x32_bf16 v[116:119], v[178:181], v[194:197], v[116:119]
	v_mfma_f32_16x16x32_bf16 v[112:115], v[186:189], v[194:197], v[112:115]
	v_mfma_f32_16x16x32_bf16 v[100:103], v[178:181], v[202:205], v[100:103]
	v_mfma_f32_16x16x32_bf16 v[96:99], v[186:189], v[202:205], v[96:99]
	v_mfma_f32_16x16x32_bf16 v[84:87], v[178:181], v[210:213], v[84:87]
	v_mfma_f32_16x16x32_bf16 v[80:83], v[186:189], v[210:213], v[80:83]
	v_mfma_f32_16x16x32_bf16 v[68:71], v[178:181], v[218:221], v[68:71]
	v_mfma_f32_16x16x32_bf16 v[64:67], v[186:189], v[218:221], v[64:67]
	s_setprio 0
	s_barrier
;     __device__ __forceinline__ void operator()(const f32x4 (&acc)[2][2][4][2], const Unit& u, int wr, int wc, int fr, int fq) const {
;     ...
;             for (int m = 0; m < 4; ++m) { const int rowg = u.pm * BM + ai * HALF + wr * 64 + m * 16, row = rowg + fr; const size_t off = (size_t)row * 1024 + col0;
;                 u32x4 w[2]; float ss = 0.f;
; #pragma unroll
;                 for (int bj = 0; bj < 2; ++bj) { f32x4 b0, b1;
; template <class Epi, class Sched, bool ALIGN_EPI = false, bool SP2 = false>
; __device__ __forceinline__ void gemm_phase(PG8_LAS unsigned char* lds, const Gemm g, const Sched& S, const Epi& E) {
;     ...
;             PG8_WAIT_V(8); PG8_WAIT_L(0); PG8_BAR; PG8_MMA(0, 0, At, B0); PG8_MMA(0, 1, At, B1); PG8_BAR; PG8_SCHED;
;             PG8_LDA(At, 1, 1); PG8_STAGE(PG8_SB(1, 0), b3, voffB); PG8_STAGE(PG8_SB(1, 1), b3 + hstepB, voffB); PG8_STAGE(PG8_SA(1, 0), a3, voffA);
;             PG8_WAIT_V(8); PG8_WAIT_L(0); PG8_BAR; PG8_MMA(1, 0, At, B0); PG8_MMA(1, 1, At, B1); PG8_BAR; PG8_SCHED;
;             } else {
;             PG8_LDB(B0, 0, 0); PG8_SCHED; PG8_LDA(At, 0, 0); PG8_STAGE(PG8_SA(1, 1), a1 + hstepA, voffA);
;             PG8_WAIT_L(8); PG8_BAR; PG8_WAIT_L(0); PG8_MMA(0, 0, At, B0); PG8_BAR; PG8_SCHED;
;             PG8_LDB(B1, 0, 1); PG8_STAGE(PG8_SB(0, 0), b2, voffB);
;             PG8_BAR; PG8_WAIT_L(0); PG8_MMA(0, 1, At, B1); PG8_BAR;
;             PG8_LDA(At, 0, 1); PG8_STAGE(PG8_SA(0, 0), a2, voffA);
;             PG8_BAR; PG8_WAIT_L(0); PG8_MMA(1, 0, At, B0); PG8_BAR; PG8_SCHED;
;             PG8_STAGE(PG8_SB(0, 1), b2 + hstepB, voffB);
;             PG8_WAIT_V(6); PG8_BAR; PG8_MMA(1, 1, At, B1); PG8_BAR;
;             PG8_LDB(B0, 1, 0); PG8_SCHED; PG8_LDA(At, 1, 0); PG8_STAGE(PG8_SA(0, 1), a2 + hstepA, voffA);
;             PG8_WAIT_L(8); PG8_BAR; PG8_WAIT_L(0); PG8_MMA(0, 0, At, B0); PG8_BAR; PG8_SCHED;
;             PG8_LDB(B1, 1, 1); PG8_STAGE(PG8_SB(1, 0), b3, voffB);
;             PG8_BAR; PG8_WAIT_L(0); PG8_MMA(0, 1, At, B1); PG8_BAR;
;             PG8_LDA(At, 1, 1); PG8_STAGE(PG8_SA(1, 0), a3, voffA);
;             PG8_BAR; PG8_WAIT_L(0); PG8_MMA(1, 0, At, B0); PG8_BAR; PG8_SCHED;
;             PG8_STAGE(PG8_SB(1, 1), b3 + hstepB, voffB);
;             PG8_WAIT_V(6); PG8_BAR; PG8_MMA(1, 1, At, B1); PG8_BAR;
;             }
;         }
;         if constexpr (ALIGN_EPI) { if (wr == 0) PG8_BAR; }
	s_add_i32 s22, s28, s34
	v_lshl_add_u64 v[222:223], v[222:223], 0, s[18:19]
	s_mov_b32 m0, s22
	ds_read_b128 v[190:193], v159 offset:49152
	ds_read_b128 v[194:197], v159 offset:50176
	ds_read_b128 v[198:201], v159 offset:51200
	ds_read_b128 v[202:205], v159 offset:52224
	ds_read_b128 v[206:209], v159 offset:53248
	ds_read_b128 v[210:213], v159 offset:54272
	ds_read_b128 v[214:217], v159 offset:55296
	ds_read_b128 v[218:221], v159 offset:56320
	global_load_lds_dwordx4 v[222:223], off
	s_add_i32 m0, s22, 0x2000
	s_add_u32 s20, s20, 0x2c080
	v_lshl_add_u64 v[222:223], v[224:225], 0, s[18:19]
	s_addc_u32 s21, s21, 0
	s_add_i32 s22, s29, s34
	global_load_lds_dwordx4 v[222:223], off
	v_lshl_add_u64 v[222:223], s[20:21], 0, v[130:131]
	s_mov_b32 m0, s22
	s_nop 0
	global_load_lds_dwordx4 v[222:223], off
	v_lshl_add_u64 v[222:223], s[20:21], 0, v[134:135]
	s_add_i32 m0, s22, 0x2000
	s_nop 0
	global_load_lds_dwordx4 v[222:223], off
	v_lshl_add_u64 v[222:223], v[226:227], 0, s[18:19]
	s_mov_b32 m0, s50
	s_nop 0
	global_load_lds_dwordx4 v[222:223], off
	v_lshl_add_u64 v[222:223], v[228:229], 0, s[18:19]
	s_mov_b32 m0, s51
	s_nop 0
	global_load_lds_dwordx4 v[222:223], off
	s_waitcnt vmcnt(8)
	s_waitcnt lgkmcnt(0)
	s_barrier
	s_setprio 1
	s_waitcnt lgkmcnt(0)
	v_mfma_f32_16x16x32_bf16 v[60:63], v[146:149], v[190:193], v[60:63]
	v_mfma_f32_16x16x32_bf16 v[56:59], v[166:169], v[190:193], v[56:59]
	v_mfma_f32_16x16x32_bf16 v[44:47], v[146:149], v[198:201], v[44:47]
	v_mfma_f32_16x16x32_bf16 v[40:43], v[166:169], v[198:201], v[40:43]
	v_mfma_f32_16x16x32_bf16 v[28:31], v[146:149], v[206:209], v[28:31]
	v_mfma_f32_16x16x32_bf16 v[24:27], v[166:169], v[206:209], v[24:27]
	v_mfma_f32_16x16x32_bf16 v[12:15], v[146:149], v[214:217], v[12:15]
	v_mfma_f32_16x16x32_bf16 v[8:11], v[166:169], v[214:217], v[8:11]
	v_mfma_f32_16x16x32_bf16 v[60:63], v[162:165], v[194:197], v[60:63]
	v_mfma_f32_16x16x32_bf16 v[56:59], v[170:173], v[194:197], v[56:59]
	v_mfma_f32_16x16x32_bf16 v[44:47], v[162:165], v[202:205], v[44:47]
	v_mfma_f32_16x16x32_bf16 v[40:43], v[170:173], v[202:205], v[40:43]
	v_mfma_f32_16x16x32_bf16 v[28:31], v[162:165], v[210:213], v[28:31]
	v_mfma_f32_16x16x32_bf16 v[24:27], v[170:173], v[210:213], v[24:27]
	v_mfma_f32_16x16x32_bf16 v[12:15], v[162:165], v[218:221], v[12:15]
	v_mfma_f32_16x16x32_bf16 v[8:11], v[170:173], v[218:221], v[8:11]
	s_setprio 0
	s_setprio 1
	v_mfma_f32_16x16x32_bf16 v[52:55], v[174:177], v[190:193], v[52:55]
	v_mfma_f32_16x16x32_bf16 v[48:51], v[182:185], v[190:193], v[48:51]
	v_mfma_f32_16x16x32_bf16 v[36:39], v[174:177], v[198:201], v[36:39]
	v_mfma_f32_16x16x32_bf16 v[32:35], v[182:185], v[198:201], v[32:35]
	v_mfma_f32_16x16x32_bf16 v[20:23], v[174:177], v[206:209], v[20:23]
	v_mfma_f32_16x16x32_bf16 v[16:19], v[182:185], v[206:209], v[16:19]
	v_mfma_f32_16x16x32_bf16 v[4:7], v[174:177], v[214:217], v[4:7]
	v_mfma_f32_16x16x32_bf16 v[0:3], v[182:185], v[214:217], v[0:3]
	v_mfma_f32_16x16x32_bf16 v[52:55], v[178:181], v[194:197], v[52:55]
	v_mfma_f32_16x16x32_bf16 v[48:51], v[186:189], v[194:197], v[48:51]
	v_mfma_f32_16x16x32_bf16 v[36:39], v[178:181], v[202:205], v[36:39]
	v_mfma_f32_16x16x32_bf16 v[32:35], v[186:189], v[202:205], v[32:35]
	v_mfma_f32_16x16x32_bf16 v[20:23], v[178:181], v[210:213], v[20:23]
	v_mfma_f32_16x16x32_bf16 v[16:19], v[186:189], v[210:213], v[16:19]
	v_mfma_f32_16x16x32_bf16 v[4:7], v[178:181], v[218:221], v[4:7]
	v_mfma_f32_16x16x32_bf16 v[0:3], v[186:189], v[218:221], v[0:3]
	s_setprio 0
	s_barrier
	s_add_i32 s27, s27, 2
	s_add_u32 s0, s0, 0x100
	s_addc_u32 s1, s1, 0
	s_add_u32 s25, s25, 0x100
	s_addc_u32 s26, s26, 0
	s_cmp_gt_u32 s27, 41
	s_cbranch_scc0 .LBB0_757
	s_lshl_b32 s22, s24, 8
	s_add_i32 s22, s22, s49
	v_or_b32_e32 v148, s22, v150
	v_ashrrev_i32_e32 v149, 31, v148
	v_readlane_b32 s30, v239, 49
	v_lshl_or_b32 v146, s14, 8, v152
	v_lshlrev_b64 v[162:163], 11, v[148:149]
	v_readlane_b32 s31, v239, 50
	v_ashrrev_i32_e32 v147, 31, v146
	v_and_b32_e32 v170, 64, v160
	v_lshl_add_u64 v[162:163], s[30:31], 0, v[162:163]
	v_lshl_add_u64 v[166:167], v[146:147], 1, v[162:163]
	v_add_co_u32_e32 v184, vcc, 0x8000, v166
	s_nop 1
	v_addc_co_u32_e32 v185, vcc, 0, v167, vcc
	v_add_co_u32_e32 v192, vcc, 0x10000, v166
	s_nop 1
	v_addc_co_u32_e32 v193, vcc, 0, v167, vcc
	v_add_co_u32_e32 v200, vcc, 0x18000, v166
	s_nop 1
	v_addc_co_u32_e32 v201, vcc, 0, v167, vcc
	v_add_co_u32_e32 v208, vcc, 0x40000, v166
	s_nop 1
	v_addc_co_u32_e32 v209, vcc, 0, v167, vcc
	v_add_co_u32_e32 v216, vcc, 0x48000, v166
	s_nop 1
	v_addc_co_u32_e32 v217, vcc, 0, v167, vcc
	v_add_co_u32_e32 v224, vcc, 0x50000, v166
	s_nop 1
	v_addc_co_u32_e32 v225, vcc, 0, v167, vcc
	v_add_co_u32_e32 v232, vcc, 0x58000, v166
	s_nop 1
	v_addc_co_u32_e32 v233, vcc, 0, v167, vcc
	global_load_dwordx4 v[162:165], v[166:167], off
	s_nop 0
	global_load_dwordx4 v[166:169], v[166:167], off offset:64
	global_load_dwordx4 v[180:183], v[184:185], off
	global_load_dwordx4 v[184:187], v[184:185], off offset:64
	global_load_dwordx4 v[188:191], v[192:193], off
	global_load_dwordx4 v[192:195], v[192:193], off offset:64
	global_load_dwordx4 v[196:199], v[200:201], off
	global_load_dwordx4 v[200:203], v[200:201], off offset:64
	global_load_dwordx4 v[204:207], v[208:209], off
	global_load_dwordx4 v[208:211], v[208:209], off offset:64
	global_load_dwordx4 v[212:215], v[216:217], off
	global_load_dwordx4 v[216:219], v[216:217], off offset:64
	global_load_dwordx4 v[220:223], v[224:225], off
	global_load_dwordx4 v[224:227], v[224:225], off offset:64
	global_load_dwordx4 v[228:231], v[232:233], off
	global_load_dwordx4 v[232:235], v[232:233], off offset:64
	s_and_b64 vcc, exec, s[36:37]
	s_cbranch_vccz .LBB0_760
	s_barrier
; __device__ __forceinline__ unsigned swap8(unsigned v) { return (unsigned)__builtin_amdgcn_update_dpp(0, (int)v, 0x128  , 0xF, 0xF, false); }
; __device__ __forceinline__ void wide_store(bf16_t* O, int ldc, int rowg  , int col0  , int fr, u32x4 w0, u32x4 w1) {
;     const bool lo = fr < 8;
;     u32x4 snd = lo ? w1 : w0, rcv;
;     rcv.x = swap8(snd.x); rcv.y = swap8(snd.y); rcv.z = swap8(snd.z); rcv.w = swap8(snd.w);
;     const u32x4 first = lo ? w0 : rcv, second = lo ? rcv : w1;
;     bf16_t* p = O + (size_t)(rowg + (fr & 7)) * ldc + col0 + (lo ? 0 : 32);
;     __builtin_nontemporal_store(first, (u32x4*)p); __builtin_nontemporal_store(second, (u32x4*)(p + (size_t)8 * ldc));
;     __device__ __forceinline__ void operator()(const f32x4 (&acc)[2][2][4][2], const Unit& u, int wr, int wc, int fr, int fq) const {
;     ...
;             for (int m = 0; m < 4; ++m) { const int rowg = u.pm * BM + ai * HALF + wr * 64 + m * 16, row = rowg + fr; const size_t off = (size_t)row * 1024 + col0;
;                 u32x4 w[2]; float ss = 0.f;
; #pragma unroll
;                 for (int bj = 0; bj < 2; ++bj) { f32x4 b0, b1;
;                     if (BASE_F32) { const float* bp = (const float*)base + off + 32 * bj; b0 = *(const f32x4*)bp; b1 = *(const f32x4*)(bp + 4); }
;                     else { const u32x4 bb = *(const u32x4*)((const bf16_t*)base + off + 32 * bj);
;                         b0 = (f32x4){__uint_as_float(bb.x << 16), __uint_as_float(bb.x & 0xffff0000u), __uint_as_float(bb.y << 16), __uint_as_float(bb.y & 0xffff0000u)};
;                         b1 = (f32x4){__uint_as_float(bb.z << 16), __uint_as_float(bb.z & 0xffff0000u), __uint_as_float(bb.w << 16), __uint_as_float(bb.w & 0xffff0000u)}; }
;                     const f32x4 o0 = b0 + acc[ai][bj][m][0], o1 = b1 + acc[ai][bj][m][1];
;                     ss += ((o0[0] * o0[0] + o0[1] * o0[1]) + (o0[2] * o0[2] + o0[3] * o0[3])) + ((o1[0] * o1[0] + o1[1] * o1[1]) + (o1[2] * o1[2] + o1[3] * o1[3]));
;                     w[bj].x = cvt_pk_bf16(o0[0], o0[1]); w[bj].y = cvt_pk_bf16(o0[2], o0[3]); w[bj].z = cvt_pk_bf16(o1[0], o1[1]); w[bj].w = cvt_pk_bf16(o1[2], o1[3]); }
;                 ss += __shfl_xor(ss, 16); ss += __shfl_xor(ss, 32); if (fq == 0) slots[(size_t)row * 16 + u.pn * 4 + wc] = ss;
;                 wide_store(xb, 1024, rowg, col0, fr, w[0], w[1]);
.LBB0_760:
	v_add_u32_e32 v178, 64, v170
	v_xor_b32_e32 v161, 16, v160
	v_cmp_lt_i32_e32 vcc, v161, v178
	s_lshl_b32 s0, s14, 2
	s_ashr_i32 s1, s0, 31
	v_cndmask_b32_e32 v161, v160, v161, vcc
	v_lshlrev_b32_e32 v161, 2, v161
	s_waitcnt vmcnt(14)
	v_lshlrev_b32_e32 v170, 16, v162
	v_and_b32_e32 v171, 0xffff0000, v162
	v_lshlrev_b32_e32 v162, 16, v163
	v_and_b32_e32 v163, 0xffff0000, v163
	v_lshlrev_b32_e32 v172, 16, v164
	v_and_b32_e32 v173, 0xffff0000, v164
	v_lshlrev_b32_e32 v164, 16, v165
	v_and_b32_e32 v165, 0xffff0000, v165
	v_lshlrev_b32_e32 v174, 16, v166
	v_and_b32_e32 v175, 0xffff0000, v166
	v_lshlrev_b32_e32 v166, 16, v167
	v_and_b32_e32 v167, 0xffff0000, v167
	v_lshlrev_b32_e32 v176, 16, v168
	v_and_b32_e32 v177, 0xffff0000, v168
	v_lshlrev_b32_e32 v168, 16, v169
	v_and_b32_e32 v169, 0xffff0000, v169
	v_pk_add_f32 v[126:127], v[126:127], v[162:163]
	v_pk_add_f32 v[124:125], v[124:125], v[170:171]
	v_pk_add_f32 v[122:123], v[122:123], v[164:165]
	v_pk_add_f32 v[120:121], v[120:121], v[172:173]
	v_pk_add_f32 v[118:119], v[118:119], v[166:167]
	v_pk_add_f32 v[116:117], v[116:117], v[174:175]
	v_pk_add_f32 v[114:115], v[114:115], v[168:169]
	v_pk_add_f32 v[112:113], v[112:113], v[176:177]
	v_mul_f32_e32 v162, v125, v125
	v_mul_f32_e32 v163, v127, v127
	v_mul_f32_e32 v164, v121, v121
	v_mul_f32_e32 v165, v123, v123
	v_mul_f32_e32 v166, v117, v117
	v_mul_f32_e32 v167, v119, v119
	v_mul_f32_e32 v168, v113, v113
	v_mul_f32_e32 v169, v115, v115
	v_fmac_f32_e32 v162, v124, v124
	v_fmac_f32_e32 v163, v126, v126
	v_fmac_f32_e32 v164, v120, v120
	v_fmac_f32_e32 v165, v122, v122
	v_fmac_f32_e32 v166, v116, v116
	v_fmac_f32_e32 v167, v118, v118
	v_fmac_f32_e32 v168, v112, v112
	v_fmac_f32_e32 v169, v114, v114
	v_add_f32_e32 v162, v162, v163
	v_add_f32_e32 v163, v164, v165
	v_add_f32_e32 v164, v166, v167
	v_add_f32_e32 v165, v168, v169
	v_add_f32_e32 v162, v162, v163
	v_add_f32_e32 v163, v164, v165
	v_add_f32_e32 v163, v162, v163
	ds_bpermute_b32 v164, v161, v163
	v_xor_b32_e32 v162, 32, v160
	v_cmp_lt_i32_e32 vcc, v162, v178
	s_waitcnt lgkmcnt(0)
	v_add_f32_e32 v163, v163, v164
	v_cndmask_b32_e32 v162, v160, v162, vcc
	v_lshlrev_b32_e32 v162, 2, v162
	ds_bpermute_b32 v164, v162, v163
	s_and_saveexec_b64 s[20:21], s[2:3]
	s_cbranch_execz .LBB0_762
	v_lshlrev_b64 v[148:149], 6, v[148:149]
	v_lshl_add_u64 v[148:149], s[82:83], 0, v[148:149]
	v_lshl_add_u64 v[148:149], s[0:1], 2, v[148:149]
	s_lshl_b32 s14, s48, 2
	v_lshl_add_u64 v[148:149], v[148:149], 0, s[14:15]
	s_waitcnt lgkmcnt(0)
	v_add_f32_e32 v163, v163, v164
	global_store_dword v[148:149], v163, off
.LBB0_762:
	s_or_b64 exec, exec, s[20:21]
	v_cvt_pk_bf16_f32 v120, v120, v121
	v_cvt_pk_bf16_f32 v112, v112, v113
	v_cvt_pk_bf16_f32 v124, v124, v125
	v_cvt_pk_bf16_f32 v125, v126, v127
	v_cvt_pk_bf16_f32 v121, v122, v123
	v_cvt_pk_bf16_f32 v118, v118, v119
	v_cvt_pk_bf16_f32 v113, v114, v115
	v_cndmask_b32_e64 v115, v120, v112, s[4:5]
	v_mov_b32_e32 v126, v137
	v_cvt_pk_bf16_f32 v122, v116, v117
	v_cndmask_b32_e64 v114, v121, v113, s[4:5]
	v_cndmask_b32_e64 v116, v125, v118, s[4:5]
	v_mov_b32_e32 v119, v137
	v_mov_b32_dpp v126, v115 row_ror:8 row_mask:0xf bank_mask:0xf
	v_mov_b32_e32 v127, v137
	v_cndmask_b32_e64 v117, v124, v122, s[4:5]
	v_mov_b32_e32 v123, v137
	v_mov_b32_dpp v119, v116 row_ror:8 row_mask:0xf bank_mask:0xf
	v_mov_b32_dpp v127, v114 row_ror:8 row_mask:0xf bank_mask:0xf
	v_cndmask_b32_e64 v116, v126, v120, s[4:5]
	v_cndmask_b32_e64 v120, v112, v126, s[4:5]
	v_or_b32_e32 v112, s22, v156
	v_mov_b32_dpp v123, v117 row_ror:8 row_mask:0xf bank_mask:0xf
	v_cndmask_b32_e64 v117, v127, v121, s[4:5]
	v_cndmask_b32_e64 v121, v113, v127, s[4:5]
	v_ashrrev_i32_e32 v113, 31, v112
	v_lshlrev_b64 v[112:113], 11, v[112:113]
	v_cndmask_b32_e64 v115, v119, v125, s[4:5]
	v_cndmask_b32_e64 v114, v123, v124, s[4:5]
	v_cndmask_b32_e64 v119, v118, v119, s[4:5]
	v_cndmask_b32_e64 v118, v122, v123, s[4:5]
	v_lshl_add_u64 v[122:123], s[30:31], 0, v[112:113]
	v_lshlrev_b64 v[112:113], 1, v[146:147]
	v_lshl_add_u64 v[122:123], v[122:123], 0, v[112:113]
	v_lshl_add_u64 v[122:123], v[122:123], 0, v[136:137]
	global_store_dwordx4 v[122:123], v[114:117], off nt
	s_or_b32 s23, s22, 16
	s_nop 0
	v_add_co_u32_e32 v114, vcc, s47, v122
	s_nop 1
	v_addc_co_u32_e32 v115, vcc, 0, v123, vcc
	global_store_dwordx4 v[114:115], v[118:121], off nt
	v_or_b32_e32 v114, s23, v150
	v_ashrrev_i32_e32 v115, 31, v114
	v_lshlrev_b64 v[116:117], 11, v[114:115]
	v_lshl_add_u64 v[116:117], s[30:31], 0, v[116:117]
	v_lshl_add_u64 v[120:121], v[116:117], 0, v[112:113]
	s_waitcnt vmcnt(15)
	v_mov_b32_e32 v116, v180
	v_mov_b32_e32 v117, v181
	v_mov_b32_e32 v118, v182
	v_mov_b32_e32 v119, v183
	v_mov_b32_e32 v120, v184
	v_mov_b32_e32 v121, v185
	v_mov_b32_e32 v122, v186
	v_mov_b32_e32 v123, v187
	v_lshlrev_b32_e32 v124, 16, v116
	v_and_b32_e32 v125, 0xffff0000, v116
	v_lshlrev_b32_e32 v116, 16, v117
	v_and_b32_e32 v117, 0xffff0000, v117
	v_lshlrev_b32_e32 v126, 16, v118
	v_and_b32_e32 v127, 0xffff0000, v118
	v_lshlrev_b32_e32 v118, 16, v119
	v_and_b32_e32 v119, 0xffff0000, v119
	v_lshlrev_b32_e32 v148, 16, v120
	v_and_b32_e32 v149, 0xffff0000, v120
	v_lshlrev_b32_e32 v120, 16, v121
	v_and_b32_e32 v121, 0xffff0000, v121
	s_waitcnt lgkmcnt(0)
	v_lshlrev_b32_e32 v164, 16, v122
	v_and_b32_e32 v165, 0xffff0000, v122
	v_lshlrev_b32_e32 v122, 16, v123
	v_and_b32_e32 v123, 0xffff0000, v123
	v_pk_add_f32 v[110:111], v[110:111], v[116:117]
	v_pk_add_f32 v[108:109], v[108:109], v[124:125]
	v_pk_add_f32 v[106:107], v[106:107], v[118:119]
	v_pk_add_f32 v[104:105], v[104:105], v[126:127]
	v_pk_add_f32 v[102:103], v[102:103], v[120:121]
	v_pk_add_f32 v[100:101], v[100:101], v[148:149]
	v_pk_add_f32 v[98:99], v[98:99], v[122:123]
	v_pk_add_f32 v[96:97], v[96:97], v[164:165]
	v_mul_f32_e32 v116, v109, v109
	v_mul_f32_e32 v117, v111, v111
	v_mul_f32_e32 v118, v105, v105
	v_mul_f32_e32 v119, v107, v107
	v_mul_f32_e32 v120, v101, v101
	v_mul_f32_e32 v121, v103, v103
	v_mul_f32_e32 v122, v97, v97
	v_mul_f32_e32 v123, v99, v99
	v_fmac_f32_e32 v116, v108, v108
	v_fmac_f32_e32 v117, v110, v110
	v_fmac_f32_e32 v118, v104, v104
	v_fmac_f32_e32 v119, v106, v106
	v_fmac_f32_e32 v120, v100, v100
	v_fmac_f32_e32 v121, v102, v102
	v_fmac_f32_e32 v122, v96, v96
	v_fmac_f32_e32 v123, v98, v98
	v_add_f32_e32 v116, v116, v117
	v_add_f32_e32 v117, v118, v119
	v_add_f32_e32 v118, v120, v121
	v_add_f32_e32 v119, v122, v123
	v_add_f32_e32 v116, v116, v117
	v_add_f32_e32 v117, v118, v119
	v_add_f32_e32 v116, v116, v117
	ds_bpermute_b32 v117, v161, v116
	s_waitcnt lgkmcnt(0)
	v_add_f32_e32 v116, v116, v117
	ds_bpermute_b32 v117, v162, v116
	s_and_saveexec_b64 s[20:21], s[2:3]
	s_cbranch_execz .LBB0_764
	v_lshlrev_b64 v[114:115], 6, v[114:115]
	v_lshl_add_u64 v[114:115], s[82:83], 0, v[114:115]
	v_lshl_add_u64 v[114:115], s[0:1], 2, v[114:115]
	s_lshl_b32 s14, s48, 2
	v_lshl_add_u64 v[114:115], v[114:115], 0, s[14:15]
	s_waitcnt lgkmcnt(0)
	v_add_f32_e32 v116, v116, v117
	global_store_dword v[114:115], v116, off
; __device__ __forceinline__ unsigned swap8(unsigned v) { return (unsigned)__builtin_amdgcn_update_dpp(0, (int)v, 0x128  , 0xF, 0xF, false); }
; __device__ __forceinline__ void wide_store(bf16_t* O, int ldc, int rowg  , int col0  , int fr, u32x4 w0, u32x4 w1) {
;     const bool lo = fr < 8;
;     u32x4 snd = lo ? w1 : w0, rcv;
;     rcv.x = swap8(snd.x); rcv.y = swap8(snd.y); rcv.z = swap8(snd.z); rcv.w = swap8(snd.w);
;     const u32x4 first = lo ? w0 : rcv, second = lo ? rcv : w1;
;     bf16_t* p = O + (size_t)(rowg + (fr & 7)) * ldc + col0 + (lo ? 0 : 32);
;     __builtin_nontemporal_store(first, (u32x4*)p); __builtin_nontemporal_store(second, (u32x4*)(p + (size_t)8 * ldc));
;     __device__ __forceinline__ void operator()(const f32x4 (&acc)[2][2][4][2], const Unit& u, int wr, int wc, int fr, int fq) const {
;     ...
;             for (int m = 0; m < 4; ++m) { const int rowg = u.pm * BM + ai * HALF + wr * 64 + m * 16, row = rowg + fr; const size_t off = (size_t)row * 1024 + col0;
;                 u32x4 w[2]; float ss = 0.f;
; #pragma unroll
;                 for (int bj = 0; bj < 2; ++bj) { f32x4 b0, b1;
;                     if (BASE_F32) { const float* bp = (const float*)base + off + 32 * bj; b0 = *(const f32x4*)bp; b1 = *(const f32x4*)(bp + 4); }
;                     else { const u32x4 bb = *(const u32x4*)((const bf16_t*)base + off + 32 * bj);
;                         b0 = (f32x4){__uint_as_float(bb.x << 16), __uint_as_float(bb.x & 0xffff0000u), __uint_as_float(bb.y << 16), __uint_as_float(bb.y & 0xffff0000u)};
;                         b1 = (f32x4){__uint_as_float(bb.z << 16), __uint_as_float(bb.z & 0xffff0000u), __uint_as_float(bb.w << 16), __uint_as_float(bb.w & 0xffff0000u)}; }
;                     const f32x4 o0 = b0 + acc[ai][bj][m][0], o1 = b1 + acc[ai][bj][m][1];
;                     ss += ((o0[0] * o0[0] + o0[1] * o0[1]) + (o0[2] * o0[2] + o0[3] * o0[3])) + ((o1[0] * o1[0] + o1[1] * o1[1]) + (o1[2] * o1[2] + o1[3] * o1[3]));
;                     w[bj].x = cvt_pk_bf16(o0[0], o0[1]); w[bj].y = cvt_pk_bf16(o0[2], o0[3]); w[bj].z = cvt_pk_bf16(o1[0], o1[1]); w[bj].w = cvt_pk_bf16(o1[2], o1[3]); }
;                 ss += __shfl_xor(ss, 16); ss += __shfl_xor(ss, 32); if (fq == 0) slots[(size_t)row * 16 + u.pn * 4 + wc] = ss;
;                 wide_store(xb, 1024, rowg, col0, fr, w[0], w[1]);
.LBB0_764:
	s_or_b64 exec, exec, s[20:21]
	v_cvt_pk_bf16_f32 v104, v104, v105
	v_cvt_pk_bf16_f32 v100, v100, v101
	v_cvt_pk_bf16_f32 v101, v102, v103
	v_cvt_pk_bf16_f32 v102, v96, v97
	v_cvt_pk_bf16_f32 v108, v108, v109
	v_cvt_pk_bf16_f32 v109, v110, v111
	v_cvt_pk_bf16_f32 v105, v106, v107
	v_cvt_pk_bf16_f32 v103, v98, v99
	v_cndmask_b32_e64 v97, v104, v102, s[4:5]
	v_mov_b32_e32 v110, v137
	v_cndmask_b32_e64 v96, v105, v103, s[4:5]
	v_cndmask_b32_e64 v98, v109, v101, s[4:5]
	v_mov_b32_e32 v107, v137
	v_mov_b32_dpp v110, v97 row_ror:8 row_mask:0xf bank_mask:0xf
	v_mov_b32_e32 v111, v137
	v_cndmask_b32_e64 v99, v108, v100, s[4:5]
	v_mov_b32_e32 v106, v137
	v_mov_b32_dpp v107, v98 row_ror:8 row_mask:0xf bank_mask:0xf
	v_mov_b32_dpp v111, v96 row_ror:8 row_mask:0xf bank_mask:0xf
	v_cndmask_b32_e64 v98, v110, v104, s[4:5]
	v_or_b32_e32 v104, s23, v156
	v_mov_b32_dpp v106, v99 row_ror:8 row_mask:0xf bank_mask:0xf
	v_cndmask_b32_e64 v99, v111, v105, s[4:5]
	v_ashrrev_i32_e32 v105, 31, v104
	v_lshlrev_b64 v[104:105], 11, v[104:105]
	v_lshl_add_u64 v[104:105], s[30:31], 0, v[104:105]
	v_lshl_add_u64 v[104:105], v[104:105], 0, v[112:113]
	v_cndmask_b32_e64 v97, v107, v109, s[4:5]
	v_cndmask_b32_e64 v96, v106, v108, s[4:5]
	v_lshl_add_u64 v[104:105], v[104:105], 0, v[136:137]
	global_store_dwordx4 v[104:105], v[96:99], off nt
	v_cndmask_b32_e64 v103, v103, v111, s[4:5]
	v_cndmask_b32_e64 v102, v102, v110, s[4:5]
	v_add_co_u32_e32 v96, vcc, s47, v104
	v_cndmask_b32_e64 v101, v101, v107, s[4:5]
	v_cndmask_b32_e64 v100, v100, v106, s[4:5]
	v_addc_co_u32_e32 v97, vcc, 0, v105, vcc
	s_or_b32 s23, s22, 32
	global_store_dwordx4 v[96:97], v[100:103], off nt
	v_or_b32_e32 v96, s23, v150
	v_ashrrev_i32_e32 v97, 31, v96
	v_lshlrev_b64 v[98:99], 11, v[96:97]
	v_lshl_add_u64 v[98:99], s[30:31], 0, v[98:99]
	v_lshl_add_u64 v[102:103], v[98:99], 0, v[112:113]
	s_waitcnt vmcnt(16)
	v_mov_b32_e32 v98, v188
	v_mov_b32_e32 v99, v189
	v_mov_b32_e32 v100, v190
	v_mov_b32_e32 v101, v191
	v_mov_b32_e32 v102, v192
	v_mov_b32_e32 v103, v193
	v_mov_b32_e32 v104, v194
	v_mov_b32_e32 v105, v195
	v_lshlrev_b32_e32 v106, 16, v98
	v_and_b32_e32 v107, 0xffff0000, v98
	v_lshlrev_b32_e32 v98, 16, v99
	v_and_b32_e32 v99, 0xffff0000, v99
	v_lshlrev_b32_e32 v108, 16, v100
	v_and_b32_e32 v109, 0xffff0000, v100
	v_lshlrev_b32_e32 v100, 16, v101
	v_and_b32_e32 v101, 0xffff0000, v101
	v_lshlrev_b32_e32 v110, 16, v102
	v_and_b32_e32 v111, 0xffff0000, v102
	v_lshlrev_b32_e32 v102, 16, v103
	v_and_b32_e32 v103, 0xffff0000, v103
	v_lshlrev_b32_e32 v114, 16, v104
	v_and_b32_e32 v115, 0xffff0000, v104
	v_lshlrev_b32_e32 v104, 16, v105
	v_and_b32_e32 v105, 0xffff0000, v105
	v_pk_add_f32 v[94:95], v[94:95], v[98:99]
	v_pk_add_f32 v[92:93], v[92:93], v[106:107]
	v_pk_add_f32 v[90:91], v[90:91], v[100:101]
	v_pk_add_f32 v[88:89], v[88:89], v[108:109]
	v_pk_add_f32 v[86:87], v[86:87], v[102:103]
	v_pk_add_f32 v[84:85], v[84:85], v[110:111]
	v_pk_add_f32 v[82:83], v[82:83], v[104:105]
	v_pk_add_f32 v[80:81], v[80:81], v[114:115]
	v_mul_f32_e32 v98, v93, v93
	v_mul_f32_e32 v99, v95, v95
	v_mul_f32_e32 v100, v89, v89
	v_mul_f32_e32 v101, v91, v91
	v_mul_f32_e32 v102, v85, v85
	v_mul_f32_e32 v103, v87, v87
	v_mul_f32_e32 v104, v81, v81
	v_mul_f32_e32 v105, v83, v83
	v_fmac_f32_e32 v98, v92, v92
	v_fmac_f32_e32 v99, v94, v94
	v_fmac_f32_e32 v100, v88, v88
	v_fmac_f32_e32 v101, v90, v90
	v_fmac_f32_e32 v102, v84, v84
	v_fmac_f32_e32 v103, v86, v86
	v_fmac_f32_e32 v104, v80, v80
	v_fmac_f32_e32 v105, v82, v82
	v_add_f32_e32 v98, v98, v99
	v_add_f32_e32 v99, v100, v101
	v_add_f32_e32 v100, v102, v103
	v_add_f32_e32 v101, v104, v105
	v_add_f32_e32 v98, v98, v99
	v_add_f32_e32 v99, v100, v101
	v_add_f32_e32 v98, v98, v99
	ds_bpermute_b32 v99, v161, v98
	s_waitcnt lgkmcnt(0)
	v_add_f32_e32 v98, v98, v99
	ds_bpermute_b32 v99, v162, v98
	s_and_saveexec_b64 s[20:21], s[2:3]
	s_cbranch_execz .LBB0_766
	v_lshlrev_b64 v[96:97], 6, v[96:97]
	v_lshl_add_u64 v[96:97], s[82:83], 0, v[96:97]
	v_lshl_add_u64 v[96:97], s[0:1], 2, v[96:97]
	s_lshl_b32 s14, s48, 2
	v_lshl_add_u64 v[96:97], v[96:97], 0, s[14:15]
	s_waitcnt lgkmcnt(0)
	v_add_f32_e32 v98, v98, v99
	global_store_dword v[96:97], v98, off
.LBB0_766:
	s_or_b64 exec, exec, s[20:21]
	v_cvt_pk_bf16_f32 v88, v88, v89
	v_cvt_pk_bf16_f32 v84, v84, v85
	v_cvt_pk_bf16_f32 v85, v86, v87
	v_cvt_pk_bf16_f32 v86, v80, v81
	v_cvt_pk_bf16_f32 v92, v92, v93
	v_cvt_pk_bf16_f32 v93, v94, v95
	v_cvt_pk_bf16_f32 v89, v90, v91
	v_cvt_pk_bf16_f32 v87, v82, v83
	v_cndmask_b32_e64 v81, v88, v86, s[4:5]
	v_mov_b32_e32 v94, v137
	v_cndmask_b32_e64 v80, v89, v87, s[4:5]
	v_cndmask_b32_e64 v82, v93, v85, s[4:5]
	v_mov_b32_e32 v91, v137
	v_mov_b32_dpp v94, v81 row_ror:8 row_mask:0xf bank_mask:0xf
	v_mov_b32_e32 v95, v137
	v_cndmask_b32_e64 v83, v92, v84, s[4:5]
	v_mov_b32_e32 v90, v137
	v_mov_b32_dpp v91, v82 row_ror:8 row_mask:0xf bank_mask:0xf
	v_mov_b32_dpp v95, v80 row_ror:8 row_mask:0xf bank_mask:0xf
	v_cndmask_b32_e64 v82, v94, v88, s[4:5]
	v_or_b32_e32 v88, s23, v156
	v_mov_b32_dpp v90, v83 row_ror:8 row_mask:0xf bank_mask:0xf
	v_cndmask_b32_e64 v83, v95, v89, s[4:5]
	v_ashrrev_i32_e32 v89, 31, v88
	v_lshlrev_b64 v[88:89], 11, v[88:89]
	v_lshl_add_u64 v[88:89], s[30:31], 0, v[88:89]
	v_lshl_add_u64 v[88:89], v[88:89], 0, v[112:113]
	v_cndmask_b32_e64 v81, v91, v93, s[4:5]
	v_cndmask_b32_e64 v80, v90, v92, s[4:5]
	v_lshl_add_u64 v[88:89], v[88:89], 0, v[136:137]
	global_store_dwordx4 v[88:89], v[80:83], off nt
	v_cndmask_b32_e64 v87, v87, v95, s[4:5]
	v_cndmask_b32_e64 v86, v86, v94, s[4:5]
	v_add_co_u32_e32 v80, vcc, s47, v88
	v_cndmask_b32_e64 v85, v85, v91, s[4:5]
	v_cndmask_b32_e64 v84, v84, v90, s[4:5]
	v_addc_co_u32_e32 v81, vcc, 0, v89, vcc
	s_or_b32 s23, s22, 48
	global_store_dwordx4 v[80:81], v[84:87], off nt
	v_or_b32_e32 v80, s23, v150
	v_ashrrev_i32_e32 v81, 31, v80
	v_lshlrev_b64 v[82:83], 11, v[80:81]
	v_lshl_add_u64 v[82:83], s[30:31], 0, v[82:83]
	v_lshl_add_u64 v[86:87], v[82:83], 0, v[112:113]
	s_waitcnt vmcnt(17)
; __device__ __forceinline__ unsigned swap8(unsigned v) { return (unsigned)__builtin_amdgcn_update_dpp(0, (int)v, 0x128  , 0xF, 0xF, false); }
; __device__ __forceinline__ void wide_store(bf16_t* O, int ldc, int rowg  , int col0  , int fr, u32x4 w0, u32x4 w1) {
;     const bool lo = fr < 8;
;     u32x4 snd = lo ? w1 : w0, rcv;
;     rcv.x = swap8(snd.x); rcv.y = swap8(snd.y); rcv.z = swap8(snd.z); rcv.w = swap8(snd.w);
;     const u32x4 first = lo ? w0 : rcv, second = lo ? rcv : w1;
;     bf16_t* p = O + (size_t)(rowg + (fr & 7)) * ldc + col0 + (lo ? 0 : 32);
;     __builtin_nontemporal_store(first, (u32x4*)p); __builtin_nontemporal_store(second, (u32x4*)(p + (size_t)8 * ldc));
;     __device__ __forceinline__ void operator()(const f32x4 (&acc)[2][2][4][2], const Unit& u, int wr, int wc, int fr, int fq) const {
;     ...
;             for (int m = 0; m < 4; ++m) { const int rowg = u.pm * BM + ai * HALF + wr * 64 + m * 16, row = rowg + fr; const size_t off = (size_t)row * 1024 + col0;
;                 u32x4 w[2]; float ss = 0.f;
; #pragma unroll
;                 for (int bj = 0; bj < 2; ++bj) { f32x4 b0, b1;
;                     if (BASE_F32) { const float* bp = (const float*)base + off + 32 * bj; b0 = *(const f32x4*)bp; b1 = *(const f32x4*)(bp + 4); }
;                     else { const u32x4 bb = *(const u32x4*)((const bf16_t*)base + off + 32 * bj);
;                         b0 = (f32x4){__uint_as_float(bb.x << 16), __uint_as_float(bb.x & 0xffff0000u), __uint_as_float(bb.y << 16), __uint_as_float(bb.y & 0xffff0000u)};
;                         b1 = (f32x4){__uint_as_float(bb.z << 16), __uint_as_float(bb.z & 0xffff0000u), __uint_as_float(bb.w << 16), __uint_as_float(bb.w & 0xffff0000u)}; }
;                     const f32x4 o0 = b0 + acc[ai][bj][m][0], o1 = b1 + acc[ai][bj][m][1];
;                     ss += ((o0[0] * o0[0] + o0[1] * o0[1]) + (o0[2] * o0[2] + o0[3] * o0[3])) + ((o1[0] * o1[0] + o1[1] * o1[1]) + (o1[2] * o1[2] + o1[3] * o1[3]));
;                     w[bj].x = cvt_pk_bf16(o0[0], o0[1]); w[bj].y = cvt_pk_bf16(o0[2], o0[3]); w[bj].z = cvt_pk_bf16(o1[0], o1[1]); w[bj].w = cvt_pk_bf16(o1[2], o1[3]); }
;                 ss += __shfl_xor(ss, 16); ss += __shfl_xor(ss, 32); if (fq == 0) slots[(size_t)row * 16 + u.pn * 4 + wc] = ss;
;                 wide_store(xb, 1024, rowg, col0, fr, w[0], w[1]);
	v_mov_b32_e32 v82, v196
	v_mov_b32_e32 v83, v197
	v_mov_b32_e32 v84, v198
	v_mov_b32_e32 v85, v199
	v_mov_b32_e32 v86, v200
	v_mov_b32_e32 v87, v201
	v_mov_b32_e32 v88, v202
	v_mov_b32_e32 v89, v203
	v_lshlrev_b32_e32 v90, 16, v82
	v_and_b32_e32 v91, 0xffff0000, v82
	v_lshlrev_b32_e32 v82, 16, v83
	v_and_b32_e32 v83, 0xffff0000, v83
	v_lshlrev_b32_e32 v92, 16, v84
	v_and_b32_e32 v93, 0xffff0000, v84
	v_lshlrev_b32_e32 v84, 16, v85
	v_and_b32_e32 v85, 0xffff0000, v85
	v_lshlrev_b32_e32 v94, 16, v86
	v_and_b32_e32 v95, 0xffff0000, v86
	v_lshlrev_b32_e32 v86, 16, v87
	v_and_b32_e32 v87, 0xffff0000, v87
	v_lshlrev_b32_e32 v96, 16, v88
	v_and_b32_e32 v97, 0xffff0000, v88
	v_lshlrev_b32_e32 v88, 16, v89
	v_and_b32_e32 v89, 0xffff0000, v89
	v_pk_add_f32 v[78:79], v[78:79], v[82:83]
	v_pk_add_f32 v[76:77], v[76:77], v[90:91]
	v_pk_add_f32 v[74:75], v[74:75], v[84:85]
	v_pk_add_f32 v[72:73], v[72:73], v[92:93]
	v_pk_add_f32 v[70:71], v[70:71], v[86:87]
	v_pk_add_f32 v[68:69], v[68:69], v[94:95]
	v_pk_add_f32 v[66:67], v[66:67], v[88:89]
	v_pk_add_f32 v[64:65], v[64:65], v[96:97]
	v_mul_f32_e32 v82, v77, v77
	v_mul_f32_e32 v83, v79, v79
	v_mul_f32_e32 v84, v73, v73
	v_mul_f32_e32 v85, v75, v75
	v_mul_f32_e32 v86, v69, v69
	v_mul_f32_e32 v87, v71, v71
	v_mul_f32_e32 v88, v65, v65
	v_mul_f32_e32 v89, v67, v67
	v_fmac_f32_e32 v82, v76, v76
	v_fmac_f32_e32 v83, v78, v78
	v_fmac_f32_e32 v84, v72, v72
	v_fmac_f32_e32 v85, v74, v74
	v_fmac_f32_e32 v86, v68, v68
	v_fmac_f32_e32 v87, v70, v70
	v_fmac_f32_e32 v88, v64, v64
	v_fmac_f32_e32 v89, v66, v66
	v_add_f32_e32 v82, v82, v83
	v_add_f32_e32 v83, v84, v85
	v_add_f32_e32 v84, v86, v87
	v_add_f32_e32 v85, v88, v89
	v_add_f32_e32 v82, v82, v83
	v_add_f32_e32 v83, v84, v85
	v_add_f32_e32 v82, v82, v83
	ds_bpermute_b32 v83, v161, v82
	s_waitcnt lgkmcnt(0)
	v_add_f32_e32 v82, v82, v83
	ds_bpermute_b32 v83, v162, v82
	s_and_saveexec_b64 s[20:21], s[2:3]
	s_cbranch_execz .LBB0_768
	v_lshlrev_b64 v[80:81], 6, v[80:81]
	v_lshl_add_u64 v[80:81], s[82:83], 0, v[80:81]
	v_lshl_add_u64 v[80:81], s[0:1], 2, v[80:81]
	s_lshl_b32 s14, s48, 2
	v_lshl_add_u64 v[80:81], v[80:81], 0, s[14:15]
	s_waitcnt lgkmcnt(0)
	v_add_f32_e32 v82, v82, v83
	global_store_dword v[80:81], v82, off
.LBB0_768:
	s_or_b64 exec, exec, s[20:21]
	v_cvt_pk_bf16_f32 v72, v72, v73
	v_cvt_pk_bf16_f32 v68, v68, v69
	v_cvt_pk_bf16_f32 v69, v70, v71
	v_cvt_pk_bf16_f32 v70, v64, v65
	v_cvt_pk_bf16_f32 v76, v76, v77
	v_cvt_pk_bf16_f32 v77, v78, v79
	v_cvt_pk_bf16_f32 v73, v74, v75
	v_cvt_pk_bf16_f32 v71, v66, v67
	v_cndmask_b32_e64 v65, v72, v70, s[4:5]
	v_mov_b32_e32 v78, v137
	v_cndmask_b32_e64 v64, v73, v71, s[4:5]
	v_cndmask_b32_e64 v66, v77, v69, s[4:5]
	v_mov_b32_e32 v75, v137
	v_mov_b32_dpp v78, v65 row_ror:8 row_mask:0xf bank_mask:0xf
	v_mov_b32_e32 v79, v137
	v_cndmask_b32_e64 v67, v76, v68, s[4:5]
	v_mov_b32_e32 v74, v137
	v_mov_b32_dpp v75, v66 row_ror:8 row_mask:0xf bank_mask:0xf
	v_mov_b32_dpp v79, v64 row_ror:8 row_mask:0xf bank_mask:0xf
	v_cndmask_b32_e64 v66, v78, v72, s[4:5]
	v_or_b32_e32 v72, s23, v156
	v_mov_b32_dpp v74, v67 row_ror:8 row_mask:0xf bank_mask:0xf
	v_cndmask_b32_e64 v67, v79, v73, s[4:5]
	v_ashrrev_i32_e32 v73, 31, v72
	v_lshlrev_b64 v[72:73], 11, v[72:73]
	v_lshl_add_u64 v[72:73], s[30:31], 0, v[72:73]
	v_lshl_add_u64 v[72:73], v[72:73], 0, v[112:113]
	v_cndmask_b32_e64 v65, v75, v77, s[4:5]
	v_cndmask_b32_e64 v64, v74, v76, s[4:5]
	v_lshl_add_u64 v[72:73], v[72:73], 0, v[136:137]
	global_store_dwordx4 v[72:73], v[64:67], off nt
	v_cndmask_b32_e64 v71, v71, v79, s[4:5]
	v_cndmask_b32_e64 v70, v70, v78, s[4:5]
	v_add_co_u32_e32 v64, vcc, s47, v72
	v_cndmask_b32_e64 v69, v69, v75, s[4:5]
	v_cndmask_b32_e64 v68, v68, v74, s[4:5]
	v_addc_co_u32_e32 v65, vcc, 0, v73, vcc
	s_add_i32 s23, s22, 0x80
	global_store_dwordx4 v[64:65], v[68:71], off nt
	v_or_b32_e32 v64, s23, v150
	v_ashrrev_i32_e32 v65, 31, v64
	v_lshlrev_b64 v[66:67], 11, v[64:65]
	v_lshl_add_u64 v[66:67], s[30:31], 0, v[66:67]
	v_lshl_add_u64 v[70:71], v[66:67], 0, v[112:113]
	s_waitcnt vmcnt(18)
	v_mov_b32_e32 v66, v204
	v_mov_b32_e32 v67, v205
	v_mov_b32_e32 v68, v206
	v_mov_b32_e32 v69, v207
	v_mov_b32_e32 v70, v208
	v_mov_b32_e32 v71, v209
	v_mov_b32_e32 v72, v210
	v_mov_b32_e32 v73, v211
	v_lshlrev_b32_e32 v74, 16, v66
	v_and_b32_e32 v75, 0xffff0000, v66
	v_lshlrev_b32_e32 v66, 16, v67
	v_and_b32_e32 v67, 0xffff0000, v67
	v_lshlrev_b32_e32 v76, 16, v68
	v_and_b32_e32 v77, 0xffff0000, v68
	v_lshlrev_b32_e32 v68, 16, v69
	v_and_b32_e32 v69, 0xffff0000, v69
	v_lshlrev_b32_e32 v78, 16, v70
	v_and_b32_e32 v79, 0xffff0000, v70
	v_lshlrev_b32_e32 v70, 16, v71
	v_and_b32_e32 v71, 0xffff0000, v71
	v_lshlrev_b32_e32 v80, 16, v72
	v_and_b32_e32 v81, 0xffff0000, v72
	v_lshlrev_b32_e32 v72, 16, v73
	v_and_b32_e32 v73, 0xffff0000, v73
	v_pk_add_f32 v[62:63], v[62:63], v[66:67]
	v_pk_add_f32 v[60:61], v[60:61], v[74:75]
	v_pk_add_f32 v[58:59], v[58:59], v[68:69]
	v_pk_add_f32 v[56:57], v[56:57], v[76:77]
	v_pk_add_f32 v[54:55], v[54:55], v[70:71]
	v_pk_add_f32 v[52:53], v[52:53], v[78:79]
	v_pk_add_f32 v[50:51], v[50:51], v[72:73]
	v_pk_add_f32 v[48:49], v[48:49], v[80:81]
	v_mul_f32_e32 v66, v61, v61
	v_mul_f32_e32 v67, v63, v63
	v_mul_f32_e32 v68, v57, v57
	v_mul_f32_e32 v69, v59, v59
	v_mul_f32_e32 v70, v53, v53
	v_mul_f32_e32 v71, v55, v55
	v_mul_f32_e32 v72, v49, v49
	v_mul_f32_e32 v73, v51, v51
	v_fmac_f32_e32 v66, v60, v60
	v_fmac_f32_e32 v67, v62, v62
	v_fmac_f32_e32 v68, v56, v56
	v_fmac_f32_e32 v69, v58, v58
	v_fmac_f32_e32 v70, v52, v52
	v_fmac_f32_e32 v71, v54, v54
	v_fmac_f32_e32 v72, v48, v48
	v_fmac_f32_e32 v73, v50, v50
	v_add_f32_e32 v66, v66, v67
	v_add_f32_e32 v67, v68, v69
	v_add_f32_e32 v68, v70, v71
	v_add_f32_e32 v69, v72, v73
	v_add_f32_e32 v66, v66, v67
	v_add_f32_e32 v67, v68, v69
	v_add_f32_e32 v66, v66, v67
	ds_bpermute_b32 v67, v161, v66
	s_waitcnt lgkmcnt(0)
	v_add_f32_e32 v66, v66, v67
	ds_bpermute_b32 v67, v162, v66
	s_and_saveexec_b64 s[20:21], s[2:3]
	s_cbranch_execz .LBB0_770
	v_lshlrev_b64 v[64:65], 6, v[64:65]
	v_lshl_add_u64 v[64:65], s[82:83], 0, v[64:65]
	v_lshl_add_u64 v[64:65], s[0:1], 2, v[64:65]
	s_lshl_b32 s14, s48, 2
	v_lshl_add_u64 v[64:65], v[64:65], 0, s[14:15]
	s_waitcnt lgkmcnt(0)
	v_add_f32_e32 v66, v66, v67
	global_store_dword v[64:65], v66, off
; __device__ __forceinline__ unsigned swap8(unsigned v) { return (unsigned)__builtin_amdgcn_update_dpp(0, (int)v, 0x128  , 0xF, 0xF, false); }
; __device__ __forceinline__ void wide_store(bf16_t* O, int ldc, int rowg  , int col0  , int fr, u32x4 w0, u32x4 w1) {
;     const bool lo = fr < 8;
;     u32x4 snd = lo ? w1 : w0, rcv;
;     rcv.x = swap8(snd.x); rcv.y = swap8(snd.y); rcv.z = swap8(snd.z); rcv.w = swap8(snd.w);
;     const u32x4 first = lo ? w0 : rcv, second = lo ? rcv : w1;
;     bf16_t* p = O + (size_t)(rowg + (fr & 7)) * ldc + col0 + (lo ? 0 : 32);
;     __builtin_nontemporal_store(first, (u32x4*)p); __builtin_nontemporal_store(second, (u32x4*)(p + (size_t)8 * ldc));
;     __device__ __forceinline__ void operator()(const f32x4 (&acc)[2][2][4][2], const Unit& u, int wr, int wc, int fr, int fq) const {
;     ...
;             for (int m = 0; m < 4; ++m) { const int rowg = u.pm * BM + ai * HALF + wr * 64 + m * 16, row = rowg + fr; const size_t off = (size_t)row * 1024 + col0;
;                 u32x4 w[2]; float ss = 0.f;
; #pragma unroll
;                 for (int bj = 0; bj < 2; ++bj) { f32x4 b0, b1;
;                     if (BASE_F32) { const float* bp = (const float*)base + off + 32 * bj; b0 = *(const f32x4*)bp; b1 = *(const f32x4*)(bp + 4); }
;                     else { const u32x4 bb = *(const u32x4*)((const bf16_t*)base + off + 32 * bj);
;                         b0 = (f32x4){__uint_as_float(bb.x << 16), __uint_as_float(bb.x & 0xffff0000u), __uint_as_float(bb.y << 16), __uint_as_float(bb.y & 0xffff0000u)};
;                         b1 = (f32x4){__uint_as_float(bb.z << 16), __uint_as_float(bb.z & 0xffff0000u), __uint_as_float(bb.w << 16), __uint_as_float(bb.w & 0xffff0000u)}; }
;                     const f32x4 o0 = b0 + acc[ai][bj][m][0], o1 = b1 + acc[ai][bj][m][1];
;                     ss += ((o0[0] * o0[0] + o0[1] * o0[1]) + (o0[2] * o0[2] + o0[3] * o0[3])) + ((o1[0] * o1[0] + o1[1] * o1[1]) + (o1[2] * o1[2] + o1[3] * o1[3]));
;                     w[bj].x = cvt_pk_bf16(o0[0], o0[1]); w[bj].y = cvt_pk_bf16(o0[2], o0[3]); w[bj].z = cvt_pk_bf16(o1[0], o1[1]); w[bj].w = cvt_pk_bf16(o1[2], o1[3]); }
;                 ss += __shfl_xor(ss, 16); ss += __shfl_xor(ss, 32); if (fq == 0) slots[(size_t)row * 16 + u.pn * 4 + wc] = ss;
;                 wide_store(xb, 1024, rowg, col0, fr, w[0], w[1]);
.LBB0_770:
	s_or_b64 exec, exec, s[20:21]
	v_cvt_pk_bf16_f32 v56, v56, v57
	v_cvt_pk_bf16_f32 v52, v52, v53
	v_cvt_pk_bf16_f32 v53, v54, v55
	v_cvt_pk_bf16_f32 v54, v48, v49
	v_cvt_pk_bf16_f32 v60, v60, v61
	v_cvt_pk_bf16_f32 v61, v62, v63
	v_cvt_pk_bf16_f32 v57, v58, v59
	v_cvt_pk_bf16_f32 v55, v50, v51
	v_cndmask_b32_e64 v49, v56, v54, s[4:5]
	v_mov_b32_e32 v62, v137
	v_cndmask_b32_e64 v48, v57, v55, s[4:5]
	v_cndmask_b32_e64 v50, v61, v53, s[4:5]
	v_mov_b32_e32 v59, v137
	v_mov_b32_dpp v62, v49 row_ror:8 row_mask:0xf bank_mask:0xf
	v_mov_b32_e32 v63, v137
	v_cndmask_b32_e64 v51, v60, v52, s[4:5]
	v_mov_b32_e32 v58, v137
	v_mov_b32_dpp v59, v50 row_ror:8 row_mask:0xf bank_mask:0xf
	v_mov_b32_dpp v63, v48 row_ror:8 row_mask:0xf bank_mask:0xf
	v_cndmask_b32_e64 v50, v62, v56, s[4:5]
	v_or_b32_e32 v56, s23, v156
	v_mov_b32_dpp v58, v51 row_ror:8 row_mask:0xf bank_mask:0xf
	v_cndmask_b32_e64 v51, v63, v57, s[4:5]
	v_ashrrev_i32_e32 v57, 31, v56
	v_lshlrev_b64 v[56:57], 11, v[56:57]
	v_lshl_add_u64 v[56:57], s[30:31], 0, v[56:57]
	v_lshl_add_u64 v[56:57], v[56:57], 0, v[112:113]
	v_cndmask_b32_e64 v49, v59, v61, s[4:5]
	v_cndmask_b32_e64 v48, v58, v60, s[4:5]
	v_lshl_add_u64 v[56:57], v[56:57], 0, v[136:137]
	global_store_dwordx4 v[56:57], v[48:51], off nt
	v_cndmask_b32_e64 v55, v55, v63, s[4:5]
	v_cndmask_b32_e64 v54, v54, v62, s[4:5]
	v_add_co_u32_e32 v48, vcc, s47, v56
	v_cndmask_b32_e64 v53, v53, v59, s[4:5]
	v_cndmask_b32_e64 v52, v52, v58, s[4:5]
	v_addc_co_u32_e32 v49, vcc, 0, v57, vcc
	s_add_i32 s23, s22, 0x90
	global_store_dwordx4 v[48:49], v[52:55], off nt
	v_or_b32_e32 v48, s23, v150
	v_ashrrev_i32_e32 v49, 31, v48
	v_lshlrev_b64 v[50:51], 11, v[48:49]
	v_lshl_add_u64 v[50:51], s[30:31], 0, v[50:51]
	v_lshl_add_u64 v[54:55], v[50:51], 0, v[112:113]
	s_waitcnt vmcnt(19)
	v_mov_b32_e32 v50, v212
	v_mov_b32_e32 v51, v213
	v_mov_b32_e32 v52, v214
	v_mov_b32_e32 v53, v215
	v_mov_b32_e32 v54, v216
	v_mov_b32_e32 v55, v217
	v_mov_b32_e32 v56, v218
	v_mov_b32_e32 v57, v219
	v_lshlrev_b32_e32 v58, 16, v50
	v_and_b32_e32 v59, 0xffff0000, v50
	v_lshlrev_b32_e32 v50, 16, v51
	v_and_b32_e32 v51, 0xffff0000, v51
	v_lshlrev_b32_e32 v60, 16, v52
	v_and_b32_e32 v61, 0xffff0000, v52
	v_lshlrev_b32_e32 v52, 16, v53
	v_and_b32_e32 v53, 0xffff0000, v53
	v_lshlrev_b32_e32 v62, 16, v54
	v_and_b32_e32 v63, 0xffff0000, v54
	v_lshlrev_b32_e32 v54, 16, v55
	v_and_b32_e32 v55, 0xffff0000, v55
	v_lshlrev_b32_e32 v64, 16, v56
	v_and_b32_e32 v65, 0xffff0000, v56
	v_lshlrev_b32_e32 v56, 16, v57
	v_and_b32_e32 v57, 0xffff0000, v57
	v_pk_add_f32 v[46:47], v[46:47], v[50:51]
	v_pk_add_f32 v[44:45], v[44:45], v[58:59]
	v_pk_add_f32 v[42:43], v[42:43], v[52:53]
	v_pk_add_f32 v[40:41], v[40:41], v[60:61]
	v_pk_add_f32 v[38:39], v[38:39], v[54:55]
	v_pk_add_f32 v[36:37], v[36:37], v[62:63]
	v_pk_add_f32 v[34:35], v[34:35], v[56:57]
	v_pk_add_f32 v[32:33], v[32:33], v[64:65]
	v_mul_f32_e32 v50, v45, v45
	v_mul_f32_e32 v51, v47, v47
	v_mul_f32_e32 v52, v41, v41
	v_mul_f32_e32 v53, v43, v43
	v_mul_f32_e32 v54, v37, v37
	v_mul_f32_e32 v55, v39, v39
	v_mul_f32_e32 v56, v33, v33
	v_mul_f32_e32 v57, v35, v35
	v_fmac_f32_e32 v50, v44, v44
	v_fmac_f32_e32 v51, v46, v46
	v_fmac_f32_e32 v52, v40, v40
	v_fmac_f32_e32 v53, v42, v42
	v_fmac_f32_e32 v54, v36, v36
	v_fmac_f32_e32 v55, v38, v38
	v_fmac_f32_e32 v56, v32, v32
	v_fmac_f32_e32 v57, v34, v34
	v_add_f32_e32 v50, v50, v51
	v_add_f32_e32 v51, v52, v53
	v_add_f32_e32 v52, v54, v55
	v_add_f32_e32 v53, v56, v57
	v_add_f32_e32 v50, v50, v51
	v_add_f32_e32 v51, v52, v53
	v_add_f32_e32 v50, v50, v51
	ds_bpermute_b32 v51, v161, v50
	s_waitcnt lgkmcnt(0)
	v_add_f32_e32 v50, v50, v51
	ds_bpermute_b32 v51, v162, v50
	s_and_saveexec_b64 s[20:21], s[2:3]
	s_cbranch_execz .LBB0_772
	v_lshlrev_b64 v[48:49], 6, v[48:49]
	v_lshl_add_u64 v[48:49], s[82:83], 0, v[48:49]
	v_lshl_add_u64 v[48:49], s[0:1], 2, v[48:49]
	s_lshl_b32 s14, s48, 2
	v_lshl_add_u64 v[48:49], v[48:49], 0, s[14:15]
	s_waitcnt lgkmcnt(0)
	v_add_f32_e32 v50, v50, v51
	global_store_dword v[48:49], v50, off
.LBB0_772:
	s_or_b64 exec, exec, s[20:21]
	v_cvt_pk_bf16_f32 v40, v40, v41
	v_cvt_pk_bf16_f32 v36, v36, v37
	v_cvt_pk_bf16_f32 v37, v38, v39
	v_cvt_pk_bf16_f32 v38, v32, v33
	v_cvt_pk_bf16_f32 v44, v44, v45
	v_cvt_pk_bf16_f32 v45, v46, v47
	v_cvt_pk_bf16_f32 v41, v42, v43
	v_cvt_pk_bf16_f32 v39, v34, v35
	v_cndmask_b32_e64 v33, v40, v38, s[4:5]
	v_mov_b32_e32 v46, v137
	v_cndmask_b32_e64 v32, v41, v39, s[4:5]
	v_cndmask_b32_e64 v34, v45, v37, s[4:5]
	v_mov_b32_e32 v43, v137
	v_mov_b32_dpp v46, v33 row_ror:8 row_mask:0xf bank_mask:0xf
	v_mov_b32_e32 v47, v137
	v_cndmask_b32_e64 v35, v44, v36, s[4:5]
	v_mov_b32_e32 v42, v137
	v_mov_b32_dpp v43, v34 row_ror:8 row_mask:0xf bank_mask:0xf
	v_mov_b32_dpp v47, v32 row_ror:8 row_mask:0xf bank_mask:0xf
	v_cndmask_b32_e64 v34, v46, v40, s[4:5]
	v_or_b32_e32 v40, s23, v156
	v_mov_b32_dpp v42, v35 row_ror:8 row_mask:0xf bank_mask:0xf
	v_cndmask_b32_e64 v35, v47, v41, s[4:5]
	v_ashrrev_i32_e32 v41, 31, v40
	v_lshlrev_b64 v[40:41], 11, v[40:41]
	v_lshl_add_u64 v[40:41], s[30:31], 0, v[40:41]
	v_lshl_add_u64 v[40:41], v[40:41], 0, v[112:113]
	v_cndmask_b32_e64 v33, v43, v45, s[4:5]
	v_cndmask_b32_e64 v32, v42, v44, s[4:5]
	v_lshl_add_u64 v[40:41], v[40:41], 0, v[136:137]
	global_store_dwordx4 v[40:41], v[32:35], off nt
	v_cndmask_b32_e64 v39, v39, v47, s[4:5]
	v_cndmask_b32_e64 v38, v38, v46, s[4:5]
	v_add_co_u32_e32 v32, vcc, s47, v40
	v_cndmask_b32_e64 v37, v37, v43, s[4:5]
	v_cndmask_b32_e64 v36, v36, v42, s[4:5]
	v_addc_co_u32_e32 v33, vcc, 0, v41, vcc
	s_add_i32 s23, s22, 0xa0
	global_store_dwordx4 v[32:33], v[36:39], off nt
	v_or_b32_e32 v32, s23, v150
	v_ashrrev_i32_e32 v33, 31, v32
	v_lshlrev_b64 v[34:35], 11, v[32:33]
	v_lshl_add_u64 v[34:35], s[30:31], 0, v[34:35]
	v_lshl_add_u64 v[38:39], v[34:35], 0, v[112:113]
	s_waitcnt vmcnt(20)
; __device__ __forceinline__ unsigned swap8(unsigned v) { return (unsigned)__builtin_amdgcn_update_dpp(0, (int)v, 0x128  , 0xF, 0xF, false); }
; __device__ __forceinline__ void wide_store(bf16_t* O, int ldc, int rowg  , int col0  , int fr, u32x4 w0, u32x4 w1) {
;     const bool lo = fr < 8;
;     u32x4 snd = lo ? w1 : w0, rcv;
;     rcv.x = swap8(snd.x); rcv.y = swap8(snd.y); rcv.z = swap8(snd.z); rcv.w = swap8(snd.w);
;     const u32x4 first = lo ? w0 : rcv, second = lo ? rcv : w1;
;     bf16_t* p = O + (size_t)(rowg + (fr & 7)) * ldc + col0 + (lo ? 0 : 32);
;     __builtin_nontemporal_store(first, (u32x4*)p); __builtin_nontemporal_store(second, (u32x4*)(p + (size_t)8 * ldc));
;     __device__ __forceinline__ void operator()(const f32x4 (&acc)[2][2][4][2], const Unit& u, int wr, int wc, int fr, int fq) const {
;     ...
;             for (int m = 0; m < 4; ++m) { const int rowg = u.pm * BM + ai * HALF + wr * 64 + m * 16, row = rowg + fr; const size_t off = (size_t)row * 1024 + col0;
;                 u32x4 w[2]; float ss = 0.f;
; #pragma unroll
;                 for (int bj = 0; bj < 2; ++bj) { f32x4 b0, b1;
;                     if (BASE_F32) { const float* bp = (const float*)base + off + 32 * bj; b0 = *(const f32x4*)bp; b1 = *(const f32x4*)(bp + 4); }
;                     else { const u32x4 bb = *(const u32x4*)((const bf16_t*)base + off + 32 * bj);
;                         b0 = (f32x4){__uint_as_float(bb.x << 16), __uint_as_float(bb.x & 0xffff0000u), __uint_as_float(bb.y << 16), __uint_as_float(bb.y & 0xffff0000u)};
;                         b1 = (f32x4){__uint_as_float(bb.z << 16), __uint_as_float(bb.z & 0xffff0000u), __uint_as_float(bb.w << 16), __uint_as_float(bb.w & 0xffff0000u)}; }
;                     const f32x4 o0 = b0 + acc[ai][bj][m][0], o1 = b1 + acc[ai][bj][m][1];
;                     ss += ((o0[0] * o0[0] + o0[1] * o0[1]) + (o0[2] * o0[2] + o0[3] * o0[3])) + ((o1[0] * o1[0] + o1[1] * o1[1]) + (o1[2] * o1[2] + o1[3] * o1[3]));
;                     w[bj].x = cvt_pk_bf16(o0[0], o0[1]); w[bj].y = cvt_pk_bf16(o0[2], o0[3]); w[bj].z = cvt_pk_bf16(o1[0], o1[1]); w[bj].w = cvt_pk_bf16(o1[2], o1[3]); }
;                 ss += __shfl_xor(ss, 16); ss += __shfl_xor(ss, 32); if (fq == 0) slots[(size_t)row * 16 + u.pn * 4 + wc] = ss;
;                 wide_store(xb, 1024, rowg, col0, fr, w[0], w[1]);
	v_mov_b32_e32 v34, v220
	v_mov_b32_e32 v35, v221
	v_mov_b32_e32 v36, v222
	v_mov_b32_e32 v37, v223
	v_mov_b32_e32 v38, v224
	v_mov_b32_e32 v39, v225
	v_mov_b32_e32 v40, v226
	v_mov_b32_e32 v41, v227
	v_lshlrev_b32_e32 v42, 16, v34
	v_and_b32_e32 v43, 0xffff0000, v34
	v_lshlrev_b32_e32 v34, 16, v35
	v_and_b32_e32 v35, 0xffff0000, v35
	v_lshlrev_b32_e32 v44, 16, v36
	v_and_b32_e32 v45, 0xffff0000, v36
	v_lshlrev_b32_e32 v36, 16, v37
	v_and_b32_e32 v37, 0xffff0000, v37
	v_lshlrev_b32_e32 v46, 16, v38
	v_and_b32_e32 v47, 0xffff0000, v38
	v_lshlrev_b32_e32 v38, 16, v39
	v_and_b32_e32 v39, 0xffff0000, v39
	v_lshlrev_b32_e32 v48, 16, v40
	v_and_b32_e32 v49, 0xffff0000, v40
	v_lshlrev_b32_e32 v40, 16, v41
	v_and_b32_e32 v41, 0xffff0000, v41
	v_pk_add_f32 v[30:31], v[30:31], v[34:35]
	v_pk_add_f32 v[28:29], v[28:29], v[42:43]
	v_pk_add_f32 v[26:27], v[26:27], v[36:37]
	v_pk_add_f32 v[24:25], v[24:25], v[44:45]
	v_pk_add_f32 v[22:23], v[22:23], v[38:39]
	v_pk_add_f32 v[20:21], v[20:21], v[46:47]
	v_pk_add_f32 v[18:19], v[18:19], v[40:41]
	v_pk_add_f32 v[16:17], v[16:17], v[48:49]
	v_mul_f32_e32 v34, v29, v29
	v_mul_f32_e32 v35, v31, v31
	v_mul_f32_e32 v36, v25, v25
	v_mul_f32_e32 v37, v27, v27
	v_mul_f32_e32 v38, v21, v21
	v_mul_f32_e32 v39, v23, v23
	v_mul_f32_e32 v40, v17, v17
	v_mul_f32_e32 v41, v19, v19
	v_fmac_f32_e32 v34, v28, v28
	v_fmac_f32_e32 v35, v30, v30
	v_fmac_f32_e32 v36, v24, v24
	v_fmac_f32_e32 v37, v26, v26
	v_fmac_f32_e32 v38, v20, v20
	v_fmac_f32_e32 v39, v22, v22
	v_fmac_f32_e32 v40, v16, v16
	v_fmac_f32_e32 v41, v18, v18
	v_add_f32_e32 v34, v34, v35
	v_add_f32_e32 v35, v36, v37
	v_add_f32_e32 v36, v38, v39
	v_add_f32_e32 v37, v40, v41
	v_add_f32_e32 v34, v34, v35
	v_add_f32_e32 v35, v36, v37
	v_add_f32_e32 v34, v34, v35
	ds_bpermute_b32 v35, v161, v34
	s_waitcnt lgkmcnt(0)
	v_add_f32_e32 v34, v34, v35
	ds_bpermute_b32 v35, v162, v34
	s_and_saveexec_b64 s[20:21], s[2:3]
	s_cbranch_execz .LBB0_774
	v_lshlrev_b64 v[32:33], 6, v[32:33]
	v_lshl_add_u64 v[32:33], s[82:83], 0, v[32:33]
	v_lshl_add_u64 v[32:33], s[0:1], 2, v[32:33]
	s_lshl_b32 s14, s48, 2
	v_lshl_add_u64 v[32:33], v[32:33], 0, s[14:15]
	s_waitcnt lgkmcnt(0)
	v_add_f32_e32 v34, v34, v35
	global_store_dword v[32:33], v34, off
.LBB0_774:
	s_or_b64 exec, exec, s[20:21]
	v_cvt_pk_bf16_f32 v24, v24, v25
	v_cvt_pk_bf16_f32 v20, v20, v21
	v_cvt_pk_bf16_f32 v21, v22, v23
	v_cvt_pk_bf16_f32 v22, v16, v17
	v_cvt_pk_bf16_f32 v28, v28, v29
	v_cvt_pk_bf16_f32 v29, v30, v31
	v_cvt_pk_bf16_f32 v25, v26, v27
	v_cvt_pk_bf16_f32 v23, v18, v19
	v_cndmask_b32_e64 v17, v24, v22, s[4:5]
	v_mov_b32_e32 v30, v137
	v_cndmask_b32_e64 v16, v25, v23, s[4:5]
	v_cndmask_b32_e64 v18, v29, v21, s[4:5]
	v_mov_b32_e32 v27, v137
	v_mov_b32_dpp v30, v17 row_ror:8 row_mask:0xf bank_mask:0xf
	v_mov_b32_e32 v31, v137
	v_cndmask_b32_e64 v19, v28, v20, s[4:5]
	v_mov_b32_e32 v26, v137
	v_mov_b32_dpp v27, v18 row_ror:8 row_mask:0xf bank_mask:0xf
	v_mov_b32_dpp v31, v16 row_ror:8 row_mask:0xf bank_mask:0xf
	v_cndmask_b32_e64 v18, v30, v24, s[4:5]
	v_or_b32_e32 v24, s23, v156
	v_mov_b32_dpp v26, v19 row_ror:8 row_mask:0xf bank_mask:0xf
	v_cndmask_b32_e64 v19, v31, v25, s[4:5]
	v_ashrrev_i32_e32 v25, 31, v24
	v_lshlrev_b64 v[24:25], 11, v[24:25]
	v_lshl_add_u64 v[24:25], s[30:31], 0, v[24:25]
	v_lshl_add_u64 v[24:25], v[24:25], 0, v[112:113]
	v_cndmask_b32_e64 v17, v27, v29, s[4:5]
	v_cndmask_b32_e64 v16, v26, v28, s[4:5]
	v_lshl_add_u64 v[24:25], v[24:25], 0, v[136:137]
	global_store_dwordx4 v[24:25], v[16:19], off nt
	v_cndmask_b32_e64 v23, v23, v31, s[4:5]
	v_cndmask_b32_e64 v22, v22, v30, s[4:5]
	v_add_co_u32_e32 v16, vcc, s47, v24
	v_cndmask_b32_e64 v21, v21, v27, s[4:5]
	v_cndmask_b32_e64 v20, v20, v26, s[4:5]
	v_addc_co_u32_e32 v17, vcc, 0, v25, vcc
	s_addk_i32 s22, 0xb0
	global_store_dwordx4 v[16:17], v[20:23], off nt
	v_or_b32_e32 v16, s22, v150
	v_ashrrev_i32_e32 v17, 31, v16
	v_lshlrev_b64 v[18:19], 11, v[16:17]
	v_lshl_add_u64 v[18:19], s[30:31], 0, v[18:19]
	v_lshl_add_u64 v[22:23], v[18:19], 0, v[112:113]
	s_waitcnt vmcnt(21)
	v_mov_b32_e32 v18, v228
	v_mov_b32_e32 v19, v229
	v_mov_b32_e32 v20, v230
	v_mov_b32_e32 v21, v231
	v_mov_b32_e32 v22, v232
	v_mov_b32_e32 v23, v233
	v_mov_b32_e32 v24, v234
	v_mov_b32_e32 v25, v235
	v_lshlrev_b32_e32 v26, 16, v18
	v_and_b32_e32 v27, 0xffff0000, v18
	v_lshlrev_b32_e32 v18, 16, v19
	v_and_b32_e32 v19, 0xffff0000, v19
	v_lshlrev_b32_e32 v28, 16, v20
	v_and_b32_e32 v29, 0xffff0000, v20
	v_lshlrev_b32_e32 v20, 16, v21
	v_and_b32_e32 v21, 0xffff0000, v21
	v_lshlrev_b32_e32 v30, 16, v22
	v_and_b32_e32 v31, 0xffff0000, v22
	v_lshlrev_b32_e32 v22, 16, v23
	v_and_b32_e32 v23, 0xffff0000, v23
	v_lshlrev_b32_e32 v32, 16, v24
	v_and_b32_e32 v33, 0xffff0000, v24
	v_lshlrev_b32_e32 v24, 16, v25
	v_and_b32_e32 v25, 0xffff0000, v25
	v_pk_add_f32 v[14:15], v[14:15], v[18:19]
	v_pk_add_f32 v[12:13], v[12:13], v[26:27]
	v_pk_add_f32 v[10:11], v[10:11], v[20:21]
	v_pk_add_f32 v[8:9], v[8:9], v[28:29]
	v_pk_add_f32 v[6:7], v[6:7], v[22:23]
	v_pk_add_f32 v[4:5], v[4:5], v[30:31]
	v_pk_add_f32 v[2:3], v[2:3], v[24:25]
	v_pk_add_f32 v[0:1], v[0:1], v[32:33]
	v_mul_f32_e32 v18, v13, v13
	v_mul_f32_e32 v19, v15, v15
	v_mul_f32_e32 v20, v9, v9
	v_mul_f32_e32 v21, v11, v11
	v_mul_f32_e32 v22, v5, v5
	v_mul_f32_e32 v23, v7, v7
	v_mul_f32_e32 v24, v1, v1
	v_mul_f32_e32 v25, v3, v3
	v_fmac_f32_e32 v18, v12, v12
	v_fmac_f32_e32 v19, v14, v14
	v_fmac_f32_e32 v20, v8, v8
	v_fmac_f32_e32 v21, v10, v10
	v_fmac_f32_e32 v22, v4, v4
	v_fmac_f32_e32 v23, v6, v6
	v_fmac_f32_e32 v24, v0, v0
	v_fmac_f32_e32 v25, v2, v2
	v_add_f32_e32 v18, v18, v19
	v_add_f32_e32 v19, v20, v21
	v_add_f32_e32 v20, v22, v23
	v_add_f32_e32 v21, v24, v25
	v_add_f32_e32 v18, v18, v19
	v_add_f32_e32 v19, v20, v21
	v_add_f32_e32 v18, v18, v19
	ds_bpermute_b32 v19, v161, v18
	s_waitcnt lgkmcnt(0)
	v_add_f32_e32 v18, v18, v19
	ds_bpermute_b32 v19, v162, v18
	s_and_saveexec_b64 s[20:21], s[2:3]
	s_cbranch_execz .LBB0_776
	v_lshlrev_b64 v[16:17], 6, v[16:17]
	v_lshl_add_u64 v[16:17], s[82:83], 0, v[16:17]
	v_lshl_add_u64 v[16:17], s[0:1], 2, v[16:17]
	s_lshl_b32 s14, s48, 2
	v_lshl_add_u64 v[16:17], v[16:17], 0, s[14:15]
	s_waitcnt lgkmcnt(0)
	v_add_f32_e32 v18, v18, v19
	global_store_dword v[16:17], v18, off

; #define PG8_STAGE(bufoff, gbase, voff) do { _Pragma("unroll") for (int _i = 0; _i < 2; ++_i) \
;         __builtin_amdgcn_global_load_lds((const unsigned*)((const char*)(gbase) + (voff)[_i]), (PG8_LAS unsigned*)(lds + (bufoff) + ldsw + _i * 8192), 16, 0, PG8_LOAD_AUX); } while (0)
; #define PG8_LDA(dst, b, h) do { _Pragma("unroll") for (int m = 0; m < 4; ++m) _Pragma("unroll") for (int k = 0; k < 2; ++k) dst[m][k] = *(const PG8_LAS bf16x8*)(lds + PG8_SA(b, h) + aoff + m * 2048 + k * 1024); } while (0)
; #define PG8_LDB(dst, b, h) do { _Pragma("unroll") for (int n = 0; n < 2; ++n) _Pragma("unroll") for (int k = 0; k < 2; ++k) dst[n][k] = *(const PG8_LAS bf16x8*)(lds + PG8_SB(b, h) + boff + n * 2048 + k * 1024); } while (0)
; #define PG8_MMA(ai, bj, At, Bt) do { __builtin_amdgcn_s_setprio(1); _Pragma("unroll") for (int m = 0; m < 4; ++m) _Pragma("unroll") for (int n = 0; n < 2; ++n) _Pragma("unroll") for (int k = 0; k < 2; ++k) \
;         acc[ai][bj][m][n] = __builtin_amdgcn_mfma_f32_16x16x32_bf16(Bt[n][k], At[m][k], acc[ai][bj][m][n], 0, 0, 0); __builtin_amdgcn_s_setprio(0); } while (0)
; #define PG8_WAIT_V(n) asm volatile("s_waitcnt vmcnt(" #n ")" ::: "memory")
; #define PG8_WAIT_L(n) asm volatile("s_waitcnt lgkmcnt(" #n ")" ::: "memory")
; #define PG8_BAR __builtin_amdgcn_s_barrier()
; #define PG8_SCHED __builtin_amdgcn_sched_barrier(0)
; template <class Epi, class Sched, bool ALIGN_EPI = false, bool SP2 = false>
; __device__ __forceinline__ void gemm_phase(PG8_LAS unsigned char* lds, const Gemm g, const Sched& S, const Epi& E) {
;     ...
;             PG8_LDB(B0, 0, 0); PG8_LDB(B1, 0, 1); PG8_SCHED; PG8_LDA(At, 0, 0); PG8_STAGE(PG8_SA(1, 1), a1 + hstepA, voffA);
;             PG8_WAIT_V(8); PG8_WAIT_L(0); PG8_BAR; PG8_MMA(0, 0, At, B0); PG8_MMA(0, 1, At, B1); PG8_BAR; PG8_SCHED;
;             PG8_LDA(At, 0, 1); PG8_STAGE(PG8_SB(0, 0), b2, voffB); PG8_STAGE(PG8_SB(0, 1), b2 + hstepB, voffB); PG8_STAGE(PG8_SA(0, 0), a2, voffA);
;             PG8_WAIT_V(8); PG8_WAIT_L(0); PG8_BAR; PG8_MMA(1, 0, At, B0); PG8_MMA(1, 1, At, B1); PG8_BAR; PG8_SCHED;
.LBB0_1018:
	s_add_u32 s30, s20, s26
	s_addc_u32 s31, s21, 0
	s_add_u32 s27, s30, 0x100
	s_addc_u32 s33, s31, 0
	s_and_b64 s[28:29], s[34:35], exec
	s_cselect_b32 s51, s9, s33
	s_cselect_b32 s50, s8, s27
	s_add_u32 s26, s0, s26
	s_addc_u32 s27, s1, 0
	s_add_u32 s28, s26, 0x100
	s_addc_u32 s29, s27, 0
	s_and_b64 s[26:27], s[34:35], exec
	s_cselect_b32 s53, s24, s29
	s_cselect_b32 s52, s25, s28
	s_add_u32 s56, s30, 0x40080
	ds_read_b128 v[142:145], v150
	ds_read_b128 v[156:159], v150 offset:1024
	ds_read_b128 v[160:163], v150 offset:2048
	ds_read_b128 v[164:167], v150 offset:3072
	ds_read_b128 v[168:171], v151
	ds_read_b128 v[172:175], v151 offset:1024
	ds_read_b128 v[176:179], v151 offset:2048
	ds_read_b128 v[180:183], v151 offset:3072
	s_addc_u32 s57, s31, 0
	s_add_i32 s38, s70, s58
	s_add_i32 m0, s47, 0xc000
	s_add_i32 s43, s47, 0xe000
	s_add_i32 s30, s38, 0x2000
	s_add_u32 s54, s52, 0x4000
	s_addc_u32 s55, s53, 0
	s_add_i32 s33, s71, s58
	s_add_i32 s31, s33, 0x2000
	s_add_i32 s29, 0, 0x18000
	s_add_i32 s28, 0, 0x1c000
	s_add_u32 s48, s50, 0x40000
	s_addc_u32 s49, s51, 0
	s_add_i32 s27, s29, s58
	s_add_i32 s26, s27, 0x2000
	s_add_u32 s34, s52, 0x4080
	s_addc_u32 s35, s53, 0
	s_add_i32 s41, s28, s58
	s_add_i32 s39, s41, 0x2000
	v_lshl_add_u64 v[216:217], s[56:57], 0, v[128:129]
	ds_read_b128 v[184:187], v152
	ds_read_b128 v[188:191], v152 offset:1024
	ds_read_b128 v[192:195], v152 offset:2048
	ds_read_b128 v[196:199], v152 offset:3072
	ds_read_b128 v[200:203], v152 offset:4096
	ds_read_b128 v[204:207], v152 offset:5120
	ds_read_b128 v[208:211], v152 offset:6144
	ds_read_b128 v[212:215], v152 offset:7168
	global_load_lds_dwordx4 v[216:217], off
	v_lshl_add_u64 v[216:217], s[56:57], 0, v[132:133]
	s_mov_b32 m0, s43
	s_nop 0
	global_load_lds_dwordx4 v[216:217], off
	s_waitcnt vmcnt(8)
	s_waitcnt lgkmcnt(0)
	s_barrier
	s_setprio 1
	s_waitcnt lgkmcnt(0)
	v_mfma_f32_16x16x32_bf16 v[124:127], v[142:145], v[184:187], v[124:127]
	v_mfma_f32_16x16x32_bf16 v[120:123], v[160:163], v[184:187], v[120:123]
	v_mfma_f32_16x16x32_bf16 v[108:111], v[142:145], v[192:195], v[108:111]
	v_mfma_f32_16x16x32_bf16 v[104:107], v[160:163], v[192:195], v[104:107]
	v_mfma_f32_16x16x32_bf16 v[92:95], v[142:145], v[200:203], v[92:95]
	v_mfma_f32_16x16x32_bf16 v[88:91], v[160:163], v[200:203], v[88:91]
	v_mfma_f32_16x16x32_bf16 v[76:79], v[142:145], v[208:211], v[76:79]
	v_mfma_f32_16x16x32_bf16 v[72:75], v[160:163], v[208:211], v[72:75]
	v_mfma_f32_16x16x32_bf16 v[124:127], v[156:159], v[188:191], v[124:127]
	v_mfma_f32_16x16x32_bf16 v[120:123], v[164:167], v[188:191], v[120:123]
	v_mfma_f32_16x16x32_bf16 v[108:111], v[156:159], v[196:199], v[108:111]
	v_mfma_f32_16x16x32_bf16 v[104:107], v[164:167], v[196:199], v[104:107]
	v_mfma_f32_16x16x32_bf16 v[92:95], v[156:159], v[204:207], v[92:95]
	v_mfma_f32_16x16x32_bf16 v[88:91], v[164:167], v[204:207], v[88:91]
	v_mfma_f32_16x16x32_bf16 v[76:79], v[156:159], v[212:215], v[76:79]
	v_mfma_f32_16x16x32_bf16 v[72:75], v[164:167], v[212:215], v[72:75]
	s_setprio 0
	s_setprio 1
	v_mfma_f32_16x16x32_bf16 v[116:119], v[168:171], v[184:187], v[116:119]
	v_mfma_f32_16x16x32_bf16 v[112:115], v[176:179], v[184:187], v[112:115]
	v_mfma_f32_16x16x32_bf16 v[100:103], v[168:171], v[192:195], v[100:103]
	v_mfma_f32_16x16x32_bf16 v[96:99], v[176:179], v[192:195], v[96:99]
	v_mfma_f32_16x16x32_bf16 v[84:87], v[168:171], v[200:203], v[84:87]
	v_mfma_f32_16x16x32_bf16 v[80:83], v[176:179], v[200:203], v[80:83]
	v_mfma_f32_16x16x32_bf16 v[68:71], v[168:171], v[208:211], v[68:71]
	v_mfma_f32_16x16x32_bf16 v[64:67], v[176:179], v[208:211], v[64:67]
	v_mfma_f32_16x16x32_bf16 v[116:119], v[172:175], v[188:191], v[116:119]
	v_mfma_f32_16x16x32_bf16 v[112:115], v[180:183], v[188:191], v[112:115]
	v_mfma_f32_16x16x32_bf16 v[100:103], v[172:175], v[196:199], v[100:103]
	v_mfma_f32_16x16x32_bf16 v[96:99], v[180:183], v[196:199], v[96:99]
	v_mfma_f32_16x16x32_bf16 v[84:87], v[172:175], v[204:207], v[84:87]
	v_mfma_f32_16x16x32_bf16 v[80:83], v[180:183], v[204:207], v[80:83]
	v_mfma_f32_16x16x32_bf16 v[68:71], v[172:175], v[212:215], v[68:71]
	v_mfma_f32_16x16x32_bf16 v[64:67], v[180:183], v[212:215], v[64:67]
	s_setprio 0
	s_barrier
	s_mov_b32 m0, s38
	v_lshl_add_u64 v[216:217], s[52:53], 0, v[130:131]
	ds_read_b128 v[184:187], v152 offset:16384
	ds_read_b128 v[188:191], v152 offset:17408
	ds_read_b128 v[192:195], v152 offset:18432
	ds_read_b128 v[196:199], v152 offset:19456
	ds_read_b128 v[200:203], v152 offset:20480
	ds_read_b128 v[204:207], v152 offset:21504
	ds_read_b128 v[208:211], v152 offset:22528
	ds_read_b128 v[212:215], v152 offset:23552
	global_load_lds_dwordx4 v[216:217], off
	v_lshl_add_u64 v[218:219], s[52:53], 0, v[134:135]
	s_mov_b32 m0, s30
	v_lshl_add_u64 v[220:221], s[54:55], 0, v[130:131]
	global_load_lds_dwordx4 v[218:219], off
	s_mov_b32 m0, s33
	v_lshl_add_u64 v[222:223], s[50:51], 0, v[132:133]
	global_load_lds_dwordx4 v[220:221], off
	v_lshl_add_u64 v[220:221], s[54:55], 0, v[134:135]
	s_mov_b32 m0, s31
	s_nop 0
	global_load_lds_dwordx4 v[220:221], off
	v_lshl_add_u64 v[220:221], s[50:51], 0, v[128:129]
	s_mov_b32 m0, s47
	s_nop 0
	global_load_lds_dwordx4 v[220:221], off
	s_mov_b32 m0, s59
	s_nop 0
	global_load_lds_dwordx4 v[222:223], off
	s_waitcnt vmcnt(8)
	s_waitcnt lgkmcnt(0)
	s_barrier
; #define PG8_STAGE(bufoff, gbase, voff) do { _Pragma("unroll") for (int _i = 0; _i < 2; ++_i) \
;         __builtin_amdgcn_global_load_lds((const unsigned*)((const char*)(gbase) + (voff)[_i]), (PG8_LAS unsigned*)(lds + (bufoff) + ldsw + _i * 8192), 16, 0, PG8_LOAD_AUX); } while (0)
; #define PG8_LDA(dst, b, h) do { _Pragma("unroll") for (int m = 0; m < 4; ++m) _Pragma("unroll") for (int k = 0; k < 2; ++k) dst[m][k] = *(const PG8_LAS bf16x8*)(lds + PG8_SA(b, h) + aoff + m * 2048 + k * 1024); } while (0)
; #define PG8_LDB(dst, b, h) do { _Pragma("unroll") for (int n = 0; n < 2; ++n) _Pragma("unroll") for (int k = 0; k < 2; ++k) dst[n][k] = *(const PG8_LAS bf16x8*)(lds + PG8_SB(b, h) + boff + n * 2048 + k * 1024); } while (0)
; #define PG8_MMA(ai, bj, At, Bt) do { __builtin_amdgcn_s_setprio(1); _Pragma("unroll") for (int m = 0; m < 4; ++m) _Pragma("unroll") for (int n = 0; n < 2; ++n) _Pragma("unroll") for (int k = 0; k < 2; ++k) \
;         acc[ai][bj][m][n] = __builtin_amdgcn_mfma_f32_16x16x32_bf16(Bt[n][k], At[m][k], acc[ai][bj][m][n], 0, 0, 0); __builtin_amdgcn_s_setprio(0); } while (0)
; #define PG8_WAIT_V(n) asm volatile("s_waitcnt vmcnt(" #n ")" ::: "memory")
; #define PG8_WAIT_L(n) asm volatile("s_waitcnt lgkmcnt(" #n ")" ::: "memory")
; #define PG8_BAR __builtin_amdgcn_s_barrier()
; #define PG8_SCHED __builtin_amdgcn_sched_barrier(0)
; template <class Epi, class Sched, bool ALIGN_EPI = false, bool SP2 = false>
; __device__ __forceinline__ void gemm_phase(PG8_LAS unsigned char* lds, const Gemm g, const Sched& S, const Epi& E) {
;     ...
;             PG8_WAIT_V(8); PG8_WAIT_L(0); PG8_BAR; PG8_MMA(1, 0, At, B0); PG8_MMA(1, 1, At, B1); PG8_BAR; PG8_SCHED;
;             PG8_LDB(B0, 1, 0); PG8_LDB(B1, 1, 1); PG8_SCHED; PG8_LDA(At, 1, 0); PG8_STAGE(PG8_SA(0, 1), a2 + hstepA, voffA);
;             PG8_WAIT_V(8); PG8_WAIT_L(0); PG8_BAR; PG8_MMA(0, 0, At, B0); PG8_MMA(0, 1, At, B1); PG8_BAR; PG8_SCHED;
;             PG8_LDA(At, 1, 1); PG8_STAGE(PG8_SB(1, 0), b3, voffB); PG8_STAGE(PG8_SB(1, 1), b3 + hstepB, voffB); PG8_STAGE(PG8_SA(1, 0), a3, voffA);
;             PG8_WAIT_V(8); PG8_WAIT_L(0); PG8_BAR; PG8_MMA(1, 0, At, B0); PG8_MMA(1, 1, At, B1); PG8_BAR; PG8_SCHED;
	s_setprio 1
	s_waitcnt lgkmcnt(0)
	v_mfma_f32_16x16x32_bf16 v[60:63], v[142:145], v[184:187], v[60:63]
	v_mfma_f32_16x16x32_bf16 v[56:59], v[160:163], v[184:187], v[56:59]
	v_mfma_f32_16x16x32_bf16 v[44:47], v[142:145], v[192:195], v[44:47]
	v_mfma_f32_16x16x32_bf16 v[40:43], v[160:163], v[192:195], v[40:43]
	v_mfma_f32_16x16x32_bf16 v[28:31], v[142:145], v[200:203], v[28:31]
	v_mfma_f32_16x16x32_bf16 v[24:27], v[160:163], v[200:203], v[24:27]
	v_mfma_f32_16x16x32_bf16 v[12:15], v[142:145], v[208:211], v[12:15]
	v_mfma_f32_16x16x32_bf16 v[8:11], v[160:163], v[208:211], v[8:11]
	v_mfma_f32_16x16x32_bf16 v[60:63], v[156:159], v[188:191], v[60:63]
	v_mfma_f32_16x16x32_bf16 v[56:59], v[164:167], v[188:191], v[56:59]
	v_mfma_f32_16x16x32_bf16 v[44:47], v[156:159], v[196:199], v[44:47]
	v_mfma_f32_16x16x32_bf16 v[40:43], v[164:167], v[196:199], v[40:43]
	v_mfma_f32_16x16x32_bf16 v[28:31], v[156:159], v[204:207], v[28:31]
	v_mfma_f32_16x16x32_bf16 v[24:27], v[164:167], v[204:207], v[24:27]
	v_mfma_f32_16x16x32_bf16 v[12:15], v[156:159], v[212:215], v[12:15]
	v_mfma_f32_16x16x32_bf16 v[8:11], v[164:167], v[212:215], v[8:11]
	s_setprio 0
	s_setprio 1
	v_mfma_f32_16x16x32_bf16 v[52:55], v[168:171], v[184:187], v[52:55]
	v_mfma_f32_16x16x32_bf16 v[48:51], v[176:179], v[184:187], v[48:51]
	v_mfma_f32_16x16x32_bf16 v[36:39], v[168:171], v[192:195], v[36:39]
	v_mfma_f32_16x16x32_bf16 v[32:35], v[176:179], v[192:195], v[32:35]
	v_mfma_f32_16x16x32_bf16 v[20:23], v[168:171], v[200:203], v[20:23]
	v_mfma_f32_16x16x32_bf16 v[16:19], v[176:179], v[200:203], v[16:19]
	v_mfma_f32_16x16x32_bf16 v[4:7], v[168:171], v[208:211], v[4:7]
	v_mfma_f32_16x16x32_bf16 v[0:3], v[176:179], v[208:211], v[0:3]
	v_mfma_f32_16x16x32_bf16 v[52:55], v[172:175], v[188:191], v[52:55]
	v_mfma_f32_16x16x32_bf16 v[48:51], v[180:183], v[188:191], v[48:51]
	v_mfma_f32_16x16x32_bf16 v[36:39], v[172:175], v[196:199], v[36:39]
	v_mfma_f32_16x16x32_bf16 v[32:35], v[180:183], v[196:199], v[32:35]
	v_mfma_f32_16x16x32_bf16 v[20:23], v[172:175], v[204:207], v[20:23]
	v_mfma_f32_16x16x32_bf16 v[16:19], v[180:183], v[204:207], v[16:19]
	v_mfma_f32_16x16x32_bf16 v[4:7], v[172:175], v[212:215], v[4:7]
	v_mfma_f32_16x16x32_bf16 v[0:3], v[180:183], v[212:215], v[0:3]
	s_setprio 0
	s_barrier
	v_add_u32_e32 v164, s29, v147
	v_add_u32_e32 v180, s28, v147
	ds_read_b128 v[142:145], v164
	ds_read_b128 v[156:159], v164 offset:1024
	ds_read_b128 v[160:163], v164 offset:2048
	ds_read_b128 v[164:167], v164 offset:3072
	ds_read_b128 v[168:171], v180
	ds_read_b128 v[172:175], v180 offset:1024
	ds_read_b128 v[176:179], v180 offset:2048
	ds_read_b128 v[180:183], v180 offset:3072
	s_mov_b32 m0, s60
	v_lshl_add_u64 v[224:225], s[48:49], 0, v[128:129]
	ds_read_b128 v[184:187], v152 offset:32768
	ds_read_b128 v[188:191], v152 offset:33792
	ds_read_b128 v[192:195], v152 offset:34816
	ds_read_b128 v[196:199], v152 offset:35840
	ds_read_b128 v[200:203], v152 offset:36864
	ds_read_b128 v[204:207], v152 offset:37888
	ds_read_b128 v[208:211], v152 offset:38912
	ds_read_b128 v[212:215], v152 offset:39936
	global_load_lds_dwordx4 v[224:225], off
	v_lshl_add_u64 v[224:225], s[48:49], 0, v[132:133]
	s_mov_b32 m0, s61
	s_nop 0
	global_load_lds_dwordx4 v[224:225], off
	s_waitcnt vmcnt(8)
	s_waitcnt lgkmcnt(0)
	s_barrier
	s_setprio 1
	s_waitcnt lgkmcnt(0)
	v_mfma_f32_16x16x32_bf16 v[124:127], v[142:145], v[184:187], v[124:127]
	v_mfma_f32_16x16x32_bf16 v[120:123], v[160:163], v[184:187], v[120:123]
	v_mfma_f32_16x16x32_bf16 v[108:111], v[142:145], v[192:195], v[108:111]
	v_mfma_f32_16x16x32_bf16 v[104:107], v[160:163], v[192:195], v[104:107]
	v_mfma_f32_16x16x32_bf16 v[92:95], v[142:145], v[200:203], v[92:95]
	v_mfma_f32_16x16x32_bf16 v[88:91], v[160:163], v[200:203], v[88:91]
	v_mfma_f32_16x16x32_bf16 v[76:79], v[142:145], v[208:211], v[76:79]
	v_mfma_f32_16x16x32_bf16 v[72:75], v[160:163], v[208:211], v[72:75]
	v_mfma_f32_16x16x32_bf16 v[124:127], v[156:159], v[188:191], v[124:127]
	v_mfma_f32_16x16x32_bf16 v[120:123], v[164:167], v[188:191], v[120:123]
	v_mfma_f32_16x16x32_bf16 v[108:111], v[156:159], v[196:199], v[108:111]
	v_mfma_f32_16x16x32_bf16 v[104:107], v[164:167], v[196:199], v[104:107]
	v_mfma_f32_16x16x32_bf16 v[92:95], v[156:159], v[204:207], v[92:95]
	v_mfma_f32_16x16x32_bf16 v[88:91], v[164:167], v[204:207], v[88:91]
	v_mfma_f32_16x16x32_bf16 v[76:79], v[156:159], v[212:215], v[76:79]
	v_mfma_f32_16x16x32_bf16 v[72:75], v[164:167], v[212:215], v[72:75]
	s_setprio 0
	s_setprio 1
	v_mfma_f32_16x16x32_bf16 v[116:119], v[168:171], v[184:187], v[116:119]
	v_mfma_f32_16x16x32_bf16 v[112:115], v[176:179], v[184:187], v[112:115]
	v_mfma_f32_16x16x32_bf16 v[100:103], v[168:171], v[192:195], v[100:103]
	v_mfma_f32_16x16x32_bf16 v[96:99], v[176:179], v[192:195], v[96:99]
	v_mfma_f32_16x16x32_bf16 v[84:87], v[168:171], v[200:203], v[84:87]
	v_mfma_f32_16x16x32_bf16 v[80:83], v[176:179], v[200:203], v[80:83]
	v_mfma_f32_16x16x32_bf16 v[68:71], v[168:171], v[208:211], v[68:71]
	v_mfma_f32_16x16x32_bf16 v[64:67], v[176:179], v[208:211], v[64:67]
	v_mfma_f32_16x16x32_bf16 v[116:119], v[172:175], v[188:191], v[116:119]
	v_mfma_f32_16x16x32_bf16 v[112:115], v[180:183], v[188:191], v[112:115]
	v_mfma_f32_16x16x32_bf16 v[100:103], v[172:175], v[196:199], v[100:103]
	v_mfma_f32_16x16x32_bf16 v[96:99], v[180:183], v[196:199], v[96:99]
	v_mfma_f32_16x16x32_bf16 v[84:87], v[172:175], v[204:207], v[84:87]
	v_mfma_f32_16x16x32_bf16 v[80:83], v[180:183], v[204:207], v[80:83]
	v_mfma_f32_16x16x32_bf16 v[68:71], v[172:175], v[212:215], v[68:71]
	v_mfma_f32_16x16x32_bf16 v[64:67], v[180:183], v[212:215], v[64:67]
	s_setprio 0
	s_barrier
;     __device__ __forceinline__ void operator()(const f32x4 (&acc)[2][2][4][2], const Unit& u, int wr, int wc, int fr, int fq) const {
;     ...
;             for (int m = 0; m < 4; ++m) { const int rowg = u.pm * BM + ai * HALF + wr * 64 + m * 16, row = rowg + fr; const size_t off = (size_t)row * 1024 + col0;
;                 u32x4 w[2]; float ss = 0.f;
; #pragma unroll
;                 for (int bj = 0; bj < 2; ++bj) { f32x4 b0, b1;
; template <class Epi, class Sched, bool ALIGN_EPI = false, bool SP2 = false>
; __device__ __forceinline__ void gemm_phase(PG8_LAS unsigned char* lds, const Gemm g, const Sched& S, const Epi& E) {
;     ...
;             PG8_WAIT_V(8); PG8_WAIT_L(0); PG8_BAR; PG8_MMA(0, 0, At, B0); PG8_MMA(0, 1, At, B1); PG8_BAR; PG8_SCHED;
;             PG8_LDA(At, 1, 1); PG8_STAGE(PG8_SB(1, 0), b3, voffB); PG8_STAGE(PG8_SB(1, 1), b3 + hstepB, voffB); PG8_STAGE(PG8_SA(1, 0), a3, voffA);
;             PG8_WAIT_V(8); PG8_WAIT_L(0); PG8_BAR; PG8_MMA(1, 0, At, B0); PG8_MMA(1, 1, At, B1); PG8_BAR; PG8_SCHED;
;             } else {
;             PG8_LDB(B0, 0, 0); PG8_SCHED; PG8_LDA(At, 0, 0); PG8_STAGE(PG8_SA(1, 1), a1 + hstepA, voffA);
;             PG8_WAIT_L(8); PG8_BAR; PG8_WAIT_L(0); PG8_MMA(0, 0, At, B0); PG8_BAR; PG8_SCHED;
;             PG8_LDB(B1, 0, 1); PG8_STAGE(PG8_SB(0, 0), b2, voffB);
;             PG8_BAR; PG8_WAIT_L(0); PG8_MMA(0, 1, At, B1); PG8_BAR;
;             PG8_LDA(At, 0, 1); PG8_STAGE(PG8_SA(0, 0), a2, voffA);
;             PG8_BAR; PG8_WAIT_L(0); PG8_MMA(1, 0, At, B0); PG8_BAR; PG8_SCHED;
;             PG8_STAGE(PG8_SB(0, 1), b2 + hstepB, voffB);
;             PG8_WAIT_V(6); PG8_BAR; PG8_MMA(1, 1, At, B1); PG8_BAR;
;             PG8_LDB(B0, 1, 0); PG8_SCHED; PG8_LDA(At, 1, 0); PG8_STAGE(PG8_SA(0, 1), a2 + hstepA, voffA);
;             PG8_WAIT_L(8); PG8_BAR; PG8_WAIT_L(0); PG8_MMA(0, 0, At, B0); PG8_BAR; PG8_SCHED;
;             PG8_LDB(B1, 1, 1); PG8_STAGE(PG8_SB(1, 0), b3, voffB);
;             PG8_BAR; PG8_WAIT_L(0); PG8_MMA(0, 1, At, B1); PG8_BAR;
;             PG8_LDA(At, 1, 1); PG8_STAGE(PG8_SA(1, 0), a3, voffA);
;             PG8_BAR; PG8_WAIT_L(0); PG8_MMA(1, 0, At, B0); PG8_BAR; PG8_SCHED;
;             PG8_STAGE(PG8_SB(1, 1), b3 + hstepB, voffB);
;             PG8_WAIT_V(6); PG8_BAR; PG8_MMA(1, 1, At, B1); PG8_BAR;
;             }
;         }
;         if constexpr (ALIGN_EPI) { if (wr == 0) PG8_BAR; }
	s_mov_b32 m0, s27
	v_lshl_add_u64 v[216:217], v[216:217], 0, s[18:19]
	ds_read_b128 v[184:187], v152 offset:49152
	ds_read_b128 v[188:191], v152 offset:50176
	ds_read_b128 v[192:195], v152 offset:51200
	ds_read_b128 v[196:199], v152 offset:52224
	ds_read_b128 v[200:203], v152 offset:53248
	ds_read_b128 v[204:207], v152 offset:54272
	ds_read_b128 v[208:211], v152 offset:55296
	ds_read_b128 v[212:215], v152 offset:56320
	global_load_lds_dwordx4 v[216:217], off
	v_lshl_add_u64 v[216:217], v[218:219], 0, s[18:19]
	s_mov_b32 m0, s26
	s_nop 0
	global_load_lds_dwordx4 v[216:217], off
	v_lshl_add_u64 v[216:217], s[34:35], 0, v[130:131]
	s_mov_b32 m0, s41
	s_nop 0
	global_load_lds_dwordx4 v[216:217], off
	v_lshl_add_u64 v[216:217], s[34:35], 0, v[134:135]
	s_mov_b32 m0, s39
	s_nop 0
	global_load_lds_dwordx4 v[216:217], off
	v_lshl_add_u64 v[216:217], v[220:221], 0, s[18:19]
	s_mov_b32 m0, s65
	s_nop 0
	global_load_lds_dwordx4 v[216:217], off
	v_lshl_add_u64 v[216:217], v[222:223], 0, s[18:19]
	s_mov_b32 m0, s66
	s_nop 0
	global_load_lds_dwordx4 v[216:217], off
	s_waitcnt vmcnt(8)
	s_waitcnt lgkmcnt(0)
	s_barrier
	s_setprio 1
	s_waitcnt lgkmcnt(0)
	v_mfma_f32_16x16x32_bf16 v[60:63], v[142:145], v[184:187], v[60:63]
	v_mfma_f32_16x16x32_bf16 v[56:59], v[160:163], v[184:187], v[56:59]
	v_mfma_f32_16x16x32_bf16 v[44:47], v[142:145], v[192:195], v[44:47]
	v_mfma_f32_16x16x32_bf16 v[40:43], v[160:163], v[192:195], v[40:43]
	v_mfma_f32_16x16x32_bf16 v[28:31], v[142:145], v[200:203], v[28:31]
	v_mfma_f32_16x16x32_bf16 v[24:27], v[160:163], v[200:203], v[24:27]
	v_mfma_f32_16x16x32_bf16 v[12:15], v[142:145], v[208:211], v[12:15]
	v_mfma_f32_16x16x32_bf16 v[8:11], v[160:163], v[208:211], v[8:11]
	v_mfma_f32_16x16x32_bf16 v[60:63], v[156:159], v[188:191], v[60:63]
	v_mfma_f32_16x16x32_bf16 v[56:59], v[164:167], v[188:191], v[56:59]
	v_mfma_f32_16x16x32_bf16 v[44:47], v[156:159], v[196:199], v[44:47]
	v_mfma_f32_16x16x32_bf16 v[40:43], v[164:167], v[196:199], v[40:43]
	v_mfma_f32_16x16x32_bf16 v[28:31], v[156:159], v[204:207], v[28:31]
	v_mfma_f32_16x16x32_bf16 v[24:27], v[164:167], v[204:207], v[24:27]
	v_mfma_f32_16x16x32_bf16 v[12:15], v[156:159], v[212:215], v[12:15]
	v_mfma_f32_16x16x32_bf16 v[8:11], v[164:167], v[212:215], v[8:11]
	s_setprio 0
	s_setprio 1
	v_mfma_f32_16x16x32_bf16 v[52:55], v[168:171], v[184:187], v[52:55]
	v_mfma_f32_16x16x32_bf16 v[48:51], v[176:179], v[184:187], v[48:51]
	v_mfma_f32_16x16x32_bf16 v[36:39], v[168:171], v[192:195], v[36:39]
	v_mfma_f32_16x16x32_bf16 v[32:35], v[176:179], v[192:195], v[32:35]
	v_mfma_f32_16x16x32_bf16 v[20:23], v[168:171], v[200:203], v[20:23]
	v_mfma_f32_16x16x32_bf16 v[16:19], v[176:179], v[200:203], v[16:19]
	v_mfma_f32_16x16x32_bf16 v[4:7], v[168:171], v[208:211], v[4:7]
	v_mfma_f32_16x16x32_bf16 v[0:3], v[176:179], v[208:211], v[0:3]
	v_mfma_f32_16x16x32_bf16 v[52:55], v[172:175], v[188:191], v[52:55]
	v_mfma_f32_16x16x32_bf16 v[48:51], v[180:183], v[188:191], v[48:51]
	v_mfma_f32_16x16x32_bf16 v[36:39], v[172:175], v[196:199], v[36:39]
	v_mfma_f32_16x16x32_bf16 v[32:35], v[180:183], v[196:199], v[32:35]
	v_mfma_f32_16x16x32_bf16 v[20:23], v[172:175], v[204:207], v[20:23]
	v_mfma_f32_16x16x32_bf16 v[16:19], v[180:183], v[204:207], v[16:19]
	v_mfma_f32_16x16x32_bf16 v[4:7], v[172:175], v[212:215], v[4:7]
	v_mfma_f32_16x16x32_bf16 v[0:3], v[180:183], v[212:215], v[0:3]
	s_setprio 0
	s_barrier
	s_movk_i32 s26, 0x100
	s_andn2_b64 vcc, exec, s[22:23]
	s_mov_b64 s[34:35], -1
	s_mov_b64 s[22:23], 0
	s_cbranch_vccz .LBB0_1018
	s_lshl_b32 s22, s46, 8
	s_add_i32 s22, s22, s64
	v_or_b32_e32 v144, s22, v146
	v_ashrrev_i32_e32 v145, 31, v144
	v_readlane_b32 s30, v239, 49
	v_lshl_or_b32 v142, s14, 8, v148
	v_lshlrev_b64 v[156:157], 11, v[144:145]
	v_readlane_b32 s31, v239, 50
	v_ashrrev_i32_e32 v143, 31, v142
	s_lshl_b32 s0, s14, 2
	v_lshl_add_u64 v[156:157], s[30:31], 0, v[156:157]
	v_lshl_add_u64 v[156:157], v[142:143], 1, v[156:157]
	v_add_co_u32_e32 v184, vcc, 0x8000, v156
	s_nop 1
	v_addc_co_u32_e32 v185, vcc, 0, v157, vcc
	v_add_co_u32_e32 v192, vcc, 0x10000, v156
	s_nop 1
	v_addc_co_u32_e32 v193, vcc, 0, v157, vcc
	v_add_co_u32_e32 v200, vcc, 0x18000, v156
	s_nop 1
	v_addc_co_u32_e32 v201, vcc, 0, v157, vcc
	v_add_co_u32_e32 v208, vcc, 0x40000, v156
	s_nop 1
	v_addc_co_u32_e32 v209, vcc, 0, v157, vcc
	v_add_co_u32_e32 v216, vcc, 0x48000, v156
	s_nop 1
	v_addc_co_u32_e32 v217, vcc, 0, v157, vcc
	v_add_co_u32_e32 v224, vcc, 0x50000, v156
	s_nop 1
	v_addc_co_u32_e32 v225, vcc, 0, v157, vcc
	v_add_co_u32_e32 v232, vcc, 0x58000, v156
	s_nop 1
	v_addc_co_u32_e32 v233, vcc, 0, v157, vcc
	global_load_dwordx4 v[158:161], v[156:157], off
	global_load_dwordx4 v[162:165], v[156:157], off offset:64
	global_load_dwordx4 v[180:183], v[184:185], off
	global_load_dwordx4 v[184:187], v[184:185], off offset:64
	global_load_dwordx4 v[188:191], v[192:193], off
	global_load_dwordx4 v[192:195], v[192:193], off offset:64
	global_load_dwordx4 v[196:199], v[200:201], off
	global_load_dwordx4 v[200:203], v[200:201], off offset:64
	global_load_dwordx4 v[204:207], v[208:209], off
	global_load_dwordx4 v[208:211], v[208:209], off offset:64
	global_load_dwordx4 v[212:215], v[216:217], off
	global_load_dwordx4 v[216:219], v[216:217], off offset:64
	global_load_dwordx4 v[220:223], v[224:225], off
	global_load_dwordx4 v[224:227], v[224:225], off offset:64
	global_load_dwordx4 v[228:231], v[232:233], off
	global_load_dwordx4 v[232:235], v[232:233], off offset:64
	s_and_b64 vcc, exec, s[36:37]
	s_cbranch_vccz .LBB0_1021
	s_barrier
; __device__ __forceinline__ unsigned swap8(unsigned v) { return (unsigned)__builtin_amdgcn_update_dpp(0, (int)v, 0x128  , 0xF, 0xF, false); }
; __device__ __forceinline__ void wide_store(bf16_t* O, int ldc, int rowg  , int col0  , int fr, u32x4 w0, u32x4 w1) {
;     const bool lo = fr < 8;
;     u32x4 snd = lo ? w1 : w0, rcv;
;     rcv.x = swap8(snd.x); rcv.y = swap8(snd.y); rcv.z = swap8(snd.z); rcv.w = swap8(snd.w);
;     const u32x4 first = lo ? w0 : rcv, second = lo ? rcv : w1;
;     bf16_t* p = O + (size_t)(rowg + (fr & 7)) * ldc + col0 + (lo ? 0 : 32);
;     __builtin_nontemporal_store(first, (u32x4*)p); __builtin_nontemporal_store(second, (u32x4*)(p + (size_t)8 * ldc));
;     __device__ __forceinline__ void operator()(const f32x4 (&acc)[2][2][4][2], const Unit& u, int wr, int wc, int fr, int fq) const {
;     ...
;             for (int m = 0; m < 4; ++m) { const int rowg = u.pm * BM + ai * HALF + wr * 64 + m * 16, row = rowg + fr; const size_t off = (size_t)row * 1024 + col0;
;                 u32x4 w[2]; float ss = 0.f;
; #pragma unroll
;                 for (int bj = 0; bj < 2; ++bj) { f32x4 b0, b1;
;                     if (BASE_F32) { const float* bp = (const float*)base + off + 32 * bj; b0 = *(const f32x4*)bp; b1 = *(const f32x4*)(bp + 4); }
;                     else { const u32x4 bb = *(const u32x4*)((const bf16_t*)base + off + 32 * bj);
;                         b0 = (f32x4){__uint_as_float(bb.x << 16), __uint_as_float(bb.x & 0xffff0000u), __uint_as_float(bb.y << 16), __uint_as_float(bb.y & 0xffff0000u)};
;                         b1 = (f32x4){__uint_as_float(bb.z << 16), __uint_as_float(bb.z & 0xffff0000u), __uint_as_float(bb.w << 16), __uint_as_float(bb.w & 0xffff0000u)}; }
;                     const f32x4 o0 = b0 + acc[ai][bj][m][0], o1 = b1 + acc[ai][bj][m][1];
;                     ss += ((o0[0] * o0[0] + o0[1] * o0[1]) + (o0[2] * o0[2] + o0[3] * o0[3])) + ((o1[0] * o1[0] + o1[1] * o1[1]) + (o1[2] * o1[2] + o1[3] * o1[3]));
;                     w[bj].x = cvt_pk_bf16(o0[0], o0[1]); w[bj].y = cvt_pk_bf16(o0[2], o0[3]); w[bj].z = cvt_pk_bf16(o1[0], o1[1]); w[bj].w = cvt_pk_bf16(o1[2], o1[3]); }
;                 ss += __shfl_xor(ss, 16); ss += __shfl_xor(ss, 32); if (fq == 0) slots[(size_t)row * 16 + u.pn * 4 + wc] = ss;
;                 wide_store(xb, 1024, rowg, col0, fr, w[0], w[1]);
.LBB0_1021:
	v_and_b32_e32 v157, 64, v155
	v_xor_b32_e32 v156, 16, v155
	v_add_u32_e32 v157, 64, v157
	v_cmp_lt_i32_e32 vcc, v156, v157
	s_ashr_i32 s1, s0, 31
	s_waitcnt vmcnt(14)
	v_lshlrev_b32_e32 v166, 16, v158
	v_and_b32_e32 v167, 0xffff0000, v158
	v_lshlrev_b32_e32 v158, 16, v159
	v_and_b32_e32 v159, 0xffff0000, v159
	v_lshlrev_b32_e32 v168, 16, v160
	v_and_b32_e32 v169, 0xffff0000, v160
	v_lshlrev_b32_e32 v160, 16, v161
	v_and_b32_e32 v161, 0xffff0000, v161
	v_lshlrev_b32_e32 v170, 16, v162
	v_and_b32_e32 v171, 0xffff0000, v162
	v_lshlrev_b32_e32 v162, 16, v163
	v_and_b32_e32 v163, 0xffff0000, v163
	v_lshlrev_b32_e32 v172, 16, v164
	v_and_b32_e32 v173, 0xffff0000, v164
	v_lshlrev_b32_e32 v164, 16, v165
	v_and_b32_e32 v165, 0xffff0000, v165
	v_pk_add_f32 v[126:127], v[126:127], v[158:159]
	v_pk_add_f32 v[124:125], v[124:125], v[166:167]
	v_pk_add_f32 v[122:123], v[122:123], v[160:161]
	v_pk_add_f32 v[120:121], v[120:121], v[168:169]
	v_pk_add_f32 v[118:119], v[118:119], v[162:163]
	v_pk_add_f32 v[116:117], v[116:117], v[170:171]
	v_pk_add_f32 v[114:115], v[114:115], v[164:165]
	v_pk_add_f32 v[112:113], v[112:113], v[172:173]
	v_mul_f32_e32 v158, v125, v125
	v_mul_f32_e32 v159, v127, v127
	v_mul_f32_e32 v160, v121, v121
	v_mul_f32_e32 v161, v123, v123
	v_mul_f32_e32 v162, v117, v117
	v_mul_f32_e32 v163, v119, v119
	v_mul_f32_e32 v164, v113, v113
	v_mul_f32_e32 v165, v115, v115
	v_fmac_f32_e32 v158, v124, v124
	v_fmac_f32_e32 v159, v126, v126
	v_fmac_f32_e32 v160, v120, v120
	v_fmac_f32_e32 v161, v122, v122
	v_fmac_f32_e32 v162, v116, v116
	v_fmac_f32_e32 v163, v118, v118
	v_fmac_f32_e32 v164, v112, v112
	v_fmac_f32_e32 v165, v114, v114
	v_add_f32_e32 v158, v158, v159
	v_add_f32_e32 v159, v160, v161
	v_add_f32_e32 v160, v162, v163
	v_add_f32_e32 v161, v164, v165
	v_cndmask_b32_e32 v156, v155, v156, vcc
	v_add_f32_e32 v158, v158, v159
	v_add_f32_e32 v159, v160, v161
	v_lshlrev_b32_e32 v156, 2, v156
	v_add_f32_e32 v158, v158, v159
	ds_bpermute_b32 v159, v156, v158
	v_xor_b32_e32 v160, 32, v155
	v_cmp_lt_i32_e32 vcc, v160, v157
	s_waitcnt lgkmcnt(0)
	v_add_f32_e32 v158, v158, v159
	v_cndmask_b32_e32 v157, v155, v160, vcc
	v_lshlrev_b32_e32 v157, 2, v157
	ds_bpermute_b32 v159, v157, v158
	s_and_saveexec_b64 s[20:21], s[2:3]
	s_cbranch_execz .LBB0_1023
	v_lshlrev_b64 v[144:145], 6, v[144:145]
	v_lshl_add_u64 v[144:145], s[82:83], 0, v[144:145]
	v_lshl_add_u64 v[144:145], s[0:1], 2, v[144:145]
	s_lshl_b32 s14, s63, 2
	v_lshl_add_u64 v[144:145], v[144:145], 0, s[14:15]
	s_waitcnt lgkmcnt(0)
	v_add_f32_e32 v158, v158, v159
	global_store_dword v[144:145], v158, off
.LBB0_1023:
	s_or_b64 exec, exec, s[20:21]
	v_cvt_pk_bf16_f32 v120, v120, v121
	v_cvt_pk_bf16_f32 v112, v112, v113
	v_cvt_pk_bf16_f32 v124, v124, v125
	v_cvt_pk_bf16_f32 v125, v126, v127
	v_cvt_pk_bf16_f32 v121, v122, v123
	v_cvt_pk_bf16_f32 v118, v118, v119
	v_cvt_pk_bf16_f32 v113, v114, v115
	v_cndmask_b32_e64 v115, v120, v112, s[4:5]
	v_mov_b32_e32 v126, v137
	v_cvt_pk_bf16_f32 v122, v116, v117
	v_cndmask_b32_e64 v114, v121, v113, s[4:5]
	v_cndmask_b32_e64 v116, v125, v118, s[4:5]
	v_mov_b32_e32 v119, v137
	v_mov_b32_dpp v126, v115 row_ror:8 row_mask:0xf bank_mask:0xf
	v_mov_b32_e32 v127, v137
	v_cndmask_b32_e64 v117, v124, v122, s[4:5]
	v_mov_b32_e32 v123, v137
	v_mov_b32_dpp v119, v116 row_ror:8 row_mask:0xf bank_mask:0xf
	v_mov_b32_dpp v127, v114 row_ror:8 row_mask:0xf bank_mask:0xf
	v_cndmask_b32_e64 v116, v126, v120, s[4:5]
	v_cndmask_b32_e64 v120, v112, v126, s[4:5]
	v_or_b32_e32 v112, s22, v149
	v_mov_b32_dpp v123, v117 row_ror:8 row_mask:0xf bank_mask:0xf
	v_cndmask_b32_e64 v117, v127, v121, s[4:5]
	v_cndmask_b32_e64 v121, v113, v127, s[4:5]
	v_ashrrev_i32_e32 v113, 31, v112
	v_lshlrev_b64 v[112:113], 11, v[112:113]
	v_cndmask_b32_e64 v115, v119, v125, s[4:5]
	v_cndmask_b32_e64 v114, v123, v124, s[4:5]
	v_cndmask_b32_e64 v119, v118, v119, s[4:5]
	v_cndmask_b32_e64 v118, v122, v123, s[4:5]
	v_lshl_add_u64 v[122:123], s[30:31], 0, v[112:113]
	v_lshlrev_b64 v[112:113], 1, v[142:143]
	v_lshl_add_u64 v[122:123], v[122:123], 0, v[112:113]
	v_lshl_add_u64 v[122:123], v[122:123], 0, v[136:137]
	global_store_dwordx4 v[122:123], v[114:117], off nt
	s_or_b32 s23, s22, 16
	s_nop 0
	v_add_co_u32_e32 v114, vcc, s62, v122
	s_nop 1
	v_addc_co_u32_e32 v115, vcc, 0, v123, vcc
	global_store_dwordx4 v[114:115], v[118:121], off nt
	v_or_b32_e32 v114, s23, v146
	v_ashrrev_i32_e32 v115, 31, v114
	v_lshlrev_b64 v[116:117], 11, v[114:115]
	v_lshl_add_u64 v[116:117], s[30:31], 0, v[116:117]
	v_lshl_add_u64 v[120:121], v[116:117], 0, v[112:113]
	s_waitcnt vmcnt(15)
	v_mov_b32_e32 v116, v180
	v_mov_b32_e32 v117, v181
	v_mov_b32_e32 v118, v182
	v_mov_b32_e32 v119, v183
	v_mov_b32_e32 v120, v184
	v_mov_b32_e32 v121, v185
	v_mov_b32_e32 v122, v186
	v_mov_b32_e32 v123, v187
	v_lshlrev_b32_e32 v124, 16, v116
	v_and_b32_e32 v125, 0xffff0000, v116
	v_lshlrev_b32_e32 v116, 16, v117
	v_and_b32_e32 v117, 0xffff0000, v117
	v_lshlrev_b32_e32 v126, 16, v118
	v_and_b32_e32 v127, 0xffff0000, v118
	v_lshlrev_b32_e32 v118, 16, v119
	v_and_b32_e32 v119, 0xffff0000, v119
	v_lshlrev_b32_e32 v144, 16, v120
	v_and_b32_e32 v145, 0xffff0000, v120
	v_lshlrev_b32_e32 v120, 16, v121
	v_and_b32_e32 v121, 0xffff0000, v121
	v_lshlrev_b32_e32 v158, 16, v122
	s_waitcnt lgkmcnt(0)
	v_and_b32_e32 v159, 0xffff0000, v122
	v_lshlrev_b32_e32 v122, 16, v123
	v_and_b32_e32 v123, 0xffff0000, v123
	v_pk_add_f32 v[110:111], v[110:111], v[116:117]
	v_pk_add_f32 v[108:109], v[108:109], v[124:125]
	v_pk_add_f32 v[106:107], v[106:107], v[118:119]
	v_pk_add_f32 v[104:105], v[104:105], v[126:127]
	v_pk_add_f32 v[102:103], v[102:103], v[120:121]
	v_pk_add_f32 v[100:101], v[100:101], v[144:145]
	v_pk_add_f32 v[98:99], v[98:99], v[122:123]
	v_pk_add_f32 v[96:97], v[96:97], v[158:159]
	v_mul_f32_e32 v116, v109, v109
	v_mul_f32_e32 v117, v111, v111
	v_mul_f32_e32 v118, v105, v105
	v_mul_f32_e32 v119, v107, v107
	v_mul_f32_e32 v120, v101, v101
	v_mul_f32_e32 v121, v103, v103
	v_mul_f32_e32 v122, v97, v97
	v_mul_f32_e32 v123, v99, v99
	v_fmac_f32_e32 v116, v108, v108
	v_fmac_f32_e32 v117, v110, v110
	v_fmac_f32_e32 v118, v104, v104
	v_fmac_f32_e32 v119, v106, v106
	v_fmac_f32_e32 v120, v100, v100
	v_fmac_f32_e32 v121, v102, v102
	v_fmac_f32_e32 v122, v96, v96
	v_fmac_f32_e32 v123, v98, v98
	v_add_f32_e32 v116, v116, v117
	v_add_f32_e32 v117, v118, v119
	v_add_f32_e32 v118, v120, v121
	v_add_f32_e32 v119, v122, v123
	v_add_f32_e32 v116, v116, v117
	v_add_f32_e32 v117, v118, v119
	v_add_f32_e32 v116, v116, v117
	ds_bpermute_b32 v117, v156, v116
	s_waitcnt lgkmcnt(0)
	v_add_f32_e32 v116, v116, v117
	ds_bpermute_b32 v117, v157, v116
	s_and_saveexec_b64 s[20:21], s[2:3]
	s_cbranch_execz .LBB0_1025
	v_lshlrev_b64 v[114:115], 6, v[114:115]
	v_lshl_add_u64 v[114:115], s[82:83], 0, v[114:115]
	v_lshl_add_u64 v[114:115], s[0:1], 2, v[114:115]
	s_lshl_b32 s14, s63, 2
	v_lshl_add_u64 v[114:115], v[114:115], 0, s[14:15]
	s_waitcnt lgkmcnt(0)
	v_add_f32_e32 v116, v116, v117
	global_store_dword v[114:115], v116, off
; __device__ __forceinline__ unsigned swap8(unsigned v) { return (unsigned)__builtin_amdgcn_update_dpp(0, (int)v, 0x128  , 0xF, 0xF, false); }
; __device__ __forceinline__ void wide_store(bf16_t* O, int ldc, int rowg  , int col0  , int fr, u32x4 w0, u32x4 w1) {
;     const bool lo = fr < 8;
;     u32x4 snd = lo ? w1 : w0, rcv;
;     rcv.x = swap8(snd.x); rcv.y = swap8(snd.y); rcv.z = swap8(snd.z); rcv.w = swap8(snd.w);
;     const u32x4 first = lo ? w0 : rcv, second = lo ? rcv : w1;
;     bf16_t* p = O + (size_t)(rowg + (fr & 7)) * ldc + col0 + (lo ? 0 : 32);
;     __builtin_nontemporal_store(first, (u32x4*)p); __builtin_nontemporal_store(second, (u32x4*)(p + (size_t)8 * ldc));
;     __device__ __forceinline__ void operator()(const f32x4 (&acc)[2][2][4][2], const Unit& u, int wr, int wc, int fr, int fq) const {
;     ...
;             for (int m = 0; m < 4; ++m) { const int rowg = u.pm * BM + ai * HALF + wr * 64 + m * 16, row = rowg + fr; const size_t off = (size_t)row * 1024 + col0;
;                 u32x4 w[2]; float ss = 0.f;
; #pragma unroll
;                 for (int bj = 0; bj < 2; ++bj) { f32x4 b0, b1;
;                     if (BASE_F32) { const float* bp = (const float*)base + off + 32 * bj; b0 = *(const f32x4*)bp; b1 = *(const f32x4*)(bp + 4); }
;                     else { const u32x4 bb = *(const u32x4*)((const bf16_t*)base + off + 32 * bj);
;                         b0 = (f32x4){__uint_as_float(bb.x << 16), __uint_as_float(bb.x & 0xffff0000u), __uint_as_float(bb.y << 16), __uint_as_float(bb.y & 0xffff0000u)};
;                         b1 = (f32x4){__uint_as_float(bb.z << 16), __uint_as_float(bb.z & 0xffff0000u), __uint_as_float(bb.w << 16), __uint_as_float(bb.w & 0xffff0000u)}; }
;                     const f32x4 o0 = b0 + acc[ai][bj][m][0], o1 = b1 + acc[ai][bj][m][1];
;                     ss += ((o0[0] * o0[0] + o0[1] * o0[1]) + (o0[2] * o0[2] + o0[3] * o0[3])) + ((o1[0] * o1[0] + o1[1] * o1[1]) + (o1[2] * o1[2] + o1[3] * o1[3]));
;                     w[bj].x = cvt_pk_bf16(o0[0], o0[1]); w[bj].y = cvt_pk_bf16(o0[2], o0[3]); w[bj].z = cvt_pk_bf16(o1[0], o1[1]); w[bj].w = cvt_pk_bf16(o1[2], o1[3]); }
;                 ss += __shfl_xor(ss, 16); ss += __shfl_xor(ss, 32); if (fq == 0) slots[(size_t)row * 16 + u.pn * 4 + wc] = ss;
;                 wide_store(xb, 1024, rowg, col0, fr, w[0], w[1]);
.LBB0_1025:
	s_or_b64 exec, exec, s[20:21]
	v_cvt_pk_bf16_f32 v104, v104, v105
	v_cvt_pk_bf16_f32 v100, v100, v101
	v_cvt_pk_bf16_f32 v101, v102, v103
	v_cvt_pk_bf16_f32 v102, v96, v97
	v_cvt_pk_bf16_f32 v108, v108, v109
	v_cvt_pk_bf16_f32 v109, v110, v111
	v_cvt_pk_bf16_f32 v105, v106, v107
	v_cvt_pk_bf16_f32 v103, v98, v99
	v_cndmask_b32_e64 v97, v104, v102, s[4:5]
	v_mov_b32_e32 v110, v137
	v_cndmask_b32_e64 v96, v105, v103, s[4:5]
	v_cndmask_b32_e64 v98, v109, v101, s[4:5]
	v_mov_b32_e32 v107, v137
	v_mov_b32_dpp v110, v97 row_ror:8 row_mask:0xf bank_mask:0xf
	v_mov_b32_e32 v111, v137
	v_cndmask_b32_e64 v99, v108, v100, s[4:5]
	v_mov_b32_e32 v106, v137
	v_mov_b32_dpp v107, v98 row_ror:8 row_mask:0xf bank_mask:0xf
	v_mov_b32_dpp v111, v96 row_ror:8 row_mask:0xf bank_mask:0xf
	v_cndmask_b32_e64 v98, v110, v104, s[4:5]
	v_or_b32_e32 v104, s23, v149
	v_mov_b32_dpp v106, v99 row_ror:8 row_mask:0xf bank_mask:0xf
	v_cndmask_b32_e64 v99, v111, v105, s[4:5]
	v_ashrrev_i32_e32 v105, 31, v104
	v_lshlrev_b64 v[104:105], 11, v[104:105]
	v_lshl_add_u64 v[104:105], s[30:31], 0, v[104:105]
	v_lshl_add_u64 v[104:105], v[104:105], 0, v[112:113]
	v_cndmask_b32_e64 v97, v107, v109, s[4:5]
	v_cndmask_b32_e64 v96, v106, v108, s[4:5]
	v_lshl_add_u64 v[104:105], v[104:105], 0, v[136:137]
	global_store_dwordx4 v[104:105], v[96:99], off nt
	v_cndmask_b32_e64 v103, v103, v111, s[4:5]
	v_cndmask_b32_e64 v102, v102, v110, s[4:5]
	v_add_co_u32_e32 v96, vcc, s62, v104
	v_cndmask_b32_e64 v101, v101, v107, s[4:5]
	v_cndmask_b32_e64 v100, v100, v106, s[4:5]
	v_addc_co_u32_e32 v97, vcc, 0, v105, vcc
	s_or_b32 s23, s22, 32
	global_store_dwordx4 v[96:97], v[100:103], off nt
	v_or_b32_e32 v96, s23, v146
	v_ashrrev_i32_e32 v97, 31, v96
	v_lshlrev_b64 v[98:99], 11, v[96:97]
	v_lshl_add_u64 v[98:99], s[30:31], 0, v[98:99]
	v_lshl_add_u64 v[102:103], v[98:99], 0, v[112:113]
	s_waitcnt vmcnt(16)
	v_mov_b32_e32 v98, v188
	v_mov_b32_e32 v99, v189
	v_mov_b32_e32 v100, v190
	v_mov_b32_e32 v101, v191
	v_mov_b32_e32 v102, v192
	v_mov_b32_e32 v103, v193
	v_mov_b32_e32 v104, v194
	v_mov_b32_e32 v105, v195
	v_lshlrev_b32_e32 v106, 16, v98
	v_and_b32_e32 v107, 0xffff0000, v98
	v_lshlrev_b32_e32 v98, 16, v99
	v_and_b32_e32 v99, 0xffff0000, v99
	v_lshlrev_b32_e32 v108, 16, v100
	v_and_b32_e32 v109, 0xffff0000, v100
	v_lshlrev_b32_e32 v100, 16, v101
	v_and_b32_e32 v101, 0xffff0000, v101
	v_lshlrev_b32_e32 v110, 16, v102
	v_and_b32_e32 v111, 0xffff0000, v102
	v_lshlrev_b32_e32 v102, 16, v103
	v_and_b32_e32 v103, 0xffff0000, v103
	v_lshlrev_b32_e32 v114, 16, v104
	v_and_b32_e32 v115, 0xffff0000, v104
	v_lshlrev_b32_e32 v104, 16, v105
	v_and_b32_e32 v105, 0xffff0000, v105
	v_pk_add_f32 v[94:95], v[94:95], v[98:99]
	v_pk_add_f32 v[92:93], v[92:93], v[106:107]
	v_pk_add_f32 v[90:91], v[90:91], v[100:101]
	v_pk_add_f32 v[88:89], v[88:89], v[108:109]
	v_pk_add_f32 v[86:87], v[86:87], v[102:103]
	v_pk_add_f32 v[84:85], v[84:85], v[110:111]
	v_pk_add_f32 v[82:83], v[82:83], v[104:105]
	v_pk_add_f32 v[80:81], v[80:81], v[114:115]
	v_mul_f32_e32 v98, v93, v93
	v_mul_f32_e32 v99, v95, v95
	v_mul_f32_e32 v100, v89, v89
	v_mul_f32_e32 v101, v91, v91
	v_mul_f32_e32 v102, v85, v85
	v_mul_f32_e32 v103, v87, v87
	v_mul_f32_e32 v104, v81, v81
	v_mul_f32_e32 v105, v83, v83
	v_fmac_f32_e32 v98, v92, v92
	v_fmac_f32_e32 v99, v94, v94
	v_fmac_f32_e32 v100, v88, v88
	v_fmac_f32_e32 v101, v90, v90
	v_fmac_f32_e32 v102, v84, v84
	v_fmac_f32_e32 v103, v86, v86
	v_fmac_f32_e32 v104, v80, v80
	v_fmac_f32_e32 v105, v82, v82
	v_add_f32_e32 v98, v98, v99
	v_add_f32_e32 v99, v100, v101
	v_add_f32_e32 v100, v102, v103
	v_add_f32_e32 v101, v104, v105
	v_add_f32_e32 v98, v98, v99
	v_add_f32_e32 v99, v100, v101
	v_add_f32_e32 v98, v98, v99
	ds_bpermute_b32 v99, v156, v98
	s_waitcnt lgkmcnt(0)
	v_add_f32_e32 v98, v98, v99
	ds_bpermute_b32 v99, v157, v98
	s_and_saveexec_b64 s[20:21], s[2:3]
	s_cbranch_execz .LBB0_1027
	v_lshlrev_b64 v[96:97], 6, v[96:97]
	v_lshl_add_u64 v[96:97], s[82:83], 0, v[96:97]
	v_lshl_add_u64 v[96:97], s[0:1], 2, v[96:97]
	s_lshl_b32 s14, s63, 2
	v_lshl_add_u64 v[96:97], v[96:97], 0, s[14:15]
	s_waitcnt lgkmcnt(0)
	v_add_f32_e32 v98, v98, v99
	global_store_dword v[96:97], v98, off
.LBB0_1027:
	s_or_b64 exec, exec, s[20:21]
	v_cvt_pk_bf16_f32 v88, v88, v89
	v_cvt_pk_bf16_f32 v84, v84, v85
	v_cvt_pk_bf16_f32 v85, v86, v87
	v_cvt_pk_bf16_f32 v86, v80, v81
	v_cvt_pk_bf16_f32 v92, v92, v93
	v_cvt_pk_bf16_f32 v93, v94, v95
	v_cvt_pk_bf16_f32 v89, v90, v91
	v_cvt_pk_bf16_f32 v87, v82, v83
	v_cndmask_b32_e64 v81, v88, v86, s[4:5]
	v_mov_b32_e32 v94, v137
	v_cndmask_b32_e64 v80, v89, v87, s[4:5]
	v_cndmask_b32_e64 v82, v93, v85, s[4:5]
	v_mov_b32_e32 v91, v137
	v_mov_b32_dpp v94, v81 row_ror:8 row_mask:0xf bank_mask:0xf
	v_mov_b32_e32 v95, v137
	v_cndmask_b32_e64 v83, v92, v84, s[4:5]
	v_mov_b32_e32 v90, v137
	v_mov_b32_dpp v91, v82 row_ror:8 row_mask:0xf bank_mask:0xf
	v_mov_b32_dpp v95, v80 row_ror:8 row_mask:0xf bank_mask:0xf
	v_cndmask_b32_e64 v82, v94, v88, s[4:5]
	v_or_b32_e32 v88, s23, v149
	v_mov_b32_dpp v90, v83 row_ror:8 row_mask:0xf bank_mask:0xf
	v_cndmask_b32_e64 v83, v95, v89, s[4:5]
	v_ashrrev_i32_e32 v89, 31, v88
	v_lshlrev_b64 v[88:89], 11, v[88:89]
	v_lshl_add_u64 v[88:89], s[30:31], 0, v[88:89]
	v_lshl_add_u64 v[88:89], v[88:89], 0, v[112:113]
	v_cndmask_b32_e64 v81, v91, v93, s[4:5]
	v_cndmask_b32_e64 v80, v90, v92, s[4:5]
	v_lshl_add_u64 v[88:89], v[88:89], 0, v[136:137]
	global_store_dwordx4 v[88:89], v[80:83], off nt
	v_cndmask_b32_e64 v87, v87, v95, s[4:5]
	v_cndmask_b32_e64 v86, v86, v94, s[4:5]
	v_add_co_u32_e32 v80, vcc, s62, v88
	v_cndmask_b32_e64 v85, v85, v91, s[4:5]
	v_cndmask_b32_e64 v84, v84, v90, s[4:5]
	v_addc_co_u32_e32 v81, vcc, 0, v89, vcc
	s_or_b32 s23, s22, 48
	global_store_dwordx4 v[80:81], v[84:87], off nt
	v_or_b32_e32 v80, s23, v146
	v_ashrrev_i32_e32 v81, 31, v80
	v_lshlrev_b64 v[82:83], 11, v[80:81]
	v_lshl_add_u64 v[82:83], s[30:31], 0, v[82:83]
	v_lshl_add_u64 v[86:87], v[82:83], 0, v[112:113]
	s_waitcnt vmcnt(17)
; __device__ __forceinline__ unsigned swap8(unsigned v) { return (unsigned)__builtin_amdgcn_update_dpp(0, (int)v, 0x128  , 0xF, 0xF, false); }
; __device__ __forceinline__ void wide_store(bf16_t* O, int ldc, int rowg  , int col0  , int fr, u32x4 w0, u32x4 w1) {
;     const bool lo = fr < 8;
;     u32x4 snd = lo ? w1 : w0, rcv;
;     rcv.x = swap8(snd.x); rcv.y = swap8(snd.y); rcv.z = swap8(snd.z); rcv.w = swap8(snd.w);
;     const u32x4 first = lo ? w0 : rcv, second = lo ? rcv : w1;
;     bf16_t* p = O + (size_t)(rowg + (fr & 7)) * ldc + col0 + (lo ? 0 : 32);
;     __builtin_nontemporal_store(first, (u32x4*)p); __builtin_nontemporal_store(second, (u32x4*)(p + (size_t)8 * ldc));
;     __device__ __forceinline__ void operator()(const f32x4 (&acc)[2][2][4][2], const Unit& u, int wr, int wc, int fr, int fq) const {
;     ...
;             for (int m = 0; m < 4; ++m) { const int rowg = u.pm * BM + ai * HALF + wr * 64 + m * 16, row = rowg + fr; const size_t off = (size_t)row * 1024 + col0;
;                 u32x4 w[2]; float ss = 0.f;
; #pragma unroll
;                 for (int bj = 0; bj < 2; ++bj) { f32x4 b0, b1;
;                     if (BASE_F32) { const float* bp = (const float*)base + off + 32 * bj; b0 = *(const f32x4*)bp; b1 = *(const f32x4*)(bp + 4); }
;                     else { const u32x4 bb = *(const u32x4*)((const bf16_t*)base + off + 32 * bj);
;                         b0 = (f32x4){__uint_as_float(bb.x << 16), __uint_as_float(bb.x & 0xffff0000u), __uint_as_float(bb.y << 16), __uint_as_float(bb.y & 0xffff0000u)};
;                         b1 = (f32x4){__uint_as_float(bb.z << 16), __uint_as_float(bb.z & 0xffff0000u), __uint_as_float(bb.w << 16), __uint_as_float(bb.w & 0xffff0000u)}; }
;                     const f32x4 o0 = b0 + acc[ai][bj][m][0], o1 = b1 + acc[ai][bj][m][1];
;                     ss += ((o0[0] * o0[0] + o0[1] * o0[1]) + (o0[2] * o0[2] + o0[3] * o0[3])) + ((o1[0] * o1[0] + o1[1] * o1[1]) + (o1[2] * o1[2] + o1[3] * o1[3]));
;                     w[bj].x = cvt_pk_bf16(o0[0], o0[1]); w[bj].y = cvt_pk_bf16(o0[2], o0[3]); w[bj].z = cvt_pk_bf16(o1[0], o1[1]); w[bj].w = cvt_pk_bf16(o1[2], o1[3]); }
;                 ss += __shfl_xor(ss, 16); ss += __shfl_xor(ss, 32); if (fq == 0) slots[(size_t)row * 16 + u.pn * 4 + wc] = ss;
;                 wide_store(xb, 1024, rowg, col0, fr, w[0], w[1]);
	v_mov_b32_e32 v82, v196
	v_mov_b32_e32 v83, v197
	v_mov_b32_e32 v84, v198
	v_mov_b32_e32 v85, v199
	v_mov_b32_e32 v86, v200
	v_mov_b32_e32 v87, v201
	v_mov_b32_e32 v88, v202
	v_mov_b32_e32 v89, v203
	v_lshlrev_b32_e32 v90, 16, v82
	v_and_b32_e32 v91, 0xffff0000, v82
	v_lshlrev_b32_e32 v82, 16, v83
	v_and_b32_e32 v83, 0xffff0000, v83
	v_lshlrev_b32_e32 v92, 16, v84
	v_and_b32_e32 v93, 0xffff0000, v84
	v_lshlrev_b32_e32 v84, 16, v85
	v_and_b32_e32 v85, 0xffff0000, v85
	v_lshlrev_b32_e32 v94, 16, v86
	v_and_b32_e32 v95, 0xffff0000, v86
	v_lshlrev_b32_e32 v86, 16, v87
	v_and_b32_e32 v87, 0xffff0000, v87
	v_lshlrev_b32_e32 v96, 16, v88
	v_and_b32_e32 v97, 0xffff0000, v88
	v_lshlrev_b32_e32 v88, 16, v89
	v_and_b32_e32 v89, 0xffff0000, v89
	v_pk_add_f32 v[78:79], v[78:79], v[82:83]
	v_pk_add_f32 v[76:77], v[76:77], v[90:91]
	v_pk_add_f32 v[74:75], v[74:75], v[84:85]
	v_pk_add_f32 v[72:73], v[72:73], v[92:93]
	v_pk_add_f32 v[70:71], v[70:71], v[86:87]
	v_pk_add_f32 v[68:69], v[68:69], v[94:95]
	v_pk_add_f32 v[66:67], v[66:67], v[88:89]
	v_pk_add_f32 v[64:65], v[64:65], v[96:97]
	v_mul_f32_e32 v82, v77, v77
	v_mul_f32_e32 v83, v79, v79
	v_mul_f32_e32 v84, v73, v73
	v_mul_f32_e32 v85, v75, v75
	v_mul_f32_e32 v86, v69, v69
	v_mul_f32_e32 v87, v71, v71
	v_mul_f32_e32 v88, v65, v65
	v_mul_f32_e32 v89, v67, v67
	v_fmac_f32_e32 v82, v76, v76
	v_fmac_f32_e32 v83, v78, v78
	v_fmac_f32_e32 v84, v72, v72
	v_fmac_f32_e32 v85, v74, v74
	v_fmac_f32_e32 v86, v68, v68
	v_fmac_f32_e32 v87, v70, v70
	v_fmac_f32_e32 v88, v64, v64
	v_fmac_f32_e32 v89, v66, v66
	v_add_f32_e32 v82, v82, v83
	v_add_f32_e32 v83, v84, v85
	v_add_f32_e32 v84, v86, v87
	v_add_f32_e32 v85, v88, v89
	v_add_f32_e32 v82, v82, v83
	v_add_f32_e32 v83, v84, v85
	v_add_f32_e32 v82, v82, v83
	ds_bpermute_b32 v83, v156, v82
	s_waitcnt lgkmcnt(0)
	v_add_f32_e32 v82, v82, v83
	ds_bpermute_b32 v83, v157, v82
	s_and_saveexec_b64 s[20:21], s[2:3]
	s_cbranch_execz .LBB0_1029
	v_lshlrev_b64 v[80:81], 6, v[80:81]
	v_lshl_add_u64 v[80:81], s[82:83], 0, v[80:81]
	v_lshl_add_u64 v[80:81], s[0:1], 2, v[80:81]
	s_lshl_b32 s14, s63, 2
	v_lshl_add_u64 v[80:81], v[80:81], 0, s[14:15]
	s_waitcnt lgkmcnt(0)
	v_add_f32_e32 v82, v82, v83
	global_store_dword v[80:81], v82, off
.LBB0_1029:
	s_or_b64 exec, exec, s[20:21]
	v_cvt_pk_bf16_f32 v72, v72, v73
	v_cvt_pk_bf16_f32 v68, v68, v69
	v_cvt_pk_bf16_f32 v69, v70, v71
	v_cvt_pk_bf16_f32 v70, v64, v65
	v_cvt_pk_bf16_f32 v76, v76, v77
	v_cvt_pk_bf16_f32 v77, v78, v79
	v_cvt_pk_bf16_f32 v73, v74, v75
	v_cvt_pk_bf16_f32 v71, v66, v67
	v_cndmask_b32_e64 v65, v72, v70, s[4:5]
	v_mov_b32_e32 v78, v137
	v_cndmask_b32_e64 v64, v73, v71, s[4:5]
	v_cndmask_b32_e64 v66, v77, v69, s[4:5]
	v_mov_b32_e32 v75, v137
	v_mov_b32_dpp v78, v65 row_ror:8 row_mask:0xf bank_mask:0xf
	v_mov_b32_e32 v79, v137
	v_cndmask_b32_e64 v67, v76, v68, s[4:5]
	v_mov_b32_e32 v74, v137
	v_mov_b32_dpp v75, v66 row_ror:8 row_mask:0xf bank_mask:0xf
	v_mov_b32_dpp v79, v64 row_ror:8 row_mask:0xf bank_mask:0xf
	v_cndmask_b32_e64 v66, v78, v72, s[4:5]
	v_or_b32_e32 v72, s23, v149
	v_mov_b32_dpp v74, v67 row_ror:8 row_mask:0xf bank_mask:0xf
	v_cndmask_b32_e64 v67, v79, v73, s[4:5]
	v_ashrrev_i32_e32 v73, 31, v72
	v_lshlrev_b64 v[72:73], 11, v[72:73]
	v_lshl_add_u64 v[72:73], s[30:31], 0, v[72:73]
	v_lshl_add_u64 v[72:73], v[72:73], 0, v[112:113]
	v_cndmask_b32_e64 v65, v75, v77, s[4:5]
	v_cndmask_b32_e64 v64, v74, v76, s[4:5]
	v_lshl_add_u64 v[72:73], v[72:73], 0, v[136:137]
	global_store_dwordx4 v[72:73], v[64:67], off nt
	v_cndmask_b32_e64 v71, v71, v79, s[4:5]
	v_cndmask_b32_e64 v70, v70, v78, s[4:5]
	v_add_co_u32_e32 v64, vcc, s62, v72
	v_cndmask_b32_e64 v69, v69, v75, s[4:5]
	v_cndmask_b32_e64 v68, v68, v74, s[4:5]
	v_addc_co_u32_e32 v65, vcc, 0, v73, vcc
	s_add_i32 s23, s22, 0x80
	global_store_dwordx4 v[64:65], v[68:71], off nt
	v_or_b32_e32 v64, s23, v146
	v_ashrrev_i32_e32 v65, 31, v64
	v_lshlrev_b64 v[66:67], 11, v[64:65]
	v_lshl_add_u64 v[66:67], s[30:31], 0, v[66:67]
	v_lshl_add_u64 v[70:71], v[66:67], 0, v[112:113]
	s_waitcnt vmcnt(18)
	v_mov_b32_e32 v66, v204
	v_mov_b32_e32 v67, v205
	v_mov_b32_e32 v68, v206
	v_mov_b32_e32 v69, v207
	v_mov_b32_e32 v70, v208
	v_mov_b32_e32 v71, v209
	v_mov_b32_e32 v72, v210
	v_mov_b32_e32 v73, v211
	v_lshlrev_b32_e32 v74, 16, v66
	v_and_b32_e32 v75, 0xffff0000, v66
	v_lshlrev_b32_e32 v66, 16, v67
	v_and_b32_e32 v67, 0xffff0000, v67
	v_lshlrev_b32_e32 v76, 16, v68
	v_and_b32_e32 v77, 0xffff0000, v68
	v_lshlrev_b32_e32 v68, 16, v69
	v_and_b32_e32 v69, 0xffff0000, v69
	v_lshlrev_b32_e32 v78, 16, v70
	v_and_b32_e32 v79, 0xffff0000, v70
	v_lshlrev_b32_e32 v70, 16, v71
	v_and_b32_e32 v71, 0xffff0000, v71
	v_lshlrev_b32_e32 v80, 16, v72
	v_and_b32_e32 v81, 0xffff0000, v72
	v_lshlrev_b32_e32 v72, 16, v73
	v_and_b32_e32 v73, 0xffff0000, v73
	v_pk_add_f32 v[62:63], v[62:63], v[66:67]
	v_pk_add_f32 v[60:61], v[60:61], v[74:75]
	v_pk_add_f32 v[58:59], v[58:59], v[68:69]
	v_pk_add_f32 v[56:57], v[56:57], v[76:77]
	v_pk_add_f32 v[54:55], v[54:55], v[70:71]
	v_pk_add_f32 v[52:53], v[52:53], v[78:79]
	v_pk_add_f32 v[50:51], v[50:51], v[72:73]
	v_pk_add_f32 v[48:49], v[48:49], v[80:81]
	v_mul_f32_e32 v66, v61, v61
	v_mul_f32_e32 v67, v63, v63
	v_mul_f32_e32 v68, v57, v57
	v_mul_f32_e32 v69, v59, v59
	v_mul_f32_e32 v70, v53, v53
	v_mul_f32_e32 v71, v55, v55
	v_mul_f32_e32 v72, v49, v49
	v_mul_f32_e32 v73, v51, v51
	v_fmac_f32_e32 v66, v60, v60
	v_fmac_f32_e32 v67, v62, v62
	v_fmac_f32_e32 v68, v56, v56
	v_fmac_f32_e32 v69, v58, v58
	v_fmac_f32_e32 v70, v52, v52
	v_fmac_f32_e32 v71, v54, v54
	v_fmac_f32_e32 v72, v48, v48
	v_fmac_f32_e32 v73, v50, v50
	v_add_f32_e32 v66, v66, v67
	v_add_f32_e32 v67, v68, v69
	v_add_f32_e32 v68, v70, v71
	v_add_f32_e32 v69, v72, v73
	v_add_f32_e32 v66, v66, v67
	v_add_f32_e32 v67, v68, v69
	v_add_f32_e32 v66, v66, v67
	ds_bpermute_b32 v67, v156, v66
	s_waitcnt lgkmcnt(0)
	v_add_f32_e32 v66, v66, v67
	ds_bpermute_b32 v67, v157, v66
	s_and_saveexec_b64 s[20:21], s[2:3]
	s_cbranch_execz .LBB0_1031
	v_lshlrev_b64 v[64:65], 6, v[64:65]
	v_lshl_add_u64 v[64:65], s[82:83], 0, v[64:65]
	v_lshl_add_u64 v[64:65], s[0:1], 2, v[64:65]
	s_lshl_b32 s14, s63, 2
	v_lshl_add_u64 v[64:65], v[64:65], 0, s[14:15]
	s_waitcnt lgkmcnt(0)
	v_add_f32_e32 v66, v66, v67
	global_store_dword v[64:65], v66, off
; __device__ __forceinline__ unsigned swap8(unsigned v) { return (unsigned)__builtin_amdgcn_update_dpp(0, (int)v, 0x128  , 0xF, 0xF, false); }
; __device__ __forceinline__ void wide_store(bf16_t* O, int ldc, int rowg  , int col0  , int fr, u32x4 w0, u32x4 w1) {
;     const bool lo = fr < 8;
;     u32x4 snd = lo ? w1 : w0, rcv;
;     rcv.x = swap8(snd.x); rcv.y = swap8(snd.y); rcv.z = swap8(snd.z); rcv.w = swap8(snd.w);
;     const u32x4 first = lo ? w0 : rcv, second = lo ? rcv : w1;
;     bf16_t* p = O + (size_t)(rowg + (fr & 7)) * ldc + col0 + (lo ? 0 : 32);
;     __builtin_nontemporal_store(first, (u32x4*)p); __builtin_nontemporal_store(second, (u32x4*)(p + (size_t)8 * ldc));
;     __device__ __forceinline__ void operator()(const f32x4 (&acc)[2][2][4][2], const Unit& u, int wr, int wc, int fr, int fq) const {
;     ...
;             for (int m = 0; m < 4; ++m) { const int rowg = u.pm * BM + ai * HALF + wr * 64 + m * 16, row = rowg + fr; const size_t off = (size_t)row * 1024 + col0;
;                 u32x4 w[2]; float ss = 0.f;
; #pragma unroll
;                 for (int bj = 0; bj < 2; ++bj) { f32x4 b0, b1;
;                     if (BASE_F32) { const float* bp = (const float*)base + off + 32 * bj; b0 = *(const f32x4*)bp; b1 = *(const f32x4*)(bp + 4); }
;                     else { const u32x4 bb = *(const u32x4*)((const bf16_t*)base + off + 32 * bj);
;                         b0 = (f32x4){__uint_as_float(bb.x << 16), __uint_as_float(bb.x & 0xffff0000u), __uint_as_float(bb.y << 16), __uint_as_float(bb.y & 0xffff0000u)};
;                         b1 = (f32x4){__uint_as_float(bb.z << 16), __uint_as_float(bb.z & 0xffff0000u), __uint_as_float(bb.w << 16), __uint_as_float(bb.w & 0xffff0000u)}; }
;                     const f32x4 o0 = b0 + acc[ai][bj][m][0], o1 = b1 + acc[ai][bj][m][1];
;                     ss += ((o0[0] * o0[0] + o0[1] * o0[1]) + (o0[2] * o0[2] + o0[3] * o0[3])) + ((o1[0] * o1[0] + o1[1] * o1[1]) + (o1[2] * o1[2] + o1[3] * o1[3]));
;                     w[bj].x = cvt_pk_bf16(o0[0], o0[1]); w[bj].y = cvt_pk_bf16(o0[2], o0[3]); w[bj].z = cvt_pk_bf16(o1[0], o1[1]); w[bj].w = cvt_pk_bf16(o1[2], o1[3]); }
;                 ss += __shfl_xor(ss, 16); ss += __shfl_xor(ss, 32); if (fq == 0) slots[(size_t)row * 16 + u.pn * 4 + wc] = ss;
;                 wide_store(xb, 1024, rowg, col0, fr, w[0], w[1]);
.LBB0_1031:
	s_or_b64 exec, exec, s[20:21]
	v_cvt_pk_bf16_f32 v56, v56, v57
	v_cvt_pk_bf16_f32 v52, v52, v53
	v_cvt_pk_bf16_f32 v53, v54, v55
	v_cvt_pk_bf16_f32 v54, v48, v49
	v_cvt_pk_bf16_f32 v60, v60, v61
	v_cvt_pk_bf16_f32 v61, v62, v63
	v_cvt_pk_bf16_f32 v57, v58, v59
	v_cvt_pk_bf16_f32 v55, v50, v51
	v_cndmask_b32_e64 v49, v56, v54, s[4:5]
	v_mov_b32_e32 v62, v137
	v_cndmask_b32_e64 v48, v57, v55, s[4:5]
	v_cndmask_b32_e64 v50, v61, v53, s[4:5]
	v_mov_b32_e32 v59, v137
	v_mov_b32_dpp v62, v49 row_ror:8 row_mask:0xf bank_mask:0xf
	v_mov_b32_e32 v63, v137
	v_cndmask_b32_e64 v51, v60, v52, s[4:5]
	v_mov_b32_e32 v58, v137
	v_mov_b32_dpp v59, v50 row_ror:8 row_mask:0xf bank_mask:0xf
	v_mov_b32_dpp v63, v48 row_ror:8 row_mask:0xf bank_mask:0xf
	v_cndmask_b32_e64 v50, v62, v56, s[4:5]
	v_or_b32_e32 v56, s23, v149
	v_mov_b32_dpp v58, v51 row_ror:8 row_mask:0xf bank_mask:0xf
	v_cndmask_b32_e64 v51, v63, v57, s[4:5]
	v_ashrrev_i32_e32 v57, 31, v56
	v_lshlrev_b64 v[56:57], 11, v[56:57]
	v_lshl_add_u64 v[56:57], s[30:31], 0, v[56:57]
	v_lshl_add_u64 v[56:57], v[56:57], 0, v[112:113]
	v_cndmask_b32_e64 v49, v59, v61, s[4:5]
	v_cndmask_b32_e64 v48, v58, v60, s[4:5]
	v_lshl_add_u64 v[56:57], v[56:57], 0, v[136:137]
	global_store_dwordx4 v[56:57], v[48:51], off nt
	v_cndmask_b32_e64 v55, v55, v63, s[4:5]
	v_cndmask_b32_e64 v54, v54, v62, s[4:5]
	v_add_co_u32_e32 v48, vcc, s62, v56
	v_cndmask_b32_e64 v53, v53, v59, s[4:5]
	v_cndmask_b32_e64 v52, v52, v58, s[4:5]
	v_addc_co_u32_e32 v49, vcc, 0, v57, vcc
	s_add_i32 s23, s22, 0x90
	global_store_dwordx4 v[48:49], v[52:55], off nt
	v_or_b32_e32 v48, s23, v146
	v_ashrrev_i32_e32 v49, 31, v48
	v_lshlrev_b64 v[50:51], 11, v[48:49]
	v_lshl_add_u64 v[50:51], s[30:31], 0, v[50:51]
	v_lshl_add_u64 v[54:55], v[50:51], 0, v[112:113]
	s_waitcnt vmcnt(19)
	v_mov_b32_e32 v50, v212
	v_mov_b32_e32 v51, v213
	v_mov_b32_e32 v52, v214
	v_mov_b32_e32 v53, v215
	v_mov_b32_e32 v54, v216
	v_mov_b32_e32 v55, v217
	v_mov_b32_e32 v56, v218
	v_mov_b32_e32 v57, v219
	v_lshlrev_b32_e32 v58, 16, v50
	v_and_b32_e32 v59, 0xffff0000, v50
	v_lshlrev_b32_e32 v50, 16, v51
	v_and_b32_e32 v51, 0xffff0000, v51
	v_lshlrev_b32_e32 v60, 16, v52
	v_and_b32_e32 v61, 0xffff0000, v52
	v_lshlrev_b32_e32 v52, 16, v53
	v_and_b32_e32 v53, 0xffff0000, v53
	v_lshlrev_b32_e32 v62, 16, v54
	v_and_b32_e32 v63, 0xffff0000, v54
	v_lshlrev_b32_e32 v54, 16, v55
	v_and_b32_e32 v55, 0xffff0000, v55
	v_lshlrev_b32_e32 v64, 16, v56
	v_and_b32_e32 v65, 0xffff0000, v56
	v_lshlrev_b32_e32 v56, 16, v57
	v_and_b32_e32 v57, 0xffff0000, v57
	v_pk_add_f32 v[46:47], v[46:47], v[50:51]
	v_pk_add_f32 v[44:45], v[44:45], v[58:59]
	v_pk_add_f32 v[42:43], v[42:43], v[52:53]
	v_pk_add_f32 v[40:41], v[40:41], v[60:61]
	v_pk_add_f32 v[38:39], v[38:39], v[54:55]
	v_pk_add_f32 v[36:37], v[36:37], v[62:63]
	v_pk_add_f32 v[34:35], v[34:35], v[56:57]
	v_pk_add_f32 v[32:33], v[32:33], v[64:65]
	v_mul_f32_e32 v50, v45, v45
	v_mul_f32_e32 v51, v47, v47
	v_mul_f32_e32 v52, v41, v41
	v_mul_f32_e32 v53, v43, v43
	v_mul_f32_e32 v54, v37, v37
	v_mul_f32_e32 v55, v39, v39
	v_mul_f32_e32 v56, v33, v33
	v_mul_f32_e32 v57, v35, v35
	v_fmac_f32_e32 v50, v44, v44
	v_fmac_f32_e32 v51, v46, v46
	v_fmac_f32_e32 v52, v40, v40
	v_fmac_f32_e32 v53, v42, v42
	v_fmac_f32_e32 v54, v36, v36
	v_fmac_f32_e32 v55, v38, v38
	v_fmac_f32_e32 v56, v32, v32
	v_fmac_f32_e32 v57, v34, v34
	v_add_f32_e32 v50, v50, v51
	v_add_f32_e32 v51, v52, v53
	v_add_f32_e32 v52, v54, v55
	v_add_f32_e32 v53, v56, v57
	v_add_f32_e32 v50, v50, v51
	v_add_f32_e32 v51, v52, v53
	v_add_f32_e32 v50, v50, v51
	ds_bpermute_b32 v51, v156, v50
	s_waitcnt lgkmcnt(0)
	v_add_f32_e32 v50, v50, v51
	ds_bpermute_b32 v51, v157, v50
	s_and_saveexec_b64 s[20:21], s[2:3]
	s_cbranch_execz .LBB0_1033
	v_lshlrev_b64 v[48:49], 6, v[48:49]
	v_lshl_add_u64 v[48:49], s[82:83], 0, v[48:49]
	v_lshl_add_u64 v[48:49], s[0:1], 2, v[48:49]
	s_lshl_b32 s14, s63, 2
	v_lshl_add_u64 v[48:49], v[48:49], 0, s[14:15]
	s_waitcnt lgkmcnt(0)
	v_add_f32_e32 v50, v50, v51
	global_store_dword v[48:49], v50, off
.LBB0_1033:
	s_or_b64 exec, exec, s[20:21]
	v_cvt_pk_bf16_f32 v40, v40, v41
	v_cvt_pk_bf16_f32 v36, v36, v37
	v_cvt_pk_bf16_f32 v37, v38, v39
	v_cvt_pk_bf16_f32 v38, v32, v33
	v_cvt_pk_bf16_f32 v44, v44, v45
	v_cvt_pk_bf16_f32 v45, v46, v47
	v_cvt_pk_bf16_f32 v41, v42, v43
	v_cvt_pk_bf16_f32 v39, v34, v35
	v_cndmask_b32_e64 v33, v40, v38, s[4:5]
	v_mov_b32_e32 v46, v137
	v_cndmask_b32_e64 v32, v41, v39, s[4:5]
	v_cndmask_b32_e64 v34, v45, v37, s[4:5]
	v_mov_b32_e32 v43, v137
	v_mov_b32_dpp v46, v33 row_ror:8 row_mask:0xf bank_mask:0xf
	v_mov_b32_e32 v47, v137
	v_cndmask_b32_e64 v35, v44, v36, s[4:5]
	v_mov_b32_e32 v42, v137
	v_mov_b32_dpp v43, v34 row_ror:8 row_mask:0xf bank_mask:0xf
	v_mov_b32_dpp v47, v32 row_ror:8 row_mask:0xf bank_mask:0xf
	v_cndmask_b32_e64 v34, v46, v40, s[4:5]
	v_or_b32_e32 v40, s23, v149
	v_mov_b32_dpp v42, v35 row_ror:8 row_mask:0xf bank_mask:0xf
	v_cndmask_b32_e64 v35, v47, v41, s[4:5]
	v_ashrrev_i32_e32 v41, 31, v40
	v_lshlrev_b64 v[40:41], 11, v[40:41]
	v_lshl_add_u64 v[40:41], s[30:31], 0, v[40:41]
	v_lshl_add_u64 v[40:41], v[40:41], 0, v[112:113]
	v_cndmask_b32_e64 v33, v43, v45, s[4:5]
	v_cndmask_b32_e64 v32, v42, v44, s[4:5]
	v_lshl_add_u64 v[40:41], v[40:41], 0, v[136:137]
	global_store_dwordx4 v[40:41], v[32:35], off nt
	v_cndmask_b32_e64 v39, v39, v47, s[4:5]
	v_cndmask_b32_e64 v38, v38, v46, s[4:5]
	v_add_co_u32_e32 v32, vcc, s62, v40
	v_cndmask_b32_e64 v37, v37, v43, s[4:5]
	v_cndmask_b32_e64 v36, v36, v42, s[4:5]
	v_addc_co_u32_e32 v33, vcc, 0, v41, vcc
	s_add_i32 s23, s22, 0xa0
	global_store_dwordx4 v[32:33], v[36:39], off nt
	v_or_b32_e32 v32, s23, v146
	v_ashrrev_i32_e32 v33, 31, v32
	v_lshlrev_b64 v[34:35], 11, v[32:33]
	v_lshl_add_u64 v[34:35], s[30:31], 0, v[34:35]
	v_lshl_add_u64 v[38:39], v[34:35], 0, v[112:113]
	s_waitcnt vmcnt(20)
; __device__ __forceinline__ unsigned swap8(unsigned v) { return (unsigned)__builtin_amdgcn_update_dpp(0, (int)v, 0x128  , 0xF, 0xF, false); }
; __device__ __forceinline__ void wide_store(bf16_t* O, int ldc, int rowg  , int col0  , int fr, u32x4 w0, u32x4 w1) {
;     const bool lo = fr < 8;
;     u32x4 snd = lo ? w1 : w0, rcv;
;     rcv.x = swap8(snd.x); rcv.y = swap8(snd.y); rcv.z = swap8(snd.z); rcv.w = swap8(snd.w);
;     const u32x4 first = lo ? w0 : rcv, second = lo ? rcv : w1;
;     bf16_t* p = O + (size_t)(rowg + (fr & 7)) * ldc + col0 + (lo ? 0 : 32);
;     __builtin_nontemporal_store(first, (u32x4*)p); __builtin_nontemporal_store(second, (u32x4*)(p + (size_t)8 * ldc));
;     __device__ __forceinline__ void operator()(const f32x4 (&acc)[2][2][4][2], const Unit& u, int wr, int wc, int fr, int fq) const {
;     ...
;             for (int m = 0; m < 4; ++m) { const int rowg = u.pm * BM + ai * HALF + wr * 64 + m * 16, row = rowg + fr; const size_t off = (size_t)row * 1024 + col0;
;                 u32x4 w[2]; float ss = 0.f;
; #pragma unroll
;                 for (int bj = 0; bj < 2; ++bj) { f32x4 b0, b1;
;                     if (BASE_F32) { const float* bp = (const float*)base + off + 32 * bj; b0 = *(const f32x4*)bp; b1 = *(const f32x4*)(bp + 4); }
;                     else { const u32x4 bb = *(const u32x4*)((const bf16_t*)base + off + 32 * bj);
;                         b0 = (f32x4){__uint_as_float(bb.x << 16), __uint_as_float(bb.x & 0xffff0000u), __uint_as_float(bb.y << 16), __uint_as_float(bb.y & 0xffff0000u)};
;                         b1 = (f32x4){__uint_as_float(bb.z << 16), __uint_as_float(bb.z & 0xffff0000u), __uint_as_float(bb.w << 16), __uint_as_float(bb.w & 0xffff0000u)}; }
;                     const f32x4 o0 = b0 + acc[ai][bj][m][0], o1 = b1 + acc[ai][bj][m][1];
;                     ss += ((o0[0] * o0[0] + o0[1] * o0[1]) + (o0[2] * o0[2] + o0[3] * o0[3])) + ((o1[0] * o1[0] + o1[1] * o1[1]) + (o1[2] * o1[2] + o1[3] * o1[3]));
;                     w[bj].x = cvt_pk_bf16(o0[0], o0[1]); w[bj].y = cvt_pk_bf16(o0[2], o0[3]); w[bj].z = cvt_pk_bf16(o1[0], o1[1]); w[bj].w = cvt_pk_bf16(o1[2], o1[3]); }
;                 ss += __shfl_xor(ss, 16); ss += __shfl_xor(ss, 32); if (fq == 0) slots[(size_t)row * 16 + u.pn * 4 + wc] = ss;
;                 wide_store(xb, 1024, rowg, col0, fr, w[0], w[1]);
	v_mov_b32_e32 v34, v220
	v_mov_b32_e32 v35, v221
	v_mov_b32_e32 v36, v222
	v_mov_b32_e32 v37, v223
	v_mov_b32_e32 v38, v224
	v_mov_b32_e32 v39, v225
	v_mov_b32_e32 v40, v226
	v_mov_b32_e32 v41, v227
	v_lshlrev_b32_e32 v42, 16, v34
	v_and_b32_e32 v43, 0xffff0000, v34
	v_lshlrev_b32_e32 v34, 16, v35
	v_and_b32_e32 v35, 0xffff0000, v35
	v_lshlrev_b32_e32 v44, 16, v36
	v_and_b32_e32 v45, 0xffff0000, v36
	v_lshlrev_b32_e32 v36, 16, v37
	v_and_b32_e32 v37, 0xffff0000, v37
	v_lshlrev_b32_e32 v46, 16, v38
	v_and_b32_e32 v47, 0xffff0000, v38
	v_lshlrev_b32_e32 v38, 16, v39
	v_and_b32_e32 v39, 0xffff0000, v39
	v_lshlrev_b32_e32 v48, 16, v40
	v_and_b32_e32 v49, 0xffff0000, v40
	v_lshlrev_b32_e32 v40, 16, v41
	v_and_b32_e32 v41, 0xffff0000, v41
	v_pk_add_f32 v[30:31], v[30:31], v[34:35]
	v_pk_add_f32 v[28:29], v[28:29], v[42:43]
	v_pk_add_f32 v[26:27], v[26:27], v[36:37]
	v_pk_add_f32 v[24:25], v[24:25], v[44:45]
	v_pk_add_f32 v[22:23], v[22:23], v[38:39]
	v_pk_add_f32 v[20:21], v[20:21], v[46:47]
	v_pk_add_f32 v[18:19], v[18:19], v[40:41]
	v_pk_add_f32 v[16:17], v[16:17], v[48:49]
	v_mul_f32_e32 v34, v29, v29
	v_mul_f32_e32 v35, v31, v31
	v_mul_f32_e32 v36, v25, v25
	v_mul_f32_e32 v37, v27, v27
	v_mul_f32_e32 v38, v21, v21
	v_mul_f32_e32 v39, v23, v23
	v_mul_f32_e32 v40, v17, v17
	v_mul_f32_e32 v41, v19, v19
	v_fmac_f32_e32 v34, v28, v28
	v_fmac_f32_e32 v35, v30, v30
	v_fmac_f32_e32 v36, v24, v24
	v_fmac_f32_e32 v37, v26, v26
	v_fmac_f32_e32 v38, v20, v20
	v_fmac_f32_e32 v39, v22, v22
	v_fmac_f32_e32 v40, v16, v16
	v_fmac_f32_e32 v41, v18, v18
	v_add_f32_e32 v34, v34, v35
	v_add_f32_e32 v35, v36, v37
	v_add_f32_e32 v36, v38, v39
	v_add_f32_e32 v37, v40, v41
	v_add_f32_e32 v34, v34, v35
	v_add_f32_e32 v35, v36, v37
	v_add_f32_e32 v34, v34, v35
	ds_bpermute_b32 v35, v156, v34
	s_waitcnt lgkmcnt(0)
	v_add_f32_e32 v34, v34, v35
	ds_bpermute_b32 v35, v157, v34
	s_and_saveexec_b64 s[20:21], s[2:3]
	s_cbranch_execz .LBB0_1035
	v_lshlrev_b64 v[32:33], 6, v[32:33]
	v_lshl_add_u64 v[32:33], s[82:83], 0, v[32:33]
	v_lshl_add_u64 v[32:33], s[0:1], 2, v[32:33]
	s_lshl_b32 s14, s63, 2
	v_lshl_add_u64 v[32:33], v[32:33], 0, s[14:15]
	s_waitcnt lgkmcnt(0)
	v_add_f32_e32 v34, v34, v35
	global_store_dword v[32:33], v34, off
.LBB0_1035:
	s_or_b64 exec, exec, s[20:21]
	v_cvt_pk_bf16_f32 v24, v24, v25
	v_cvt_pk_bf16_f32 v20, v20, v21
	v_cvt_pk_bf16_f32 v21, v22, v23
	v_cvt_pk_bf16_f32 v22, v16, v17
	v_cvt_pk_bf16_f32 v28, v28, v29
	v_cvt_pk_bf16_f32 v29, v30, v31
	v_cvt_pk_bf16_f32 v25, v26, v27
	v_cvt_pk_bf16_f32 v23, v18, v19
	v_cndmask_b32_e64 v17, v24, v22, s[4:5]
	v_mov_b32_e32 v30, v137
	v_cndmask_b32_e64 v16, v25, v23, s[4:5]
	v_cndmask_b32_e64 v18, v29, v21, s[4:5]
	v_mov_b32_e32 v27, v137
	v_mov_b32_dpp v30, v17 row_ror:8 row_mask:0xf bank_mask:0xf
	v_mov_b32_e32 v31, v137
	v_cndmask_b32_e64 v19, v28, v20, s[4:5]
	v_mov_b32_e32 v26, v137
	v_mov_b32_dpp v27, v18 row_ror:8 row_mask:0xf bank_mask:0xf
	v_mov_b32_dpp v31, v16 row_ror:8 row_mask:0xf bank_mask:0xf
	v_cndmask_b32_e64 v18, v30, v24, s[4:5]
	v_or_b32_e32 v24, s23, v149
	v_mov_b32_dpp v26, v19 row_ror:8 row_mask:0xf bank_mask:0xf
	v_cndmask_b32_e64 v19, v31, v25, s[4:5]
	v_ashrrev_i32_e32 v25, 31, v24
	v_lshlrev_b64 v[24:25], 11, v[24:25]
	v_lshl_add_u64 v[24:25], s[30:31], 0, v[24:25]
	v_lshl_add_u64 v[24:25], v[24:25], 0, v[112:113]
	v_cndmask_b32_e64 v17, v27, v29, s[4:5]
	v_cndmask_b32_e64 v16, v26, v28, s[4:5]
	v_lshl_add_u64 v[24:25], v[24:25], 0, v[136:137]
	global_store_dwordx4 v[24:25], v[16:19], off nt
	v_cndmask_b32_e64 v23, v23, v31, s[4:5]
	v_cndmask_b32_e64 v22, v22, v30, s[4:5]
	v_add_co_u32_e32 v16, vcc, s62, v24
	v_cndmask_b32_e64 v21, v21, v27, s[4:5]
	v_cndmask_b32_e64 v20, v20, v26, s[4:5]
	v_addc_co_u32_e32 v17, vcc, 0, v25, vcc
	s_addk_i32 s22, 0xb0
	global_store_dwordx4 v[16:17], v[20:23], off nt
	v_or_b32_e32 v16, s22, v146
	v_ashrrev_i32_e32 v17, 31, v16
	v_lshlrev_b64 v[18:19], 11, v[16:17]
	v_lshl_add_u64 v[18:19], s[30:31], 0, v[18:19]
	v_lshl_add_u64 v[22:23], v[18:19], 0, v[112:113]
	s_waitcnt vmcnt(21)
	v_mov_b32_e32 v18, v228
	v_mov_b32_e32 v19, v229
	v_mov_b32_e32 v20, v230
	v_mov_b32_e32 v21, v231
	v_mov_b32_e32 v22, v232
	v_mov_b32_e32 v23, v233
	v_mov_b32_e32 v24, v234
	v_mov_b32_e32 v25, v235
	v_lshlrev_b32_e32 v26, 16, v18
	v_and_b32_e32 v27, 0xffff0000, v18
	v_lshlrev_b32_e32 v18, 16, v19
	v_and_b32_e32 v19, 0xffff0000, v19
	v_lshlrev_b32_e32 v28, 16, v20
	v_and_b32_e32 v29, 0xffff0000, v20
	v_lshlrev_b32_e32 v20, 16, v21
	v_and_b32_e32 v21, 0xffff0000, v21
	v_lshlrev_b32_e32 v30, 16, v22
	v_and_b32_e32 v31, 0xffff0000, v22
	v_lshlrev_b32_e32 v22, 16, v23
	v_and_b32_e32 v23, 0xffff0000, v23
	v_lshlrev_b32_e32 v32, 16, v24
	v_and_b32_e32 v33, 0xffff0000, v24
	v_lshlrev_b32_e32 v24, 16, v25
	v_and_b32_e32 v25, 0xffff0000, v25
	v_pk_add_f32 v[14:15], v[14:15], v[18:19]
	v_pk_add_f32 v[12:13], v[12:13], v[26:27]
	v_pk_add_f32 v[10:11], v[10:11], v[20:21]
	v_pk_add_f32 v[8:9], v[8:9], v[28:29]
	v_pk_add_f32 v[6:7], v[6:7], v[22:23]
	v_pk_add_f32 v[4:5], v[4:5], v[30:31]
	v_pk_add_f32 v[2:3], v[2:3], v[24:25]
	v_pk_add_f32 v[0:1], v[0:1], v[32:33]
	v_mul_f32_e32 v18, v13, v13
	v_mul_f32_e32 v19, v15, v15
	v_mul_f32_e32 v20, v9, v9
	v_mul_f32_e32 v21, v11, v11
	v_mul_f32_e32 v22, v5, v5
	v_mul_f32_e32 v23, v7, v7
	v_mul_f32_e32 v24, v1, v1
	v_mul_f32_e32 v25, v3, v3
	v_fmac_f32_e32 v18, v12, v12
	v_fmac_f32_e32 v19, v14, v14
	v_fmac_f32_e32 v20, v8, v8
	v_fmac_f32_e32 v21, v10, v10
	v_fmac_f32_e32 v22, v4, v4
	v_fmac_f32_e32 v23, v6, v6
	v_fmac_f32_e32 v24, v0, v0
	v_fmac_f32_e32 v25, v2, v2
	v_add_f32_e32 v18, v18, v19
	v_add_f32_e32 v19, v20, v21
	v_add_f32_e32 v20, v22, v23
	v_add_f32_e32 v21, v24, v25
	v_add_f32_e32 v18, v18, v19
	v_add_f32_e32 v19, v20, v21
	v_add_f32_e32 v18, v18, v19
	ds_bpermute_b32 v19, v156, v18
	s_waitcnt lgkmcnt(0)
	v_add_f32_e32 v18, v18, v19
	ds_bpermute_b32 v19, v157, v18
	s_and_saveexec_b64 s[20:21], s[2:3]
	s_cbranch_execz .LBB0_1037
	v_lshlrev_b64 v[16:17], 6, v[16:17]
	v_lshl_add_u64 v[16:17], s[82:83], 0, v[16:17]
	v_lshl_add_u64 v[16:17], s[0:1], 2, v[16:17]
	s_lshl_b32 s14, s63, 2
	v_lshl_add_u64 v[16:17], v[16:17], 0, s[14:15]
	s_waitcnt lgkmcnt(0)
	v_add_f32_e32 v18, v18, v19
	global_store_dword v[16:17], v18, off

; #define PG8_STAGE(bufoff, gbase, voff) do { _Pragma("unroll") for (int _i = 0; _i < 2; ++_i) \
;         __builtin_amdgcn_global_load_lds((const unsigned*)((const char*)(gbase) + (voff)[_i]), (PG8_LAS unsigned*)(lds + (bufoff) + ldsw + _i * 8192), 16, 0, PG8_LOAD_AUX); } while (0)
; #define PG8_LDA(dst, b, h) do { _Pragma("unroll") for (int m = 0; m < 4; ++m) _Pragma("unroll") for (int k = 0; k < 2; ++k) dst[m][k] = *(const PG8_LAS bf16x8*)(lds + PG8_SA(b, h) + aoff + m * 2048 + k * 1024); } while (0)
; #define PG8_LDB(dst, b, h) do { _Pragma("unroll") for (int n = 0; n < 2; ++n) _Pragma("unroll") for (int k = 0; k < 2; ++k) dst[n][k] = *(const PG8_LAS bf16x8*)(lds + PG8_SB(b, h) + boff + n * 2048 + k * 1024); } while (0)
; #define PG8_MMA(ai, bj, At, Bt) do { __builtin_amdgcn_s_setprio(1); _Pragma("unroll") for (int m = 0; m < 4; ++m) _Pragma("unroll") for (int n = 0; n < 2; ++n) _Pragma("unroll") for (int k = 0; k < 2; ++k) \
;         acc[ai][bj][m][n] = __builtin_amdgcn_mfma_f32_16x16x32_bf16(Bt[n][k], At[m][k], acc[ai][bj][m][n], 0, 0, 0); __builtin_amdgcn_s_setprio(0); } while (0)
; #define PG8_WAIT_V(n) asm volatile("s_waitcnt vmcnt(" #n ")" ::: "memory")
; #define PG8_BAR __builtin_amdgcn_s_barrier()
; template <class Epi, class Sched, bool ALIGN_EPI = false, bool SP2 = false>
; __device__ __forceinline__ void gemm_phase(PG8_LAS unsigned char* lds, const Gemm g, const Sched& S, const Epi& E) {
;     ...
;         for (int t = 0; t < nt; t += 2) {
;             const bool last = (t == nt - 2);
;             const char* a1 = cA + (size_t)(t + 1) * kstep;
;             const char* a2 = last ? nA : cA + (size_t)(t + 2) * kstep; const char* b2 = last ? nB : cB + (size_t)(t + 2) * kstep;
;             const char* a3 = a2 + kstep; const char* b3 = b2 + kstep;
;             if (last && has_next) S.a_ready(nxt);
;             if constexpr (SP2) {
;             PG8_LDB(B0, 0, 0); PG8_LDB(B1, 0, 1); PG8_SCHED; PG8_LDA(At, 0, 0); PG8_STAGE(PG8_SA(1, 1), a1 + hstepA, voffA);
;             PG8_WAIT_V(8); PG8_WAIT_L(0); PG8_BAR; PG8_MMA(0, 0, At, B0); PG8_MMA(0, 1, At, B1); PG8_BAR; PG8_SCHED;
;             PG8_LDA(At, 0, 1); PG8_STAGE(PG8_SB(0, 0), b2, voffB); PG8_STAGE(PG8_SB(0, 1), b2 + hstepB, voffB); PG8_STAGE(PG8_SA(0, 0), a2, voffA);
;             PG8_WAIT_V(8); PG8_WAIT_L(0); PG8_BAR; PG8_MMA(1, 0, At, B0); PG8_MMA(1, 1, At, B1); PG8_BAR; PG8_SCHED;
.LBB0_1196:
	ds_read_b128 v[146:149], v155
	ds_read_b128 v[160:163], v155 offset:1024
	ds_read_b128 v[164:167], v155 offset:2048
	ds_read_b128 v[168:171], v155 offset:3072
	ds_read_b128 v[172:175], v156
	ds_read_b128 v[176:179], v156 offset:1024
	ds_read_b128 v[180:183], v156 offset:2048
	ds_read_b128 v[184:187], v156 offset:3072
	s_add_u32 s20, s0, 0xfff50080
	s_addc_u32 s21, s1, -1
	s_cmp_eq_u32 s27, 40
	s_cselect_b32 s23, s9, s21
	s_cselect_b32 s22, s8, s20
	s_cselect_b32 s21, s41, s26
	s_cselect_b32 s20, s40, s25
	v_lshl_add_u64 v[220:221], s[0:1], 0, v[138:139]
	s_add_i32 m0, s43, 0xc000
	ds_read_b128 v[188:191], v157
	ds_read_b128 v[192:195], v157 offset:1024
	ds_read_b128 v[196:199], v157 offset:2048
	ds_read_b128 v[200:203], v157 offset:3072
	ds_read_b128 v[204:207], v157 offset:4096
	ds_read_b128 v[208:211], v157 offset:5120
	ds_read_b128 v[212:215], v157 offset:6144
	ds_read_b128 v[216:219], v157 offset:7168
	global_load_lds_dwordx4 v[220:221], off
	v_lshl_add_u64 v[220:221], s[0:1], 0, v[140:141]
	s_add_i32 m0, s43, 0xe000
	s_nop 0
	global_load_lds_dwordx4 v[220:221], off
	s_waitcnt vmcnt(8)
	s_waitcnt lgkmcnt(0)
	s_barrier
	s_setprio 1
	s_waitcnt lgkmcnt(0)
	v_mfma_f32_16x16x32_bf16 v[124:127], v[146:149], v[188:191], v[124:127]
	v_mfma_f32_16x16x32_bf16 v[120:123], v[164:167], v[188:191], v[120:123]
	v_mfma_f32_16x16x32_bf16 v[108:111], v[146:149], v[196:199], v[108:111]
	v_mfma_f32_16x16x32_bf16 v[104:107], v[164:167], v[196:199], v[104:107]
	v_mfma_f32_16x16x32_bf16 v[92:95], v[146:149], v[204:207], v[92:95]
	v_mfma_f32_16x16x32_bf16 v[88:91], v[164:167], v[204:207], v[88:91]
	v_mfma_f32_16x16x32_bf16 v[76:79], v[146:149], v[212:215], v[76:79]
	v_mfma_f32_16x16x32_bf16 v[72:75], v[164:167], v[212:215], v[72:75]
	v_mfma_f32_16x16x32_bf16 v[124:127], v[160:163], v[192:195], v[124:127]
	v_mfma_f32_16x16x32_bf16 v[120:123], v[168:171], v[192:195], v[120:123]
	v_mfma_f32_16x16x32_bf16 v[108:111], v[160:163], v[200:203], v[108:111]
	v_mfma_f32_16x16x32_bf16 v[104:107], v[168:171], v[200:203], v[104:107]
	v_mfma_f32_16x16x32_bf16 v[92:95], v[160:163], v[208:211], v[92:95]
	v_mfma_f32_16x16x32_bf16 v[88:91], v[168:171], v[208:211], v[88:91]
	v_mfma_f32_16x16x32_bf16 v[76:79], v[160:163], v[216:219], v[76:79]
	v_mfma_f32_16x16x32_bf16 v[72:75], v[168:171], v[216:219], v[72:75]
	s_setprio 0
	s_setprio 1
	v_mfma_f32_16x16x32_bf16 v[116:119], v[172:175], v[188:191], v[116:119]
	v_mfma_f32_16x16x32_bf16 v[112:115], v[180:183], v[188:191], v[112:115]
	v_mfma_f32_16x16x32_bf16 v[100:103], v[172:175], v[196:199], v[100:103]
	v_mfma_f32_16x16x32_bf16 v[96:99], v[180:183], v[196:199], v[96:99]
	v_mfma_f32_16x16x32_bf16 v[84:87], v[172:175], v[204:207], v[84:87]
	v_mfma_f32_16x16x32_bf16 v[80:83], v[180:183], v[204:207], v[80:83]
	v_mfma_f32_16x16x32_bf16 v[68:71], v[172:175], v[212:215], v[68:71]
	v_mfma_f32_16x16x32_bf16 v[64:67], v[180:183], v[212:215], v[64:67]
	v_mfma_f32_16x16x32_bf16 v[116:119], v[176:179], v[192:195], v[116:119]
	v_mfma_f32_16x16x32_bf16 v[112:115], v[184:187], v[192:195], v[112:115]
	v_mfma_f32_16x16x32_bf16 v[100:103], v[176:179], v[200:203], v[100:103]
	v_mfma_f32_16x16x32_bf16 v[96:99], v[184:187], v[200:203], v[96:99]
	v_mfma_f32_16x16x32_bf16 v[84:87], v[176:179], v[208:211], v[84:87]
	v_mfma_f32_16x16x32_bf16 v[80:83], v[184:187], v[208:211], v[80:83]
	v_mfma_f32_16x16x32_bf16 v[68:71], v[176:179], v[216:219], v[68:71]
	v_mfma_f32_16x16x32_bf16 v[64:67], v[184:187], v[216:219], v[64:67]
	s_setprio 0
	s_barrier
	s_add_i32 s28, s55, s42
	v_lshl_add_u64 v[220:221], s[20:21], 0, v[130:131]
	s_mov_b32 m0, s28
	ds_read_b128 v[188:191], v157 offset:16384
	ds_read_b128 v[192:195], v157 offset:17408
	ds_read_b128 v[196:199], v157 offset:18432
	ds_read_b128 v[200:203], v157 offset:19456
	ds_read_b128 v[204:207], v157 offset:20480
	ds_read_b128 v[208:211], v157 offset:21504
	ds_read_b128 v[212:215], v157 offset:22528
	ds_read_b128 v[216:219], v157 offset:23552
	global_load_lds_dwordx4 v[220:221], off
	s_add_i32 m0, s28, 0x2000
	s_add_u32 s28, s20, 0x2c000
	v_lshl_add_u64 v[222:223], s[20:21], 0, v[134:135]
	s_addc_u32 s29, s21, 0
	s_add_i32 s30, s56, s42
	global_load_lds_dwordx4 v[222:223], off
	v_lshl_add_u64 v[224:225], s[28:29], 0, v[130:131]
	s_mov_b32 m0, s30
	v_lshl_add_u64 v[226:227], s[22:23], 0, v[132:133]
	global_load_lds_dwordx4 v[224:225], off
	v_lshl_add_u64 v[224:225], s[28:29], 0, v[134:135]
	s_add_i32 m0, s30, 0x2000
	s_nop 0
	global_load_lds_dwordx4 v[224:225], off
	v_lshl_add_u64 v[224:225], s[22:23], 0, v[128:129]
	s_mov_b32 m0, s43
	s_nop 0
	global_load_lds_dwordx4 v[224:225], off
	s_mov_b32 m0, s44
	s_nop 0
	global_load_lds_dwordx4 v[226:227], off
	s_waitcnt vmcnt(8)
	s_waitcnt lgkmcnt(0)
	s_barrier
; #define PG8_STAGE(bufoff, gbase, voff) do { _Pragma("unroll") for (int _i = 0; _i < 2; ++_i) \
;         __builtin_amdgcn_global_load_lds((const unsigned*)((const char*)(gbase) + (voff)[_i]), (PG8_LAS unsigned*)(lds + (bufoff) + ldsw + _i * 8192), 16, 0, PG8_LOAD_AUX); } while (0)
; #define PG8_LDA(dst, b, h) do { _Pragma("unroll") for (int m = 0; m < 4; ++m) _Pragma("unroll") for (int k = 0; k < 2; ++k) dst[m][k] = *(const PG8_LAS bf16x8*)(lds + PG8_SA(b, h) + aoff + m * 2048 + k * 1024); } while (0)
; #define PG8_LDB(dst, b, h) do { _Pragma("unroll") for (int n = 0; n < 2; ++n) _Pragma("unroll") for (int k = 0; k < 2; ++k) dst[n][k] = *(const PG8_LAS bf16x8*)(lds + PG8_SB(b, h) + boff + n * 2048 + k * 1024); } while (0)
; #define PG8_MMA(ai, bj, At, Bt) do { __builtin_amdgcn_s_setprio(1); _Pragma("unroll") for (int m = 0; m < 4; ++m) _Pragma("unroll") for (int n = 0; n < 2; ++n) _Pragma("unroll") for (int k = 0; k < 2; ++k) \
;         acc[ai][bj][m][n] = __builtin_amdgcn_mfma_f32_16x16x32_bf16(Bt[n][k], At[m][k], acc[ai][bj][m][n], 0, 0, 0); __builtin_amdgcn_s_setprio(0); } while (0)
; #define PG8_WAIT_V(n) asm volatile("s_waitcnt vmcnt(" #n ")" ::: "memory")
; #define PG8_WAIT_L(n) asm volatile("s_waitcnt lgkmcnt(" #n ")" ::: "memory")
; #define PG8_BAR __builtin_amdgcn_s_barrier()
; #define PG8_SCHED __builtin_amdgcn_sched_barrier(0)
; template <class Epi, class Sched, bool ALIGN_EPI = false, bool SP2 = false>
; __device__ __forceinline__ void gemm_phase(PG8_LAS unsigned char* lds, const Gemm g, const Sched& S, const Epi& E) {
;     ...
;             PG8_WAIT_V(8); PG8_WAIT_L(0); PG8_BAR; PG8_MMA(1, 0, At, B0); PG8_MMA(1, 1, At, B1); PG8_BAR; PG8_SCHED;
;             PG8_LDB(B0, 1, 0); PG8_LDB(B1, 1, 1); PG8_SCHED; PG8_LDA(At, 1, 0); PG8_STAGE(PG8_SA(0, 1), a2 + hstepA, voffA);
;             PG8_WAIT_V(8); PG8_WAIT_L(0); PG8_BAR; PG8_MMA(0, 0, At, B0); PG8_MMA(0, 1, At, B1); PG8_BAR; PG8_SCHED;
;             PG8_LDA(At, 1, 1); PG8_STAGE(PG8_SB(1, 0), b3, voffB); PG8_STAGE(PG8_SB(1, 1), b3 + hstepB, voffB); PG8_STAGE(PG8_SA(1, 0), a3, voffA);
;             PG8_WAIT_V(8); PG8_WAIT_L(0); PG8_BAR; PG8_MMA(1, 0, At, B0); PG8_MMA(1, 1, At, B1); PG8_BAR; PG8_SCHED;
	s_setprio 1
	s_waitcnt lgkmcnt(0)
	v_mfma_f32_16x16x32_bf16 v[60:63], v[146:149], v[188:191], v[60:63]
	v_mfma_f32_16x16x32_bf16 v[56:59], v[164:167], v[188:191], v[56:59]
	v_mfma_f32_16x16x32_bf16 v[44:47], v[146:149], v[196:199], v[44:47]
	v_mfma_f32_16x16x32_bf16 v[40:43], v[164:167], v[196:199], v[40:43]
	v_mfma_f32_16x16x32_bf16 v[28:31], v[146:149], v[204:207], v[28:31]
	v_mfma_f32_16x16x32_bf16 v[24:27], v[164:167], v[204:207], v[24:27]
	v_mfma_f32_16x16x32_bf16 v[12:15], v[146:149], v[212:215], v[12:15]
	v_mfma_f32_16x16x32_bf16 v[8:11], v[164:167], v[212:215], v[8:11]
	v_mfma_f32_16x16x32_bf16 v[60:63], v[160:163], v[192:195], v[60:63]
	v_mfma_f32_16x16x32_bf16 v[56:59], v[168:171], v[192:195], v[56:59]
	v_mfma_f32_16x16x32_bf16 v[44:47], v[160:163], v[200:203], v[44:47]
	v_mfma_f32_16x16x32_bf16 v[40:43], v[168:171], v[200:203], v[40:43]
	v_mfma_f32_16x16x32_bf16 v[28:31], v[160:163], v[208:211], v[28:31]
	v_mfma_f32_16x16x32_bf16 v[24:27], v[168:171], v[208:211], v[24:27]
	v_mfma_f32_16x16x32_bf16 v[12:15], v[160:163], v[216:219], v[12:15]
	v_mfma_f32_16x16x32_bf16 v[8:11], v[168:171], v[216:219], v[8:11]
	s_setprio 0
	s_setprio 1
	v_mfma_f32_16x16x32_bf16 v[52:55], v[172:175], v[188:191], v[52:55]
	v_mfma_f32_16x16x32_bf16 v[48:51], v[180:183], v[188:191], v[48:51]
	v_mfma_f32_16x16x32_bf16 v[36:39], v[172:175], v[196:199], v[36:39]
	v_mfma_f32_16x16x32_bf16 v[32:35], v[180:183], v[196:199], v[32:35]
	v_mfma_f32_16x16x32_bf16 v[20:23], v[172:175], v[204:207], v[20:23]
	v_mfma_f32_16x16x32_bf16 v[16:19], v[180:183], v[204:207], v[16:19]
	v_mfma_f32_16x16x32_bf16 v[4:7], v[172:175], v[212:215], v[4:7]
	v_mfma_f32_16x16x32_bf16 v[0:3], v[180:183], v[212:215], v[0:3]
	v_mfma_f32_16x16x32_bf16 v[52:55], v[176:179], v[192:195], v[52:55]
	v_mfma_f32_16x16x32_bf16 v[48:51], v[184:187], v[192:195], v[48:51]
	v_mfma_f32_16x16x32_bf16 v[36:39], v[176:179], v[200:203], v[36:39]
	v_mfma_f32_16x16x32_bf16 v[32:35], v[184:187], v[200:203], v[32:35]
	v_mfma_f32_16x16x32_bf16 v[20:23], v[176:179], v[208:211], v[20:23]
	v_mfma_f32_16x16x32_bf16 v[16:19], v[184:187], v[208:211], v[16:19]
	v_mfma_f32_16x16x32_bf16 v[4:7], v[176:179], v[216:219], v[4:7]
	v_mfma_f32_16x16x32_bf16 v[0:3], v[184:187], v[216:219], v[0:3]
	s_setprio 0
	s_barrier
	s_add_i32 s28, 0, 0x18000
	v_add_u32_e32 v159, s28, v151
	s_add_i32 s29, 0, 0x1c000
	ds_read_b128 v[146:149], v159
	ds_read_b128 v[160:163], v159 offset:1024
	ds_read_b128 v[164:167], v159 offset:2048
	ds_read_b128 v[168:171], v159 offset:3072
	v_add_u32_e32 v159, s29, v151
	ds_read_b128 v[172:175], v159
	ds_read_b128 v[176:179], v159 offset:1024
	ds_read_b128 v[180:183], v159 offset:2048
	ds_read_b128 v[184:187], v159 offset:3072
	s_add_u32 s22, s22, 0xb0000
	s_addc_u32 s23, s23, 0
	s_mov_b32 m0, s45
	v_lshl_add_u64 v[228:229], s[22:23], 0, v[128:129]
	ds_read_b128 v[188:191], v157 offset:32768
	ds_read_b128 v[192:195], v157 offset:33792
	ds_read_b128 v[196:199], v157 offset:34816
	ds_read_b128 v[200:203], v157 offset:35840
	ds_read_b128 v[204:207], v157 offset:36864
	ds_read_b128 v[208:211], v157 offset:37888
	ds_read_b128 v[212:215], v157 offset:38912
	ds_read_b128 v[216:219], v157 offset:39936
	global_load_lds_dwordx4 v[228:229], off
	v_lshl_add_u64 v[228:229], s[22:23], 0, v[132:133]
	s_mov_b32 m0, s46
	s_nop 0
	global_load_lds_dwordx4 v[228:229], off
	s_waitcnt vmcnt(8)
	s_waitcnt lgkmcnt(0)
	s_barrier
	s_setprio 1
	s_waitcnt lgkmcnt(0)
	v_mfma_f32_16x16x32_bf16 v[124:127], v[146:149], v[188:191], v[124:127]
	v_mfma_f32_16x16x32_bf16 v[120:123], v[164:167], v[188:191], v[120:123]
	v_mfma_f32_16x16x32_bf16 v[108:111], v[146:149], v[196:199], v[108:111]
	v_mfma_f32_16x16x32_bf16 v[104:107], v[164:167], v[196:199], v[104:107]
	v_mfma_f32_16x16x32_bf16 v[92:95], v[146:149], v[204:207], v[92:95]
	v_mfma_f32_16x16x32_bf16 v[88:91], v[164:167], v[204:207], v[88:91]
	v_mfma_f32_16x16x32_bf16 v[76:79], v[146:149], v[212:215], v[76:79]
	v_mfma_f32_16x16x32_bf16 v[72:75], v[164:167], v[212:215], v[72:75]
	v_mfma_f32_16x16x32_bf16 v[124:127], v[160:163], v[192:195], v[124:127]
	v_mfma_f32_16x16x32_bf16 v[120:123], v[168:171], v[192:195], v[120:123]
	v_mfma_f32_16x16x32_bf16 v[108:111], v[160:163], v[200:203], v[108:111]
	v_mfma_f32_16x16x32_bf16 v[104:107], v[168:171], v[200:203], v[104:107]
	v_mfma_f32_16x16x32_bf16 v[92:95], v[160:163], v[208:211], v[92:95]
	v_mfma_f32_16x16x32_bf16 v[88:91], v[168:171], v[208:211], v[88:91]
	v_mfma_f32_16x16x32_bf16 v[76:79], v[160:163], v[216:219], v[76:79]
	v_mfma_f32_16x16x32_bf16 v[72:75], v[168:171], v[216:219], v[72:75]
	s_setprio 0
	s_setprio 1
	v_mfma_f32_16x16x32_bf16 v[116:119], v[172:175], v[188:191], v[116:119]
	v_mfma_f32_16x16x32_bf16 v[112:115], v[180:183], v[188:191], v[112:115]
	v_mfma_f32_16x16x32_bf16 v[100:103], v[172:175], v[196:199], v[100:103]
	v_mfma_f32_16x16x32_bf16 v[96:99], v[180:183], v[196:199], v[96:99]
	v_mfma_f32_16x16x32_bf16 v[84:87], v[172:175], v[204:207], v[84:87]
	v_mfma_f32_16x16x32_bf16 v[80:83], v[180:183], v[204:207], v[80:83]
	v_mfma_f32_16x16x32_bf16 v[68:71], v[172:175], v[212:215], v[68:71]
	v_mfma_f32_16x16x32_bf16 v[64:67], v[180:183], v[212:215], v[64:67]
	v_mfma_f32_16x16x32_bf16 v[116:119], v[176:179], v[192:195], v[116:119]
	v_mfma_f32_16x16x32_bf16 v[112:115], v[184:187], v[192:195], v[112:115]
	v_mfma_f32_16x16x32_bf16 v[100:103], v[176:179], v[200:203], v[100:103]
	v_mfma_f32_16x16x32_bf16 v[96:99], v[184:187], v[200:203], v[96:99]
	v_mfma_f32_16x16x32_bf16 v[84:87], v[176:179], v[208:211], v[84:87]
	v_mfma_f32_16x16x32_bf16 v[80:83], v[184:187], v[208:211], v[80:83]
	v_mfma_f32_16x16x32_bf16 v[68:71], v[176:179], v[216:219], v[68:71]
	v_mfma_f32_16x16x32_bf16 v[64:67], v[184:187], v[216:219], v[64:67]
	s_setprio 0
	s_barrier
;     __device__ __forceinline__ void operator()(const f32x4 (&acc)[2][2][4][2], const Unit& u, int wr, int wc, int fr, int fq) const {
;     ...
;             for (int m = 0; m < 4; ++m) { const int rowg = u.pm * BM + ai * HALF + wr * 64 + m * 16, row = rowg + fr; const size_t off = (size_t)row * 1024 + col0;
;                 u32x4 w[2]; float ss = 0.f;
; #pragma unroll
;                 for (int bj = 0; bj < 2; ++bj) { f32x4 b0, b1;
; template <class Epi, class Sched, bool ALIGN_EPI = false, bool SP2 = false>
; __device__ __forceinline__ void gemm_phase(PG8_LAS unsigned char* lds, const Gemm g, const Sched& S, const Epi& E) {
;     ...
;             PG8_WAIT_V(8); PG8_WAIT_L(0); PG8_BAR; PG8_MMA(0, 0, At, B0); PG8_MMA(0, 1, At, B1); PG8_BAR; PG8_SCHED;
;             PG8_LDA(At, 1, 1); PG8_STAGE(PG8_SB(1, 0), b3, voffB); PG8_STAGE(PG8_SB(1, 1), b3 + hstepB, voffB); PG8_STAGE(PG8_SA(1, 0), a3, voffA);
;             PG8_WAIT_V(8); PG8_WAIT_L(0); PG8_BAR; PG8_MMA(1, 0, At, B0); PG8_MMA(1, 1, At, B1); PG8_BAR; PG8_SCHED;
;             } else {
;             PG8_LDB(B0, 0, 0); PG8_SCHED; PG8_LDA(At, 0, 0); PG8_STAGE(PG8_SA(1, 1), a1 + hstepA, voffA);
;             PG8_WAIT_L(8); PG8_BAR; PG8_WAIT_L(0); PG8_MMA(0, 0, At, B0); PG8_BAR; PG8_SCHED;
;             PG8_LDB(B1, 0, 1); PG8_STAGE(PG8_SB(0, 0), b2, voffB);
;             PG8_BAR; PG8_WAIT_L(0); PG8_MMA(0, 1, At, B1); PG8_BAR;
;             PG8_LDA(At, 0, 1); PG8_STAGE(PG8_SA(0, 0), a2, voffA);
;             PG8_BAR; PG8_WAIT_L(0); PG8_MMA(1, 0, At, B0); PG8_BAR; PG8_SCHED;
;             PG8_STAGE(PG8_SB(0, 1), b2 + hstepB, voffB);
;             PG8_WAIT_V(6); PG8_BAR; PG8_MMA(1, 1, At, B1); PG8_BAR;
;             PG8_LDB(B0, 1, 0); PG8_SCHED; PG8_LDA(At, 1, 0); PG8_STAGE(PG8_SA(0, 1), a2 + hstepA, voffA);
;             PG8_WAIT_L(8); PG8_BAR; PG8_WAIT_L(0); PG8_MMA(0, 0, At, B0); PG8_BAR; PG8_SCHED;
;             PG8_LDB(B1, 1, 1); PG8_STAGE(PG8_SB(1, 0), b3, voffB);
;             PG8_BAR; PG8_WAIT_L(0); PG8_MMA(0, 1, At, B1); PG8_BAR;
;             PG8_LDA(At, 1, 1); PG8_STAGE(PG8_SA(1, 0), a3, voffA);
;             PG8_BAR; PG8_WAIT_L(0); PG8_MMA(1, 0, At, B0); PG8_BAR; PG8_SCHED;
;             PG8_STAGE(PG8_SB(1, 1), b3 + hstepB, voffB);
;             PG8_WAIT_V(6); PG8_BAR; PG8_MMA(1, 1, At, B1); PG8_BAR;
;             }
;         }
;         if constexpr (ALIGN_EPI) { if (wr == 0) PG8_BAR; }
	s_add_i32 s22, s28, s42
	v_lshl_add_u64 v[220:221], v[220:221], 0, s[18:19]
	s_mov_b32 m0, s22
	ds_read_b128 v[188:191], v157 offset:49152
	ds_read_b128 v[192:195], v157 offset:50176
	ds_read_b128 v[196:199], v157 offset:51200
	ds_read_b128 v[200:203], v157 offset:52224
	ds_read_b128 v[204:207], v157 offset:53248
	ds_read_b128 v[208:211], v157 offset:54272
	ds_read_b128 v[212:215], v157 offset:55296
	ds_read_b128 v[216:219], v157 offset:56320
	global_load_lds_dwordx4 v[220:221], off
	s_add_i32 m0, s22, 0x2000
	s_add_u32 s20, s20, 0x2c080
	v_lshl_add_u64 v[220:221], v[222:223], 0, s[18:19]
	s_addc_u32 s21, s21, 0
	s_add_i32 s22, s29, s42
	global_load_lds_dwordx4 v[220:221], off
	v_lshl_add_u64 v[220:221], s[20:21], 0, v[130:131]
	s_mov_b32 m0, s22
	s_nop 0
	global_load_lds_dwordx4 v[220:221], off
	v_lshl_add_u64 v[220:221], s[20:21], 0, v[134:135]
	s_add_i32 m0, s22, 0x2000
	s_nop 0
	global_load_lds_dwordx4 v[220:221], off
	v_lshl_add_u64 v[220:221], v[224:225], 0, s[18:19]
	s_mov_b32 m0, s50
	s_nop 0
	global_load_lds_dwordx4 v[220:221], off
	v_lshl_add_u64 v[220:221], v[226:227], 0, s[18:19]
	s_mov_b32 m0, s51
	s_nop 0
	global_load_lds_dwordx4 v[220:221], off
	s_waitcnt vmcnt(8)
	s_waitcnt lgkmcnt(0)
	s_barrier
	s_setprio 1
	s_waitcnt lgkmcnt(0)
	v_mfma_f32_16x16x32_bf16 v[60:63], v[146:149], v[188:191], v[60:63]
	v_mfma_f32_16x16x32_bf16 v[56:59], v[164:167], v[188:191], v[56:59]
	v_mfma_f32_16x16x32_bf16 v[44:47], v[146:149], v[196:199], v[44:47]
	v_mfma_f32_16x16x32_bf16 v[40:43], v[164:167], v[196:199], v[40:43]
	v_mfma_f32_16x16x32_bf16 v[28:31], v[146:149], v[204:207], v[28:31]
	v_mfma_f32_16x16x32_bf16 v[24:27], v[164:167], v[204:207], v[24:27]
	v_mfma_f32_16x16x32_bf16 v[12:15], v[146:149], v[212:215], v[12:15]
	v_mfma_f32_16x16x32_bf16 v[8:11], v[164:167], v[212:215], v[8:11]
	v_mfma_f32_16x16x32_bf16 v[60:63], v[160:163], v[192:195], v[60:63]
	v_mfma_f32_16x16x32_bf16 v[56:59], v[168:171], v[192:195], v[56:59]
	v_mfma_f32_16x16x32_bf16 v[44:47], v[160:163], v[200:203], v[44:47]
	v_mfma_f32_16x16x32_bf16 v[40:43], v[168:171], v[200:203], v[40:43]
	v_mfma_f32_16x16x32_bf16 v[28:31], v[160:163], v[208:211], v[28:31]
	v_mfma_f32_16x16x32_bf16 v[24:27], v[168:171], v[208:211], v[24:27]
	v_mfma_f32_16x16x32_bf16 v[12:15], v[160:163], v[216:219], v[12:15]
	v_mfma_f32_16x16x32_bf16 v[8:11], v[168:171], v[216:219], v[8:11]
	s_setprio 0
	s_setprio 1
	v_mfma_f32_16x16x32_bf16 v[52:55], v[172:175], v[188:191], v[52:55]
	v_mfma_f32_16x16x32_bf16 v[48:51], v[180:183], v[188:191], v[48:51]
	v_mfma_f32_16x16x32_bf16 v[36:39], v[172:175], v[196:199], v[36:39]
	v_mfma_f32_16x16x32_bf16 v[32:35], v[180:183], v[196:199], v[32:35]
	v_mfma_f32_16x16x32_bf16 v[20:23], v[172:175], v[204:207], v[20:23]
	v_mfma_f32_16x16x32_bf16 v[16:19], v[180:183], v[204:207], v[16:19]
	v_mfma_f32_16x16x32_bf16 v[4:7], v[172:175], v[212:215], v[4:7]
	v_mfma_f32_16x16x32_bf16 v[0:3], v[180:183], v[212:215], v[0:3]
	v_mfma_f32_16x16x32_bf16 v[52:55], v[176:179], v[192:195], v[52:55]
	v_mfma_f32_16x16x32_bf16 v[48:51], v[184:187], v[192:195], v[48:51]
	v_mfma_f32_16x16x32_bf16 v[36:39], v[176:179], v[200:203], v[36:39]
	v_mfma_f32_16x16x32_bf16 v[32:35], v[184:187], v[200:203], v[32:35]
	v_mfma_f32_16x16x32_bf16 v[20:23], v[176:179], v[208:211], v[20:23]
	v_mfma_f32_16x16x32_bf16 v[16:19], v[184:187], v[208:211], v[16:19]
	v_mfma_f32_16x16x32_bf16 v[4:7], v[176:179], v[216:219], v[4:7]
	v_mfma_f32_16x16x32_bf16 v[0:3], v[184:187], v[216:219], v[0:3]
	s_setprio 0
	s_barrier
	s_add_i32 s27, s27, 2
	s_add_u32 s0, s0, 0x100
	s_addc_u32 s1, s1, 0
	s_add_u32 s25, s25, 0x100
	s_addc_u32 s26, s26, 0
	s_cmp_gt_u32 s27, 41
	s_cbranch_scc0 .LBB0_1196
	s_lshl_b32 s22, s24, 8
	s_add_i32 s22, s22, s49
	v_or_b32_e32 v148, s22, v150
	v_ashrrev_i32_e32 v149, 31, v148
	v_readlane_b32 s26, v239, 49
	v_lshl_or_b32 v146, s14, 8, v152
	v_lshlrev_b64 v[160:161], 11, v[148:149]
	v_readlane_b32 s27, v239, 50
	v_ashrrev_i32_e32 v147, 31, v146
	v_and_b32_e32 v168, 64, v158
	v_lshl_add_u64 v[160:161], s[26:27], 0, v[160:161]
	v_lshl_add_u64 v[164:165], v[146:147], 1, v[160:161]
	v_add_co_u32_e32 v184, vcc, 0x8000, v164
	s_nop 1
	v_addc_co_u32_e32 v185, vcc, 0, v165, vcc
	v_add_co_u32_e32 v192, vcc, 0x10000, v164
	s_nop 1
	v_addc_co_u32_e32 v193, vcc, 0, v165, vcc
	v_add_co_u32_e32 v200, vcc, 0x18000, v164
	s_nop 1
	v_addc_co_u32_e32 v201, vcc, 0, v165, vcc
	v_add_co_u32_e32 v208, vcc, 0x40000, v164
	s_nop 1
	v_addc_co_u32_e32 v209, vcc, 0, v165, vcc
	v_add_co_u32_e32 v216, vcc, 0x48000, v164
	s_nop 1
	v_addc_co_u32_e32 v217, vcc, 0, v165, vcc
	v_add_co_u32_e32 v224, vcc, 0x50000, v164
	s_nop 1
	v_addc_co_u32_e32 v225, vcc, 0, v165, vcc
	v_add_co_u32_e32 v232, vcc, 0x58000, v164
	s_nop 1
	v_addc_co_u32_e32 v233, vcc, 0, v165, vcc
	global_load_dwordx4 v[160:163], v[164:165], off
	s_nop 0
	global_load_dwordx4 v[164:167], v[164:165], off offset:64
	global_load_dwordx4 v[180:183], v[184:185], off
	global_load_dwordx4 v[184:187], v[184:185], off offset:64
	global_load_dwordx4 v[188:191], v[192:193], off
	global_load_dwordx4 v[192:195], v[192:193], off offset:64
	global_load_dwordx4 v[196:199], v[200:201], off
	global_load_dwordx4 v[200:203], v[200:201], off offset:64
	global_load_dwordx4 v[204:207], v[208:209], off
	global_load_dwordx4 v[208:211], v[208:209], off offset:64
	global_load_dwordx4 v[212:215], v[216:217], off
	global_load_dwordx4 v[216:219], v[216:217], off offset:64
	global_load_dwordx4 v[220:223], v[224:225], off
	global_load_dwordx4 v[224:227], v[224:225], off offset:64
	global_load_dwordx4 v[228:231], v[232:233], off
	global_load_dwordx4 v[232:235], v[232:233], off offset:64
	s_and_b64 vcc, exec, s[36:37]
	s_cbranch_vccz .LBB0_1199
	s_barrier
; __device__ __forceinline__ unsigned swap8(unsigned v) { return (unsigned)__builtin_amdgcn_update_dpp(0, (int)v, 0x128  , 0xF, 0xF, false); }
; __device__ __forceinline__ void wide_store(bf16_t* O, int ldc, int rowg  , int col0  , int fr, u32x4 w0, u32x4 w1) {
;     const bool lo = fr < 8;
;     u32x4 snd = lo ? w1 : w0, rcv;
;     rcv.x = swap8(snd.x); rcv.y = swap8(snd.y); rcv.z = swap8(snd.z); rcv.w = swap8(snd.w);
;     const u32x4 first = lo ? w0 : rcv, second = lo ? rcv : w1;
;     bf16_t* p = O + (size_t)(rowg + (fr & 7)) * ldc + col0 + (lo ? 0 : 32);
;     __builtin_nontemporal_store(first, (u32x4*)p); __builtin_nontemporal_store(second, (u32x4*)(p + (size_t)8 * ldc));
;     __device__ __forceinline__ void operator()(const f32x4 (&acc)[2][2][4][2], const Unit& u, int wr, int wc, int fr, int fq) const {
;     ...
;             for (int m = 0; m < 4; ++m) { const int rowg = u.pm * BM + ai * HALF + wr * 64 + m * 16, row = rowg + fr; const size_t off = (size_t)row * 1024 + col0;
;                 u32x4 w[2]; float ss = 0.f;
; #pragma unroll
;                 for (int bj = 0; bj < 2; ++bj) { f32x4 b0, b1;
;                     if (BASE_F32) { const float* bp = (const float*)base + off + 32 * bj; b0 = *(const f32x4*)bp; b1 = *(const f32x4*)(bp + 4); }
;                     else { const u32x4 bb = *(const u32x4*)((const bf16_t*)base + off + 32 * bj);
;                         b0 = (f32x4){__uint_as_float(bb.x << 16), __uint_as_float(bb.x & 0xffff0000u), __uint_as_float(bb.y << 16), __uint_as_float(bb.y & 0xffff0000u)};
;                         b1 = (f32x4){__uint_as_float(bb.z << 16), __uint_as_float(bb.z & 0xffff0000u), __uint_as_float(bb.w << 16), __uint_as_float(bb.w & 0xffff0000u)}; }
;                     const f32x4 o0 = b0 + acc[ai][bj][m][0], o1 = b1 + acc[ai][bj][m][1];
;                     ss += ((o0[0] * o0[0] + o0[1] * o0[1]) + (o0[2] * o0[2] + o0[3] * o0[3])) + ((o1[0] * o1[0] + o1[1] * o1[1]) + (o1[2] * o1[2] + o1[3] * o1[3]));
;                     w[bj].x = cvt_pk_bf16(o0[0], o0[1]); w[bj].y = cvt_pk_bf16(o0[2], o0[3]); w[bj].z = cvt_pk_bf16(o1[0], o1[1]); w[bj].w = cvt_pk_bf16(o1[2], o1[3]); }
;                 ss += __shfl_xor(ss, 16); ss += __shfl_xor(ss, 32); if (fq == 0) slots[(size_t)row * 16 + u.pn * 4 + wc] = ss;
;                 wide_store(xb, 1024, rowg, col0, fr, w[0], w[1]);
.LBB0_1199:
	v_add_u32_e32 v176, 64, v168
	v_xor_b32_e32 v159, 16, v158
	v_cmp_lt_i32_e32 vcc, v159, v176
	s_lshl_b32 s0, s14, 2
	s_ashr_i32 s1, s0, 31
	v_cndmask_b32_e32 v159, v158, v159, vcc
	v_lshlrev_b32_e32 v159, 2, v159
	s_waitcnt vmcnt(14)
	v_lshlrev_b32_e32 v168, 16, v160
	v_and_b32_e32 v169, 0xffff0000, v160
	v_lshlrev_b32_e32 v160, 16, v161
	v_and_b32_e32 v161, 0xffff0000, v161
	v_lshlrev_b32_e32 v170, 16, v162
	v_and_b32_e32 v171, 0xffff0000, v162
	v_lshlrev_b32_e32 v162, 16, v163
	v_and_b32_e32 v163, 0xffff0000, v163
	v_lshlrev_b32_e32 v172, 16, v164
	v_and_b32_e32 v173, 0xffff0000, v164
	v_lshlrev_b32_e32 v164, 16, v165
	v_and_b32_e32 v165, 0xffff0000, v165
	v_lshlrev_b32_e32 v174, 16, v166
	v_and_b32_e32 v175, 0xffff0000, v166
	v_lshlrev_b32_e32 v166, 16, v167
	v_and_b32_e32 v167, 0xffff0000, v167
	v_pk_add_f32 v[126:127], v[126:127], v[160:161]
	v_pk_add_f32 v[124:125], v[124:125], v[168:169]
	v_pk_add_f32 v[122:123], v[122:123], v[162:163]
	v_pk_add_f32 v[120:121], v[120:121], v[170:171]
	v_pk_add_f32 v[118:119], v[118:119], v[164:165]
	v_pk_add_f32 v[116:117], v[116:117], v[172:173]
	v_pk_add_f32 v[114:115], v[114:115], v[166:167]
	v_pk_add_f32 v[112:113], v[112:113], v[174:175]
	v_mul_f32_e32 v160, v125, v125
	v_mul_f32_e32 v161, v127, v127
	v_mul_f32_e32 v162, v121, v121
	v_mul_f32_e32 v163, v123, v123
	v_mul_f32_e32 v164, v117, v117
	v_mul_f32_e32 v165, v119, v119
	v_mul_f32_e32 v166, v113, v113
	v_mul_f32_e32 v167, v115, v115
	v_fmac_f32_e32 v160, v124, v124
	v_fmac_f32_e32 v161, v126, v126
	v_fmac_f32_e32 v162, v120, v120
	v_fmac_f32_e32 v163, v122, v122
	v_fmac_f32_e32 v164, v116, v116
	v_fmac_f32_e32 v165, v118, v118
	v_fmac_f32_e32 v166, v112, v112
	v_fmac_f32_e32 v167, v114, v114
	v_add_f32_e32 v160, v160, v161
	v_add_f32_e32 v161, v162, v163
	v_add_f32_e32 v162, v164, v165
	v_add_f32_e32 v163, v166, v167
	v_add_f32_e32 v160, v160, v161
	v_add_f32_e32 v161, v162, v163
	v_add_f32_e32 v161, v160, v161
	ds_bpermute_b32 v162, v159, v161
	v_xor_b32_e32 v160, 32, v158
	v_cmp_lt_i32_e32 vcc, v160, v176
	s_waitcnt lgkmcnt(0)
	v_add_f32_e32 v161, v161, v162
	v_cndmask_b32_e32 v160, v158, v160, vcc
	v_lshlrev_b32_e32 v160, 2, v160
	ds_bpermute_b32 v162, v160, v161
	s_and_saveexec_b64 s[20:21], s[2:3]
	s_cbranch_execz .LBB0_1201
	v_lshlrev_b64 v[148:149], 6, v[148:149]
	v_lshl_add_u64 v[148:149], s[82:83], 0, v[148:149]
	v_lshl_add_u64 v[148:149], s[0:1], 2, v[148:149]
	s_lshl_b32 s14, s48, 2
	v_lshl_add_u64 v[148:149], v[148:149], 0, s[14:15]
	s_waitcnt lgkmcnt(0)
	v_add_f32_e32 v161, v161, v162
	global_store_dword v[148:149], v161, off
.LBB0_1201:
	s_or_b64 exec, exec, s[20:21]
	v_cvt_pk_bf16_f32 v120, v120, v121
	v_cvt_pk_bf16_f32 v112, v112, v113
	v_cvt_pk_bf16_f32 v124, v124, v125
	v_cvt_pk_bf16_f32 v125, v126, v127
	v_cvt_pk_bf16_f32 v121, v122, v123
	v_cvt_pk_bf16_f32 v118, v118, v119
	v_cvt_pk_bf16_f32 v113, v114, v115
	v_cndmask_b32_e64 v115, v120, v112, s[4:5]
	v_mov_b32_e32 v126, v137
	v_cvt_pk_bf16_f32 v122, v116, v117
	v_cndmask_b32_e64 v114, v121, v113, s[4:5]
	v_cndmask_b32_e64 v116, v125, v118, s[4:5]
	v_mov_b32_e32 v119, v137
	v_mov_b32_dpp v126, v115 row_ror:8 row_mask:0xf bank_mask:0xf
	v_mov_b32_e32 v127, v137
	v_cndmask_b32_e64 v117, v124, v122, s[4:5]
	v_mov_b32_e32 v123, v137
	v_mov_b32_dpp v119, v116 row_ror:8 row_mask:0xf bank_mask:0xf
	v_mov_b32_dpp v127, v114 row_ror:8 row_mask:0xf bank_mask:0xf
	v_cndmask_b32_e64 v116, v126, v120, s[4:5]
	v_cndmask_b32_e64 v120, v112, v126, s[4:5]
	v_or_b32_e32 v112, s22, v154
	v_mov_b32_dpp v123, v117 row_ror:8 row_mask:0xf bank_mask:0xf
	v_cndmask_b32_e64 v117, v127, v121, s[4:5]
	v_cndmask_b32_e64 v121, v113, v127, s[4:5]
	v_ashrrev_i32_e32 v113, 31, v112
	v_lshlrev_b64 v[112:113], 11, v[112:113]
	v_cndmask_b32_e64 v115, v119, v125, s[4:5]
	v_cndmask_b32_e64 v114, v123, v124, s[4:5]
	v_cndmask_b32_e64 v119, v118, v119, s[4:5]
	v_cndmask_b32_e64 v118, v122, v123, s[4:5]
	v_lshl_add_u64 v[122:123], s[26:27], 0, v[112:113]
	v_lshlrev_b64 v[112:113], 1, v[146:147]
	v_lshl_add_u64 v[122:123], v[122:123], 0, v[112:113]
	v_lshl_add_u64 v[122:123], v[122:123], 0, v[136:137]
	global_store_dwordx4 v[122:123], v[114:117], off nt
	s_or_b32 s23, s22, 16
	s_nop 0
	v_add_co_u32_e32 v114, vcc, s47, v122
	s_nop 1
	v_addc_co_u32_e32 v115, vcc, 0, v123, vcc
	global_store_dwordx4 v[114:115], v[118:121], off nt
	v_or_b32_e32 v114, s23, v150
	v_ashrrev_i32_e32 v115, 31, v114
	v_lshlrev_b64 v[116:117], 11, v[114:115]
	v_lshl_add_u64 v[116:117], s[26:27], 0, v[116:117]
	v_lshl_add_u64 v[120:121], v[116:117], 0, v[112:113]
	s_waitcnt vmcnt(15)
	v_mov_b32_e32 v116, v180
	v_mov_b32_e32 v117, v181
	v_mov_b32_e32 v118, v182
	v_mov_b32_e32 v119, v183
	v_mov_b32_e32 v120, v184
	v_mov_b32_e32 v121, v185
	v_mov_b32_e32 v122, v186
	v_mov_b32_e32 v123, v187
	v_lshlrev_b32_e32 v124, 16, v116
	v_and_b32_e32 v125, 0xffff0000, v116
	v_lshlrev_b32_e32 v116, 16, v117
	v_and_b32_e32 v117, 0xffff0000, v117
	v_lshlrev_b32_e32 v126, 16, v118
	v_and_b32_e32 v127, 0xffff0000, v118
	v_lshlrev_b32_e32 v118, 16, v119
	v_and_b32_e32 v119, 0xffff0000, v119
	v_lshlrev_b32_e32 v148, 16, v120
	v_and_b32_e32 v149, 0xffff0000, v120
	v_lshlrev_b32_e32 v120, 16, v121
	v_and_b32_e32 v121, 0xffff0000, v121
	s_waitcnt lgkmcnt(0)
	v_lshlrev_b32_e32 v162, 16, v122
	v_and_b32_e32 v163, 0xffff0000, v122
	v_lshlrev_b32_e32 v122, 16, v123
	v_and_b32_e32 v123, 0xffff0000, v123
	v_pk_add_f32 v[110:111], v[110:111], v[116:117]
	v_pk_add_f32 v[108:109], v[108:109], v[124:125]
	v_pk_add_f32 v[106:107], v[106:107], v[118:119]
	v_pk_add_f32 v[104:105], v[104:105], v[126:127]
	v_pk_add_f32 v[102:103], v[102:103], v[120:121]
	v_pk_add_f32 v[100:101], v[100:101], v[148:149]
	v_pk_add_f32 v[98:99], v[98:99], v[122:123]
	v_pk_add_f32 v[96:97], v[96:97], v[162:163]
	v_mul_f32_e32 v116, v109, v109
	v_mul_f32_e32 v117, v111, v111
	v_mul_f32_e32 v118, v105, v105
	v_mul_f32_e32 v119, v107, v107
	v_mul_f32_e32 v120, v101, v101
	v_mul_f32_e32 v121, v103, v103
	v_mul_f32_e32 v122, v97, v97
	v_mul_f32_e32 v123, v99, v99
	v_fmac_f32_e32 v116, v108, v108
	v_fmac_f32_e32 v117, v110, v110
	v_fmac_f32_e32 v118, v104, v104
	v_fmac_f32_e32 v119, v106, v106
	v_fmac_f32_e32 v120, v100, v100
	v_fmac_f32_e32 v121, v102, v102
	v_fmac_f32_e32 v122, v96, v96
	v_fmac_f32_e32 v123, v98, v98
	v_add_f32_e32 v116, v116, v117
	v_add_f32_e32 v117, v118, v119
	v_add_f32_e32 v118, v120, v121
	v_add_f32_e32 v119, v122, v123
	v_add_f32_e32 v116, v116, v117
	v_add_f32_e32 v117, v118, v119
	v_add_f32_e32 v116, v116, v117
	ds_bpermute_b32 v117, v159, v116
	s_waitcnt lgkmcnt(0)
	v_add_f32_e32 v116, v116, v117
	ds_bpermute_b32 v117, v160, v116
	s_and_saveexec_b64 s[20:21], s[2:3]
	s_cbranch_execz .LBB0_1203
	v_lshlrev_b64 v[114:115], 6, v[114:115]
	v_lshl_add_u64 v[114:115], s[82:83], 0, v[114:115]
	v_lshl_add_u64 v[114:115], s[0:1], 2, v[114:115]
	s_lshl_b32 s14, s48, 2
	v_lshl_add_u64 v[114:115], v[114:115], 0, s[14:15]
	s_waitcnt lgkmcnt(0)
	v_add_f32_e32 v116, v116, v117
	global_store_dword v[114:115], v116, off
; __device__ __forceinline__ unsigned swap8(unsigned v) { return (unsigned)__builtin_amdgcn_update_dpp(0, (int)v, 0x128  , 0xF, 0xF, false); }
; __device__ __forceinline__ void wide_store(bf16_t* O, int ldc, int rowg  , int col0  , int fr, u32x4 w0, u32x4 w1) {
;     const bool lo = fr < 8;
;     u32x4 snd = lo ? w1 : w0, rcv;
;     rcv.x = swap8(snd.x); rcv.y = swap8(snd.y); rcv.z = swap8(snd.z); rcv.w = swap8(snd.w);
;     const u32x4 first = lo ? w0 : rcv, second = lo ? rcv : w1;
;     bf16_t* p = O + (size_t)(rowg + (fr & 7)) * ldc + col0 + (lo ? 0 : 32);
;     __builtin_nontemporal_store(first, (u32x4*)p); __builtin_nontemporal_store(second, (u32x4*)(p + (size_t)8 * ldc));
;     __device__ __forceinline__ void operator()(const f32x4 (&acc)[2][2][4][2], const Unit& u, int wr, int wc, int fr, int fq) const {
;     ...
;             for (int m = 0; m < 4; ++m) { const int rowg = u.pm * BM + ai * HALF + wr * 64 + m * 16, row = rowg + fr; const size_t off = (size_t)row * 1024 + col0;
;                 u32x4 w[2]; float ss = 0.f;
; #pragma unroll
;                 for (int bj = 0; bj < 2; ++bj) { f32x4 b0, b1;
;                     if (BASE_F32) { const float* bp = (const float*)base + off + 32 * bj; b0 = *(const f32x4*)bp; b1 = *(const f32x4*)(bp + 4); }
;                     else { const u32x4 bb = *(const u32x4*)((const bf16_t*)base + off + 32 * bj);
;                         b0 = (f32x4){__uint_as_float(bb.x << 16), __uint_as_float(bb.x & 0xffff0000u), __uint_as_float(bb.y << 16), __uint_as_float(bb.y & 0xffff0000u)};
;                         b1 = (f32x4){__uint_as_float(bb.z << 16), __uint_as_float(bb.z & 0xffff0000u), __uint_as_float(bb.w << 16), __uint_as_float(bb.w & 0xffff0000u)}; }
;                     const f32x4 o0 = b0 + acc[ai][bj][m][0], o1 = b1 + acc[ai][bj][m][1];
;                     ss += ((o0[0] * o0[0] + o0[1] * o0[1]) + (o0[2] * o0[2] + o0[3] * o0[3])) + ((o1[0] * o1[0] + o1[1] * o1[1]) + (o1[2] * o1[2] + o1[3] * o1[3]));
;                     w[bj].x = cvt_pk_bf16(o0[0], o0[1]); w[bj].y = cvt_pk_bf16(o0[2], o0[3]); w[bj].z = cvt_pk_bf16(o1[0], o1[1]); w[bj].w = cvt_pk_bf16(o1[2], o1[3]); }
;                 ss += __shfl_xor(ss, 16); ss += __shfl_xor(ss, 32); if (fq == 0) slots[(size_t)row * 16 + u.pn * 4 + wc] = ss;
;                 wide_store(xb, 1024, rowg, col0, fr, w[0], w[1]);
.LBB0_1203:
	s_or_b64 exec, exec, s[20:21]
	v_cvt_pk_bf16_f32 v104, v104, v105
	v_cvt_pk_bf16_f32 v100, v100, v101
	v_cvt_pk_bf16_f32 v101, v102, v103
	v_cvt_pk_bf16_f32 v102, v96, v97
	v_cvt_pk_bf16_f32 v108, v108, v109
	v_cvt_pk_bf16_f32 v109, v110, v111
	v_cvt_pk_bf16_f32 v105, v106, v107
	v_cvt_pk_bf16_f32 v103, v98, v99
	v_cndmask_b32_e64 v97, v104, v102, s[4:5]
	v_mov_b32_e32 v110, v137
	v_cndmask_b32_e64 v96, v105, v103, s[4:5]
	v_cndmask_b32_e64 v98, v109, v101, s[4:5]
	v_mov_b32_e32 v107, v137
	v_mov_b32_dpp v110, v97 row_ror:8 row_mask:0xf bank_mask:0xf
	v_mov_b32_e32 v111, v137
	v_cndmask_b32_e64 v99, v108, v100, s[4:5]
	v_mov_b32_e32 v106, v137
	v_mov_b32_dpp v107, v98 row_ror:8 row_mask:0xf bank_mask:0xf
	v_mov_b32_dpp v111, v96 row_ror:8 row_mask:0xf bank_mask:0xf
	v_cndmask_b32_e64 v98, v110, v104, s[4:5]
	v_or_b32_e32 v104, s23, v154
	v_mov_b32_dpp v106, v99 row_ror:8 row_mask:0xf bank_mask:0xf
	v_cndmask_b32_e64 v99, v111, v105, s[4:5]
	v_ashrrev_i32_e32 v105, 31, v104
	v_lshlrev_b64 v[104:105], 11, v[104:105]
	v_lshl_add_u64 v[104:105], s[26:27], 0, v[104:105]
	v_lshl_add_u64 v[104:105], v[104:105], 0, v[112:113]
	v_cndmask_b32_e64 v97, v107, v109, s[4:5]
	v_cndmask_b32_e64 v96, v106, v108, s[4:5]
	v_lshl_add_u64 v[104:105], v[104:105], 0, v[136:137]
	global_store_dwordx4 v[104:105], v[96:99], off nt
	v_cndmask_b32_e64 v103, v103, v111, s[4:5]
	v_cndmask_b32_e64 v102, v102, v110, s[4:5]
	v_add_co_u32_e32 v96, vcc, s47, v104
	v_cndmask_b32_e64 v101, v101, v107, s[4:5]
	v_cndmask_b32_e64 v100, v100, v106, s[4:5]
	v_addc_co_u32_e32 v97, vcc, 0, v105, vcc
	s_or_b32 s23, s22, 32
	global_store_dwordx4 v[96:97], v[100:103], off nt
	v_or_b32_e32 v96, s23, v150
	v_ashrrev_i32_e32 v97, 31, v96
	v_lshlrev_b64 v[98:99], 11, v[96:97]
	v_lshl_add_u64 v[98:99], s[26:27], 0, v[98:99]
	v_lshl_add_u64 v[102:103], v[98:99], 0, v[112:113]
	s_waitcnt vmcnt(16)
	v_mov_b32_e32 v98, v188
	v_mov_b32_e32 v99, v189
	v_mov_b32_e32 v100, v190
	v_mov_b32_e32 v101, v191
	v_mov_b32_e32 v102, v192
	v_mov_b32_e32 v103, v193
	v_mov_b32_e32 v104, v194
	v_mov_b32_e32 v105, v195
	v_lshlrev_b32_e32 v106, 16, v98
	v_and_b32_e32 v107, 0xffff0000, v98
	v_lshlrev_b32_e32 v98, 16, v99
	v_and_b32_e32 v99, 0xffff0000, v99
	v_lshlrev_b32_e32 v108, 16, v100
	v_and_b32_e32 v109, 0xffff0000, v100
	v_lshlrev_b32_e32 v100, 16, v101
	v_and_b32_e32 v101, 0xffff0000, v101
	v_lshlrev_b32_e32 v110, 16, v102
	v_and_b32_e32 v111, 0xffff0000, v102
	v_lshlrev_b32_e32 v102, 16, v103
	v_and_b32_e32 v103, 0xffff0000, v103
	v_lshlrev_b32_e32 v114, 16, v104
	v_and_b32_e32 v115, 0xffff0000, v104
	v_lshlrev_b32_e32 v104, 16, v105
	v_and_b32_e32 v105, 0xffff0000, v105
	v_pk_add_f32 v[94:95], v[94:95], v[98:99]
	v_pk_add_f32 v[92:93], v[92:93], v[106:107]
	v_pk_add_f32 v[90:91], v[90:91], v[100:101]
	v_pk_add_f32 v[88:89], v[88:89], v[108:109]
	v_pk_add_f32 v[86:87], v[86:87], v[102:103]
	v_pk_add_f32 v[84:85], v[84:85], v[110:111]
	v_pk_add_f32 v[82:83], v[82:83], v[104:105]
	v_pk_add_f32 v[80:81], v[80:81], v[114:115]
	v_mul_f32_e32 v98, v93, v93
	v_mul_f32_e32 v99, v95, v95
	v_mul_f32_e32 v100, v89, v89
	v_mul_f32_e32 v101, v91, v91
	v_mul_f32_e32 v102, v85, v85
	v_mul_f32_e32 v103, v87, v87
	v_mul_f32_e32 v104, v81, v81
	v_mul_f32_e32 v105, v83, v83
	v_fmac_f32_e32 v98, v92, v92
	v_fmac_f32_e32 v99, v94, v94
	v_fmac_f32_e32 v100, v88, v88
	v_fmac_f32_e32 v101, v90, v90
	v_fmac_f32_e32 v102, v84, v84
	v_fmac_f32_e32 v103, v86, v86
	v_fmac_f32_e32 v104, v80, v80
	v_fmac_f32_e32 v105, v82, v82
	v_add_f32_e32 v98, v98, v99
	v_add_f32_e32 v99, v100, v101
	v_add_f32_e32 v100, v102, v103
	v_add_f32_e32 v101, v104, v105
	v_add_f32_e32 v98, v98, v99
	v_add_f32_e32 v99, v100, v101
	v_add_f32_e32 v98, v98, v99
	ds_bpermute_b32 v99, v159, v98
	s_waitcnt lgkmcnt(0)
	v_add_f32_e32 v98, v98, v99
	ds_bpermute_b32 v99, v160, v98
	s_and_saveexec_b64 s[20:21], s[2:3]
	s_cbranch_execz .LBB0_1205
	v_lshlrev_b64 v[96:97], 6, v[96:97]
	v_lshl_add_u64 v[96:97], s[82:83], 0, v[96:97]
	v_lshl_add_u64 v[96:97], s[0:1], 2, v[96:97]
	s_lshl_b32 s14, s48, 2
	v_lshl_add_u64 v[96:97], v[96:97], 0, s[14:15]
	s_waitcnt lgkmcnt(0)
	v_add_f32_e32 v98, v98, v99
	global_store_dword v[96:97], v98, off
.LBB0_1205:
	s_or_b64 exec, exec, s[20:21]
	v_cvt_pk_bf16_f32 v88, v88, v89
	v_cvt_pk_bf16_f32 v84, v84, v85
	v_cvt_pk_bf16_f32 v85, v86, v87
	v_cvt_pk_bf16_f32 v86, v80, v81
	v_cvt_pk_bf16_f32 v92, v92, v93
	v_cvt_pk_bf16_f32 v93, v94, v95
	v_cvt_pk_bf16_f32 v89, v90, v91
	v_cvt_pk_bf16_f32 v87, v82, v83
	v_cndmask_b32_e64 v81, v88, v86, s[4:5]
	v_mov_b32_e32 v94, v137
	v_cndmask_b32_e64 v80, v89, v87, s[4:5]
	v_cndmask_b32_e64 v82, v93, v85, s[4:5]
	v_mov_b32_e32 v91, v137
	v_mov_b32_dpp v94, v81 row_ror:8 row_mask:0xf bank_mask:0xf
	v_mov_b32_e32 v95, v137
	v_cndmask_b32_e64 v83, v92, v84, s[4:5]
	v_mov_b32_e32 v90, v137
	v_mov_b32_dpp v91, v82 row_ror:8 row_mask:0xf bank_mask:0xf
	v_mov_b32_dpp v95, v80 row_ror:8 row_mask:0xf bank_mask:0xf
	v_cndmask_b32_e64 v82, v94, v88, s[4:5]
	v_or_b32_e32 v88, s23, v154
	v_mov_b32_dpp v90, v83 row_ror:8 row_mask:0xf bank_mask:0xf
	v_cndmask_b32_e64 v83, v95, v89, s[4:5]
	v_ashrrev_i32_e32 v89, 31, v88
	v_lshlrev_b64 v[88:89], 11, v[88:89]
	v_lshl_add_u64 v[88:89], s[26:27], 0, v[88:89]
	v_lshl_add_u64 v[88:89], v[88:89], 0, v[112:113]
	v_cndmask_b32_e64 v81, v91, v93, s[4:5]
	v_cndmask_b32_e64 v80, v90, v92, s[4:5]
	v_lshl_add_u64 v[88:89], v[88:89], 0, v[136:137]
	global_store_dwordx4 v[88:89], v[80:83], off nt
	v_cndmask_b32_e64 v87, v87, v95, s[4:5]
	v_cndmask_b32_e64 v86, v86, v94, s[4:5]
	v_add_co_u32_e32 v80, vcc, s47, v88
	v_cndmask_b32_e64 v85, v85, v91, s[4:5]
	v_cndmask_b32_e64 v84, v84, v90, s[4:5]
	v_addc_co_u32_e32 v81, vcc, 0, v89, vcc
	s_or_b32 s23, s22, 48
	global_store_dwordx4 v[80:81], v[84:87], off nt
	v_or_b32_e32 v80, s23, v150
	v_ashrrev_i32_e32 v81, 31, v80
	v_lshlrev_b64 v[82:83], 11, v[80:81]
	v_lshl_add_u64 v[82:83], s[26:27], 0, v[82:83]
	v_lshl_add_u64 v[86:87], v[82:83], 0, v[112:113]
	s_waitcnt vmcnt(17)
; __device__ __forceinline__ unsigned swap8(unsigned v) { return (unsigned)__builtin_amdgcn_update_dpp(0, (int)v, 0x128  , 0xF, 0xF, false); }
; __device__ __forceinline__ void wide_store(bf16_t* O, int ldc, int rowg  , int col0  , int fr, u32x4 w0, u32x4 w1) {
;     const bool lo = fr < 8;
;     u32x4 snd = lo ? w1 : w0, rcv;
;     rcv.x = swap8(snd.x); rcv.y = swap8(snd.y); rcv.z = swap8(snd.z); rcv.w = swap8(snd.w);
;     const u32x4 first = lo ? w0 : rcv, second = lo ? rcv : w1;
;     bf16_t* p = O + (size_t)(rowg + (fr & 7)) * ldc + col0 + (lo ? 0 : 32);
;     __builtin_nontemporal_store(first, (u32x4*)p); __builtin_nontemporal_store(second, (u32x4*)(p + (size_t)8 * ldc));
;     __device__ __forceinline__ void operator()(const f32x4 (&acc)[2][2][4][2], const Unit& u, int wr, int wc, int fr, int fq) const {
;     ...
;             for (int m = 0; m < 4; ++m) { const int rowg = u.pm * BM + ai * HALF + wr * 64 + m * 16, row = rowg + fr; const size_t off = (size_t)row * 1024 + col0;
;                 u32x4 w[2]; float ss = 0.f;
; #pragma unroll
;                 for (int bj = 0; bj < 2; ++bj) { f32x4 b0, b1;
;                     if (BASE_F32) { const float* bp = (const float*)base + off + 32 * bj; b0 = *(const f32x4*)bp; b1 = *(const f32x4*)(bp + 4); }
;                     else { const u32x4 bb = *(const u32x4*)((const bf16_t*)base + off + 32 * bj);
;                         b0 = (f32x4){__uint_as_float(bb.x << 16), __uint_as_float(bb.x & 0xffff0000u), __uint_as_float(bb.y << 16), __uint_as_float(bb.y & 0xffff0000u)};
;                         b1 = (f32x4){__uint_as_float(bb.z << 16), __uint_as_float(bb.z & 0xffff0000u), __uint_as_float(bb.w << 16), __uint_as_float(bb.w & 0xffff0000u)}; }
;                     const f32x4 o0 = b0 + acc[ai][bj][m][0], o1 = b1 + acc[ai][bj][m][1];
;                     ss += ((o0[0] * o0[0] + o0[1] * o0[1]) + (o0[2] * o0[2] + o0[3] * o0[3])) + ((o1[0] * o1[0] + o1[1] * o1[1]) + (o1[2] * o1[2] + o1[3] * o1[3]));
;                     w[bj].x = cvt_pk_bf16(o0[0], o0[1]); w[bj].y = cvt_pk_bf16(o0[2], o0[3]); w[bj].z = cvt_pk_bf16(o1[0], o1[1]); w[bj].w = cvt_pk_bf16(o1[2], o1[3]); }
;                 ss += __shfl_xor(ss, 16); ss += __shfl_xor(ss, 32); if (fq == 0) slots[(size_t)row * 16 + u.pn * 4 + wc] = ss;
;                 wide_store(xb, 1024, rowg, col0, fr, w[0], w[1]);
	v_mov_b32_e32 v82, v196
	v_mov_b32_e32 v83, v197
	v_mov_b32_e32 v84, v198
	v_mov_b32_e32 v85, v199
	v_mov_b32_e32 v86, v200
	v_mov_b32_e32 v87, v201
	v_mov_b32_e32 v88, v202
	v_mov_b32_e32 v89, v203
	v_lshlrev_b32_e32 v90, 16, v82
	v_and_b32_e32 v91, 0xffff0000, v82
	v_lshlrev_b32_e32 v82, 16, v83
	v_and_b32_e32 v83, 0xffff0000, v83
	v_lshlrev_b32_e32 v92, 16, v84
	v_and_b32_e32 v93, 0xffff0000, v84
	v_lshlrev_b32_e32 v84, 16, v85
	v_and_b32_e32 v85, 0xffff0000, v85
	v_lshlrev_b32_e32 v94, 16, v86
	v_and_b32_e32 v95, 0xffff0000, v86
	v_lshlrev_b32_e32 v86, 16, v87
	v_and_b32_e32 v87, 0xffff0000, v87
	v_lshlrev_b32_e32 v96, 16, v88
	v_and_b32_e32 v97, 0xffff0000, v88
	v_lshlrev_b32_e32 v88, 16, v89
	v_and_b32_e32 v89, 0xffff0000, v89
	v_pk_add_f32 v[78:79], v[78:79], v[82:83]
	v_pk_add_f32 v[76:77], v[76:77], v[90:91]
	v_pk_add_f32 v[74:75], v[74:75], v[84:85]
	v_pk_add_f32 v[72:73], v[72:73], v[92:93]
	v_pk_add_f32 v[70:71], v[70:71], v[86:87]
	v_pk_add_f32 v[68:69], v[68:69], v[94:95]
	v_pk_add_f32 v[66:67], v[66:67], v[88:89]
	v_pk_add_f32 v[64:65], v[64:65], v[96:97]
	v_mul_f32_e32 v82, v77, v77
	v_mul_f32_e32 v83, v79, v79
	v_mul_f32_e32 v84, v73, v73
	v_mul_f32_e32 v85, v75, v75
	v_mul_f32_e32 v86, v69, v69
	v_mul_f32_e32 v87, v71, v71
	v_mul_f32_e32 v88, v65, v65
	v_mul_f32_e32 v89, v67, v67
	v_fmac_f32_e32 v82, v76, v76
	v_fmac_f32_e32 v83, v78, v78
	v_fmac_f32_e32 v84, v72, v72
	v_fmac_f32_e32 v85, v74, v74
	v_fmac_f32_e32 v86, v68, v68
	v_fmac_f32_e32 v87, v70, v70
	v_fmac_f32_e32 v88, v64, v64
	v_fmac_f32_e32 v89, v66, v66
	v_add_f32_e32 v82, v82, v83
	v_add_f32_e32 v83, v84, v85
	v_add_f32_e32 v84, v86, v87
	v_add_f32_e32 v85, v88, v89
	v_add_f32_e32 v82, v82, v83
	v_add_f32_e32 v83, v84, v85
	v_add_f32_e32 v82, v82, v83
	ds_bpermute_b32 v83, v159, v82
	s_waitcnt lgkmcnt(0)
	v_add_f32_e32 v82, v82, v83
	ds_bpermute_b32 v83, v160, v82
	s_and_saveexec_b64 s[20:21], s[2:3]
	s_cbranch_execz .LBB0_1207
	v_lshlrev_b64 v[80:81], 6, v[80:81]
	v_lshl_add_u64 v[80:81], s[82:83], 0, v[80:81]
	v_lshl_add_u64 v[80:81], s[0:1], 2, v[80:81]
	s_lshl_b32 s14, s48, 2
	v_lshl_add_u64 v[80:81], v[80:81], 0, s[14:15]
	s_waitcnt lgkmcnt(0)
	v_add_f32_e32 v82, v82, v83
	global_store_dword v[80:81], v82, off
.LBB0_1207:
	s_or_b64 exec, exec, s[20:21]
	v_cvt_pk_bf16_f32 v72, v72, v73
	v_cvt_pk_bf16_f32 v68, v68, v69
	v_cvt_pk_bf16_f32 v69, v70, v71
	v_cvt_pk_bf16_f32 v70, v64, v65
	v_cvt_pk_bf16_f32 v76, v76, v77
	v_cvt_pk_bf16_f32 v77, v78, v79
	v_cvt_pk_bf16_f32 v73, v74, v75
	v_cvt_pk_bf16_f32 v71, v66, v67
	v_cndmask_b32_e64 v65, v72, v70, s[4:5]
	v_mov_b32_e32 v78, v137
	v_cndmask_b32_e64 v64, v73, v71, s[4:5]
	v_cndmask_b32_e64 v66, v77, v69, s[4:5]
	v_mov_b32_e32 v75, v137
	v_mov_b32_dpp v78, v65 row_ror:8 row_mask:0xf bank_mask:0xf
	v_mov_b32_e32 v79, v137
	v_cndmask_b32_e64 v67, v76, v68, s[4:5]
	v_mov_b32_e32 v74, v137
	v_mov_b32_dpp v75, v66 row_ror:8 row_mask:0xf bank_mask:0xf
	v_mov_b32_dpp v79, v64 row_ror:8 row_mask:0xf bank_mask:0xf
	v_cndmask_b32_e64 v66, v78, v72, s[4:5]
	v_or_b32_e32 v72, s23, v154
	v_mov_b32_dpp v74, v67 row_ror:8 row_mask:0xf bank_mask:0xf
	v_cndmask_b32_e64 v67, v79, v73, s[4:5]
	v_ashrrev_i32_e32 v73, 31, v72
	v_lshlrev_b64 v[72:73], 11, v[72:73]
	v_lshl_add_u64 v[72:73], s[26:27], 0, v[72:73]
	v_lshl_add_u64 v[72:73], v[72:73], 0, v[112:113]
	v_cndmask_b32_e64 v65, v75, v77, s[4:5]
	v_cndmask_b32_e64 v64, v74, v76, s[4:5]
	v_lshl_add_u64 v[72:73], v[72:73], 0, v[136:137]
	global_store_dwordx4 v[72:73], v[64:67], off nt
	v_cndmask_b32_e64 v71, v71, v79, s[4:5]
	v_cndmask_b32_e64 v70, v70, v78, s[4:5]
	v_add_co_u32_e32 v64, vcc, s47, v72
	v_cndmask_b32_e64 v69, v69, v75, s[4:5]
	v_cndmask_b32_e64 v68, v68, v74, s[4:5]
	v_addc_co_u32_e32 v65, vcc, 0, v73, vcc
	s_add_i32 s23, s22, 0x80
	global_store_dwordx4 v[64:65], v[68:71], off nt
	v_or_b32_e32 v64, s23, v150
	v_ashrrev_i32_e32 v65, 31, v64
	v_lshlrev_b64 v[66:67], 11, v[64:65]
	v_lshl_add_u64 v[66:67], s[26:27], 0, v[66:67]
	v_lshl_add_u64 v[70:71], v[66:67], 0, v[112:113]
	s_waitcnt vmcnt(18)
	v_mov_b32_e32 v66, v204
	v_mov_b32_e32 v67, v205
	v_mov_b32_e32 v68, v206
	v_mov_b32_e32 v69, v207
	v_mov_b32_e32 v70, v208
	v_mov_b32_e32 v71, v209
	v_mov_b32_e32 v72, v210
	v_mov_b32_e32 v73, v211
	v_lshlrev_b32_e32 v74, 16, v66
	v_and_b32_e32 v75, 0xffff0000, v66
	v_lshlrev_b32_e32 v66, 16, v67
	v_and_b32_e32 v67, 0xffff0000, v67
	v_lshlrev_b32_e32 v76, 16, v68
	v_and_b32_e32 v77, 0xffff0000, v68
	v_lshlrev_b32_e32 v68, 16, v69
	v_and_b32_e32 v69, 0xffff0000, v69
	v_lshlrev_b32_e32 v78, 16, v70
	v_and_b32_e32 v79, 0xffff0000, v70
	v_lshlrev_b32_e32 v70, 16, v71
	v_and_b32_e32 v71, 0xffff0000, v71
	v_lshlrev_b32_e32 v80, 16, v72
	v_and_b32_e32 v81, 0xffff0000, v72
	v_lshlrev_b32_e32 v72, 16, v73
	v_and_b32_e32 v73, 0xffff0000, v73
	v_pk_add_f32 v[62:63], v[62:63], v[66:67]
	v_pk_add_f32 v[60:61], v[60:61], v[74:75]
	v_pk_add_f32 v[58:59], v[58:59], v[68:69]
	v_pk_add_f32 v[56:57], v[56:57], v[76:77]
	v_pk_add_f32 v[54:55], v[54:55], v[70:71]
	v_pk_add_f32 v[52:53], v[52:53], v[78:79]
	v_pk_add_f32 v[50:51], v[50:51], v[72:73]
	v_pk_add_f32 v[48:49], v[48:49], v[80:81]
	v_mul_f32_e32 v66, v61, v61
	v_mul_f32_e32 v67, v63, v63
	v_mul_f32_e32 v68, v57, v57
	v_mul_f32_e32 v69, v59, v59
	v_mul_f32_e32 v70, v53, v53
	v_mul_f32_e32 v71, v55, v55
	v_mul_f32_e32 v72, v49, v49
	v_mul_f32_e32 v73, v51, v51
	v_fmac_f32_e32 v66, v60, v60
	v_fmac_f32_e32 v67, v62, v62
	v_fmac_f32_e32 v68, v56, v56
	v_fmac_f32_e32 v69, v58, v58
	v_fmac_f32_e32 v70, v52, v52
	v_fmac_f32_e32 v71, v54, v54
	v_fmac_f32_e32 v72, v48, v48
	v_fmac_f32_e32 v73, v50, v50
	v_add_f32_e32 v66, v66, v67
	v_add_f32_e32 v67, v68, v69
	v_add_f32_e32 v68, v70, v71
	v_add_f32_e32 v69, v72, v73
	v_add_f32_e32 v66, v66, v67
	v_add_f32_e32 v67, v68, v69
	v_add_f32_e32 v66, v66, v67
	ds_bpermute_b32 v67, v159, v66
	s_waitcnt lgkmcnt(0)
	v_add_f32_e32 v66, v66, v67
	ds_bpermute_b32 v67, v160, v66
	s_and_saveexec_b64 s[20:21], s[2:3]
	s_cbranch_execz .LBB0_1209
	v_lshlrev_b64 v[64:65], 6, v[64:65]
	v_lshl_add_u64 v[64:65], s[82:83], 0, v[64:65]
	v_lshl_add_u64 v[64:65], s[0:1], 2, v[64:65]
	s_lshl_b32 s14, s48, 2
	v_lshl_add_u64 v[64:65], v[64:65], 0, s[14:15]
	s_waitcnt lgkmcnt(0)
	v_add_f32_e32 v66, v66, v67
	global_store_dword v[64:65], v66, off
; __device__ __forceinline__ unsigned swap8(unsigned v) { return (unsigned)__builtin_amdgcn_update_dpp(0, (int)v, 0x128  , 0xF, 0xF, false); }
; __device__ __forceinline__ void wide_store(bf16_t* O, int ldc, int rowg  , int col0  , int fr, u32x4 w0, u32x4 w1) {
;     const bool lo = fr < 8;
;     u32x4 snd = lo ? w1 : w0, rcv;
;     rcv.x = swap8(snd.x); rcv.y = swap8(snd.y); rcv.z = swap8(snd.z); rcv.w = swap8(snd.w);
;     const u32x4 first = lo ? w0 : rcv, second = lo ? rcv : w1;
;     bf16_t* p = O + (size_t)(rowg + (fr & 7)) * ldc + col0 + (lo ? 0 : 32);
;     __builtin_nontemporal_store(first, (u32x4*)p); __builtin_nontemporal_store(second, (u32x4*)(p + (size_t)8 * ldc));
;     __device__ __forceinline__ void operator()(const f32x4 (&acc)[2][2][4][2], const Unit& u, int wr, int wc, int fr, int fq) const {
;     ...
;             for (int m = 0; m < 4; ++m) { const int rowg = u.pm * BM + ai * HALF + wr * 64 + m * 16, row = rowg + fr; const size_t off = (size_t)row * 1024 + col0;
;                 u32x4 w[2]; float ss = 0.f;
; #pragma unroll
;                 for (int bj = 0; bj < 2; ++bj) { f32x4 b0, b1;
;                     if (BASE_F32) { const float* bp = (const float*)base + off + 32 * bj; b0 = *(const f32x4*)bp; b1 = *(const f32x4*)(bp + 4); }
;                     else { const u32x4 bb = *(const u32x4*)((const bf16_t*)base + off + 32 * bj);
;                         b0 = (f32x4){__uint_as_float(bb.x << 16), __uint_as_float(bb.x & 0xffff0000u), __uint_as_float(bb.y << 16), __uint_as_float(bb.y & 0xffff0000u)};
;                         b1 = (f32x4){__uint_as_float(bb.z << 16), __uint_as_float(bb.z & 0xffff0000u), __uint_as_float(bb.w << 16), __uint_as_float(bb.w & 0xffff0000u)}; }
;                     const f32x4 o0 = b0 + acc[ai][bj][m][0], o1 = b1 + acc[ai][bj][m][1];
;                     ss += ((o0[0] * o0[0] + o0[1] * o0[1]) + (o0[2] * o0[2] + o0[3] * o0[3])) + ((o1[0] * o1[0] + o1[1] * o1[1]) + (o1[2] * o1[2] + o1[3] * o1[3]));
;                     w[bj].x = cvt_pk_bf16(o0[0], o0[1]); w[bj].y = cvt_pk_bf16(o0[2], o0[3]); w[bj].z = cvt_pk_bf16(o1[0], o1[1]); w[bj].w = cvt_pk_bf16(o1[2], o1[3]); }
;                 ss += __shfl_xor(ss, 16); ss += __shfl_xor(ss, 32); if (fq == 0) slots[(size_t)row * 16 + u.pn * 4 + wc] = ss;
;                 wide_store(xb, 1024, rowg, col0, fr, w[0], w[1]);
.LBB0_1209:
	s_or_b64 exec, exec, s[20:21]
	v_cvt_pk_bf16_f32 v56, v56, v57
	v_cvt_pk_bf16_f32 v52, v52, v53
	v_cvt_pk_bf16_f32 v53, v54, v55
	v_cvt_pk_bf16_f32 v54, v48, v49
	v_cvt_pk_bf16_f32 v60, v60, v61
	v_cvt_pk_bf16_f32 v61, v62, v63
	v_cvt_pk_bf16_f32 v57, v58, v59
	v_cvt_pk_bf16_f32 v55, v50, v51
	v_cndmask_b32_e64 v49, v56, v54, s[4:5]
	v_mov_b32_e32 v62, v137
	v_cndmask_b32_e64 v48, v57, v55, s[4:5]
	v_cndmask_b32_e64 v50, v61, v53, s[4:5]
	v_mov_b32_e32 v59, v137
	v_mov_b32_dpp v62, v49 row_ror:8 row_mask:0xf bank_mask:0xf
	v_mov_b32_e32 v63, v137
	v_cndmask_b32_e64 v51, v60, v52, s[4:5]
	v_mov_b32_e32 v58, v137
	v_mov_b32_dpp v59, v50 row_ror:8 row_mask:0xf bank_mask:0xf
	v_mov_b32_dpp v63, v48 row_ror:8 row_mask:0xf bank_mask:0xf
	v_cndmask_b32_e64 v50, v62, v56, s[4:5]
	v_or_b32_e32 v56, s23, v154
	v_mov_b32_dpp v58, v51 row_ror:8 row_mask:0xf bank_mask:0xf
	v_cndmask_b32_e64 v51, v63, v57, s[4:5]
	v_ashrrev_i32_e32 v57, 31, v56
	v_lshlrev_b64 v[56:57], 11, v[56:57]
	v_lshl_add_u64 v[56:57], s[26:27], 0, v[56:57]
	v_lshl_add_u64 v[56:57], v[56:57], 0, v[112:113]
	v_cndmask_b32_e64 v49, v59, v61, s[4:5]
	v_cndmask_b32_e64 v48, v58, v60, s[4:5]
	v_lshl_add_u64 v[56:57], v[56:57], 0, v[136:137]
	global_store_dwordx4 v[56:57], v[48:51], off nt
	v_cndmask_b32_e64 v55, v55, v63, s[4:5]
	v_cndmask_b32_e64 v54, v54, v62, s[4:5]
	v_add_co_u32_e32 v48, vcc, s47, v56
	v_cndmask_b32_e64 v53, v53, v59, s[4:5]
	v_cndmask_b32_e64 v52, v52, v58, s[4:5]
	v_addc_co_u32_e32 v49, vcc, 0, v57, vcc
	s_add_i32 s23, s22, 0x90
	global_store_dwordx4 v[48:49], v[52:55], off nt
	v_or_b32_e32 v48, s23, v150
	v_ashrrev_i32_e32 v49, 31, v48
	v_lshlrev_b64 v[50:51], 11, v[48:49]
	v_lshl_add_u64 v[50:51], s[26:27], 0, v[50:51]
	v_lshl_add_u64 v[54:55], v[50:51], 0, v[112:113]
	s_waitcnt vmcnt(19)
	v_mov_b32_e32 v50, v212
	v_mov_b32_e32 v51, v213
	v_mov_b32_e32 v52, v214
	v_mov_b32_e32 v53, v215
	v_mov_b32_e32 v54, v216
	v_mov_b32_e32 v55, v217
	v_mov_b32_e32 v56, v218
	v_mov_b32_e32 v57, v219
	v_lshlrev_b32_e32 v58, 16, v50
	v_and_b32_e32 v59, 0xffff0000, v50
	v_lshlrev_b32_e32 v50, 16, v51
	v_and_b32_e32 v51, 0xffff0000, v51
	v_lshlrev_b32_e32 v60, 16, v52
	v_and_b32_e32 v61, 0xffff0000, v52
	v_lshlrev_b32_e32 v52, 16, v53
	v_and_b32_e32 v53, 0xffff0000, v53
	v_lshlrev_b32_e32 v62, 16, v54
	v_and_b32_e32 v63, 0xffff0000, v54
	v_lshlrev_b32_e32 v54, 16, v55
	v_and_b32_e32 v55, 0xffff0000, v55
	v_lshlrev_b32_e32 v64, 16, v56
	v_and_b32_e32 v65, 0xffff0000, v56
	v_lshlrev_b32_e32 v56, 16, v57
	v_and_b32_e32 v57, 0xffff0000, v57
	v_pk_add_f32 v[46:47], v[46:47], v[50:51]
	v_pk_add_f32 v[44:45], v[44:45], v[58:59]
	v_pk_add_f32 v[42:43], v[42:43], v[52:53]
	v_pk_add_f32 v[40:41], v[40:41], v[60:61]
	v_pk_add_f32 v[38:39], v[38:39], v[54:55]
	v_pk_add_f32 v[36:37], v[36:37], v[62:63]
	v_pk_add_f32 v[34:35], v[34:35], v[56:57]
	v_pk_add_f32 v[32:33], v[32:33], v[64:65]
	v_mul_f32_e32 v50, v45, v45
	v_mul_f32_e32 v51, v47, v47
	v_mul_f32_e32 v52, v41, v41
	v_mul_f32_e32 v53, v43, v43
	v_mul_f32_e32 v54, v37, v37
	v_mul_f32_e32 v55, v39, v39
	v_mul_f32_e32 v56, v33, v33
	v_mul_f32_e32 v57, v35, v35
	v_fmac_f32_e32 v50, v44, v44
	v_fmac_f32_e32 v51, v46, v46
	v_fmac_f32_e32 v52, v40, v40
	v_fmac_f32_e32 v53, v42, v42
	v_fmac_f32_e32 v54, v36, v36
	v_fmac_f32_e32 v55, v38, v38
	v_fmac_f32_e32 v56, v32, v32
	v_fmac_f32_e32 v57, v34, v34
	v_add_f32_e32 v50, v50, v51
	v_add_f32_e32 v51, v52, v53
	v_add_f32_e32 v52, v54, v55
	v_add_f32_e32 v53, v56, v57
	v_add_f32_e32 v50, v50, v51
	v_add_f32_e32 v51, v52, v53
	v_add_f32_e32 v50, v50, v51
	ds_bpermute_b32 v51, v159, v50
	s_waitcnt lgkmcnt(0)
	v_add_f32_e32 v50, v50, v51
	ds_bpermute_b32 v51, v160, v50
	s_and_saveexec_b64 s[20:21], s[2:3]
	s_cbranch_execz .LBB0_1211
	v_lshlrev_b64 v[48:49], 6, v[48:49]
	v_lshl_add_u64 v[48:49], s[82:83], 0, v[48:49]
	v_lshl_add_u64 v[48:49], s[0:1], 2, v[48:49]
	s_lshl_b32 s14, s48, 2
	v_lshl_add_u64 v[48:49], v[48:49], 0, s[14:15]
	s_waitcnt lgkmcnt(0)
	v_add_f32_e32 v50, v50, v51
	global_store_dword v[48:49], v50, off
.LBB0_1211:
	s_or_b64 exec, exec, s[20:21]
	v_cvt_pk_bf16_f32 v40, v40, v41
	v_cvt_pk_bf16_f32 v36, v36, v37
	v_cvt_pk_bf16_f32 v37, v38, v39
	v_cvt_pk_bf16_f32 v38, v32, v33
	v_cvt_pk_bf16_f32 v44, v44, v45
	v_cvt_pk_bf16_f32 v45, v46, v47
	v_cvt_pk_bf16_f32 v41, v42, v43
	v_cvt_pk_bf16_f32 v39, v34, v35
	v_cndmask_b32_e64 v33, v40, v38, s[4:5]
	v_mov_b32_e32 v46, v137
	v_cndmask_b32_e64 v32, v41, v39, s[4:5]
	v_cndmask_b32_e64 v34, v45, v37, s[4:5]
	v_mov_b32_e32 v43, v137
	v_mov_b32_dpp v46, v33 row_ror:8 row_mask:0xf bank_mask:0xf
	v_mov_b32_e32 v47, v137
	v_cndmask_b32_e64 v35, v44, v36, s[4:5]
	v_mov_b32_e32 v42, v137
	v_mov_b32_dpp v43, v34 row_ror:8 row_mask:0xf bank_mask:0xf
	v_mov_b32_dpp v47, v32 row_ror:8 row_mask:0xf bank_mask:0xf
	v_cndmask_b32_e64 v34, v46, v40, s[4:5]
	v_or_b32_e32 v40, s23, v154
	v_mov_b32_dpp v42, v35 row_ror:8 row_mask:0xf bank_mask:0xf
	v_cndmask_b32_e64 v35, v47, v41, s[4:5]
	v_ashrrev_i32_e32 v41, 31, v40
	v_lshlrev_b64 v[40:41], 11, v[40:41]
	v_lshl_add_u64 v[40:41], s[26:27], 0, v[40:41]
	v_lshl_add_u64 v[40:41], v[40:41], 0, v[112:113]
	v_cndmask_b32_e64 v33, v43, v45, s[4:5]
	v_cndmask_b32_e64 v32, v42, v44, s[4:5]
	v_lshl_add_u64 v[40:41], v[40:41], 0, v[136:137]
	global_store_dwordx4 v[40:41], v[32:35], off nt
	v_cndmask_b32_e64 v39, v39, v47, s[4:5]
	v_cndmask_b32_e64 v38, v38, v46, s[4:5]
	v_add_co_u32_e32 v32, vcc, s47, v40
	v_cndmask_b32_e64 v37, v37, v43, s[4:5]
	v_cndmask_b32_e64 v36, v36, v42, s[4:5]
	v_addc_co_u32_e32 v33, vcc, 0, v41, vcc
	s_add_i32 s23, s22, 0xa0
	global_store_dwordx4 v[32:33], v[36:39], off nt
	v_or_b32_e32 v32, s23, v150
	v_ashrrev_i32_e32 v33, 31, v32
	v_lshlrev_b64 v[34:35], 11, v[32:33]
	v_lshl_add_u64 v[34:35], s[26:27], 0, v[34:35]
	v_lshl_add_u64 v[38:39], v[34:35], 0, v[112:113]
	s_waitcnt vmcnt(20)
; __device__ __forceinline__ unsigned swap8(unsigned v) { return (unsigned)__builtin_amdgcn_update_dpp(0, (int)v, 0x128  , 0xF, 0xF, false); }
; __device__ __forceinline__ void wide_store(bf16_t* O, int ldc, int rowg  , int col0  , int fr, u32x4 w0, u32x4 w1) {
;     const bool lo = fr < 8;
;     u32x4 snd = lo ? w1 : w0, rcv;
;     rcv.x = swap8(snd.x); rcv.y = swap8(snd.y); rcv.z = swap8(snd.z); rcv.w = swap8(snd.w);
;     const u32x4 first = lo ? w0 : rcv, second = lo ? rcv : w1;
;     bf16_t* p = O + (size_t)(rowg + (fr & 7)) * ldc + col0 + (lo ? 0 : 32);
;     __builtin_nontemporal_store(first, (u32x4*)p); __builtin_nontemporal_store(second, (u32x4*)(p + (size_t)8 * ldc));
;     __device__ __forceinline__ void operator()(const f32x4 (&acc)[2][2][4][2], const Unit& u, int wr, int wc, int fr, int fq) const {
;     ...
;             for (int m = 0; m < 4; ++m) { const int rowg = u.pm * BM + ai * HALF + wr * 64 + m * 16, row = rowg + fr; const size_t off = (size_t)row * 1024 + col0;
;                 u32x4 w[2]; float ss = 0.f;
; #pragma unroll
;                 for (int bj = 0; bj < 2; ++bj) { f32x4 b0, b1;
;                     if (BASE_F32) { const float* bp = (const float*)base + off + 32 * bj; b0 = *(const f32x4*)bp; b1 = *(const f32x4*)(bp + 4); }
;                     else { const u32x4 bb = *(const u32x4*)((const bf16_t*)base + off + 32 * bj);
;                         b0 = (f32x4){__uint_as_float(bb.x << 16), __uint_as_float(bb.x & 0xffff0000u), __uint_as_float(bb.y << 16), __uint_as_float(bb.y & 0xffff0000u)};
;                         b1 = (f32x4){__uint_as_float(bb.z << 16), __uint_as_float(bb.z & 0xffff0000u), __uint_as_float(bb.w << 16), __uint_as_float(bb.w & 0xffff0000u)}; }
;                     const f32x4 o0 = b0 + acc[ai][bj][m][0], o1 = b1 + acc[ai][bj][m][1];
;                     ss += ((o0[0] * o0[0] + o0[1] * o0[1]) + (o0[2] * o0[2] + o0[3] * o0[3])) + ((o1[0] * o1[0] + o1[1] * o1[1]) + (o1[2] * o1[2] + o1[3] * o1[3]));
;                     w[bj].x = cvt_pk_bf16(o0[0], o0[1]); w[bj].y = cvt_pk_bf16(o0[2], o0[3]); w[bj].z = cvt_pk_bf16(o1[0], o1[1]); w[bj].w = cvt_pk_bf16(o1[2], o1[3]); }
;                 ss += __shfl_xor(ss, 16); ss += __shfl_xor(ss, 32); if (fq == 0) slots[(size_t)row * 16 + u.pn * 4 + wc] = ss;
;                 wide_store(xb, 1024, rowg, col0, fr, w[0], w[1]);
	v_mov_b32_e32 v34, v220
	v_mov_b32_e32 v35, v221
	v_mov_b32_e32 v36, v222
	v_mov_b32_e32 v37, v223
	v_mov_b32_e32 v38, v224
	v_mov_b32_e32 v39, v225
	v_mov_b32_e32 v40, v226
	v_mov_b32_e32 v41, v227
	v_lshlrev_b32_e32 v42, 16, v34
	v_and_b32_e32 v43, 0xffff0000, v34
	v_lshlrev_b32_e32 v34, 16, v35
	v_and_b32_e32 v35, 0xffff0000, v35
	v_lshlrev_b32_e32 v44, 16, v36
	v_and_b32_e32 v45, 0xffff0000, v36
	v_lshlrev_b32_e32 v36, 16, v37
	v_and_b32_e32 v37, 0xffff0000, v37
	v_lshlrev_b32_e32 v46, 16, v38
	v_and_b32_e32 v47, 0xffff0000, v38
	v_lshlrev_b32_e32 v38, 16, v39
	v_and_b32_e32 v39, 0xffff0000, v39
	v_lshlrev_b32_e32 v48, 16, v40
	v_and_b32_e32 v49, 0xffff0000, v40
	v_lshlrev_b32_e32 v40, 16, v41
	v_and_b32_e32 v41, 0xffff0000, v41
	v_pk_add_f32 v[30:31], v[30:31], v[34:35]
	v_pk_add_f32 v[28:29], v[28:29], v[42:43]
	v_pk_add_f32 v[26:27], v[26:27], v[36:37]
	v_pk_add_f32 v[24:25], v[24:25], v[44:45]
	v_pk_add_f32 v[22:23], v[22:23], v[38:39]
	v_pk_add_f32 v[20:21], v[20:21], v[46:47]
	v_pk_add_f32 v[18:19], v[18:19], v[40:41]
	v_pk_add_f32 v[16:17], v[16:17], v[48:49]
	v_mul_f32_e32 v34, v29, v29
	v_mul_f32_e32 v35, v31, v31
	v_mul_f32_e32 v36, v25, v25
	v_mul_f32_e32 v37, v27, v27
	v_mul_f32_e32 v38, v21, v21
	v_mul_f32_e32 v39, v23, v23
	v_mul_f32_e32 v40, v17, v17
	v_mul_f32_e32 v41, v19, v19
	v_fmac_f32_e32 v34, v28, v28
	v_fmac_f32_e32 v35, v30, v30
	v_fmac_f32_e32 v36, v24, v24
	v_fmac_f32_e32 v37, v26, v26
	v_fmac_f32_e32 v38, v20, v20
	v_fmac_f32_e32 v39, v22, v22
	v_fmac_f32_e32 v40, v16, v16
	v_fmac_f32_e32 v41, v18, v18
	v_add_f32_e32 v34, v34, v35
	v_add_f32_e32 v35, v36, v37
	v_add_f32_e32 v36, v38, v39
	v_add_f32_e32 v37, v40, v41
	v_add_f32_e32 v34, v34, v35
	v_add_f32_e32 v35, v36, v37
	v_add_f32_e32 v34, v34, v35
	ds_bpermute_b32 v35, v159, v34
	s_waitcnt lgkmcnt(0)
	v_add_f32_e32 v34, v34, v35
	ds_bpermute_b32 v35, v160, v34
	s_and_saveexec_b64 s[20:21], s[2:3]
	s_cbranch_execz .LBB0_1213
	v_lshlrev_b64 v[32:33], 6, v[32:33]
	v_lshl_add_u64 v[32:33], s[82:83], 0, v[32:33]
	v_lshl_add_u64 v[32:33], s[0:1], 2, v[32:33]
	s_lshl_b32 s14, s48, 2
	v_lshl_add_u64 v[32:33], v[32:33], 0, s[14:15]
	s_waitcnt lgkmcnt(0)
	v_add_f32_e32 v34, v34, v35
	global_store_dword v[32:33], v34, off
.LBB0_1213:
	s_or_b64 exec, exec, s[20:21]
	v_cvt_pk_bf16_f32 v24, v24, v25
	v_cvt_pk_bf16_f32 v20, v20, v21
	v_cvt_pk_bf16_f32 v21, v22, v23
	v_cvt_pk_bf16_f32 v22, v16, v17
	v_cvt_pk_bf16_f32 v28, v28, v29
	v_cvt_pk_bf16_f32 v29, v30, v31
	v_cvt_pk_bf16_f32 v25, v26, v27
	v_cvt_pk_bf16_f32 v23, v18, v19
	v_cndmask_b32_e64 v17, v24, v22, s[4:5]
	v_mov_b32_e32 v30, v137
	v_cndmask_b32_e64 v16, v25, v23, s[4:5]
	v_cndmask_b32_e64 v18, v29, v21, s[4:5]
	v_mov_b32_e32 v27, v137
	v_mov_b32_dpp v30, v17 row_ror:8 row_mask:0xf bank_mask:0xf
	v_mov_b32_e32 v31, v137
	v_cndmask_b32_e64 v19, v28, v20, s[4:5]
	v_mov_b32_e32 v26, v137
	v_mov_b32_dpp v27, v18 row_ror:8 row_mask:0xf bank_mask:0xf
	v_mov_b32_dpp v31, v16 row_ror:8 row_mask:0xf bank_mask:0xf
	v_cndmask_b32_e64 v18, v30, v24, s[4:5]
	v_or_b32_e32 v24, s23, v154
	v_mov_b32_dpp v26, v19 row_ror:8 row_mask:0xf bank_mask:0xf
	v_cndmask_b32_e64 v19, v31, v25, s[4:5]
	v_ashrrev_i32_e32 v25, 31, v24
	v_lshlrev_b64 v[24:25], 11, v[24:25]
	v_lshl_add_u64 v[24:25], s[26:27], 0, v[24:25]
	v_lshl_add_u64 v[24:25], v[24:25], 0, v[112:113]
	v_cndmask_b32_e64 v17, v27, v29, s[4:5]
	v_cndmask_b32_e64 v16, v26, v28, s[4:5]
	v_lshl_add_u64 v[24:25], v[24:25], 0, v[136:137]
	global_store_dwordx4 v[24:25], v[16:19], off nt
	v_cndmask_b32_e64 v23, v23, v31, s[4:5]
	v_cndmask_b32_e64 v22, v22, v30, s[4:5]
	v_add_co_u32_e32 v16, vcc, s47, v24
	v_cndmask_b32_e64 v21, v21, v27, s[4:5]
	v_cndmask_b32_e64 v20, v20, v26, s[4:5]
	v_addc_co_u32_e32 v17, vcc, 0, v25, vcc
	s_addk_i32 s22, 0xb0
	global_store_dwordx4 v[16:17], v[20:23], off nt
	v_or_b32_e32 v16, s22, v150
	v_ashrrev_i32_e32 v17, 31, v16
	v_lshlrev_b64 v[18:19], 11, v[16:17]
	v_lshl_add_u64 v[18:19], s[26:27], 0, v[18:19]
	v_lshl_add_u64 v[22:23], v[18:19], 0, v[112:113]
	s_waitcnt vmcnt(21)
	v_mov_b32_e32 v18, v228
	v_mov_b32_e32 v19, v229
	v_mov_b32_e32 v20, v230
	v_mov_b32_e32 v21, v231
	v_mov_b32_e32 v22, v232
	v_mov_b32_e32 v23, v233
	v_mov_b32_e32 v24, v234
	v_mov_b32_e32 v25, v235
	v_lshlrev_b32_e32 v26, 16, v18
	v_and_b32_e32 v27, 0xffff0000, v18
	v_lshlrev_b32_e32 v18, 16, v19
	v_and_b32_e32 v19, 0xffff0000, v19
	v_lshlrev_b32_e32 v28, 16, v20
	v_and_b32_e32 v29, 0xffff0000, v20
	v_lshlrev_b32_e32 v20, 16, v21
	v_and_b32_e32 v21, 0xffff0000, v21
	v_lshlrev_b32_e32 v30, 16, v22
	v_and_b32_e32 v31, 0xffff0000, v22
	v_lshlrev_b32_e32 v22, 16, v23
	v_and_b32_e32 v23, 0xffff0000, v23
	v_lshlrev_b32_e32 v32, 16, v24
	v_and_b32_e32 v33, 0xffff0000, v24
	v_lshlrev_b32_e32 v24, 16, v25
	v_and_b32_e32 v25, 0xffff0000, v25
	v_pk_add_f32 v[14:15], v[14:15], v[18:19]
	v_pk_add_f32 v[12:13], v[12:13], v[26:27]
	v_pk_add_f32 v[10:11], v[10:11], v[20:21]
	v_pk_add_f32 v[8:9], v[8:9], v[28:29]
	v_pk_add_f32 v[6:7], v[6:7], v[22:23]
	v_pk_add_f32 v[4:5], v[4:5], v[30:31]
	v_pk_add_f32 v[2:3], v[2:3], v[24:25]
	v_pk_add_f32 v[0:1], v[0:1], v[32:33]
	v_mul_f32_e32 v18, v13, v13
	v_mul_f32_e32 v19, v15, v15
	v_mul_f32_e32 v20, v9, v9
	v_mul_f32_e32 v21, v11, v11
	v_mul_f32_e32 v22, v5, v5
	v_mul_f32_e32 v23, v7, v7
	v_mul_f32_e32 v24, v1, v1
	v_mul_f32_e32 v25, v3, v3
	v_fmac_f32_e32 v18, v12, v12
	v_fmac_f32_e32 v19, v14, v14
	v_fmac_f32_e32 v20, v8, v8
	v_fmac_f32_e32 v21, v10, v10
	v_fmac_f32_e32 v22, v4, v4
	v_fmac_f32_e32 v23, v6, v6
	v_fmac_f32_e32 v24, v0, v0
	v_fmac_f32_e32 v25, v2, v2
	v_add_f32_e32 v18, v18, v19
	v_add_f32_e32 v19, v20, v21
	v_add_f32_e32 v20, v22, v23
	v_add_f32_e32 v21, v24, v25
	v_add_f32_e32 v18, v18, v19
	v_add_f32_e32 v19, v20, v21
	v_add_f32_e32 v18, v18, v19
	ds_bpermute_b32 v19, v159, v18
	s_waitcnt lgkmcnt(0)
	v_add_f32_e32 v18, v18, v19
	ds_bpermute_b32 v19, v160, v18
	s_and_saveexec_b64 s[20:21], s[2:3]
	s_cbranch_execz .LBB0_1215
	v_lshlrev_b64 v[16:17], 6, v[16:17]
	v_lshl_add_u64 v[16:17], s[82:83], 0, v[16:17]
	v_lshl_add_u64 v[16:17], s[0:1], 2, v[16:17]
	s_lshl_b32 s14, s48, 2
	v_lshl_add_u64 v[16:17], v[16:17], 0, s[14:15]
	s_waitcnt lgkmcnt(0)
	v_add_f32_e32 v18, v18, v19
	global_store_dword v[16:17], v18, off
